# GEMM K-loops: LDS-DMA loads use SGPR-base saddr form (removed 14-16 64-bit VALU address adds per iteration in all 8 loop copies)
# speedup vs baseline: 1.0075x; 1.0056x over previous
; #define PG8_STAGE(bufoff, gbase, voff) do { _Pragma("unroll") for (int _i = 0; _i < 2; ++_i) \
;         __builtin_amdgcn_global_load_lds((const unsigned*)((const char*)(gbase) + (voff)[_i]), (PG8_LAS unsigned*)(lds + (bufoff) + ldsw + _i * 8192), 16, 0, 0); } while (0)
; #define PG8_LDA(dst, b, h) do { _Pragma("unroll") for (int m = 0; m < 4; ++m) _Pragma("unroll") for (int k = 0; k < 2; ++k) dst[m][k] = *(const PG8_LAS bf16x8*)(lds + PG8_SA(b, h) + aoff + m * 2048 + k * 1024); } while (0)
; #define PG8_LDB(dst, b, h) do { _Pragma("unroll") for (int n = 0; n < 2; ++n) _Pragma("unroll") for (int k = 0; k < 2; ++k) dst[n][k] = *(const PG8_LAS bf16x8*)(lds + PG8_SB(b, h) + boff + n * 2048 + k * 1024); } while (0)
; #define PG8_MMA(ai, bj, At, Bt) do { __builtin_amdgcn_s_setprio(1); _Pragma("unroll") for (int m = 0; m < 4; ++m) _Pragma("unroll") for (int n = 0; n < 2; ++n) _Pragma("unroll") for (int k = 0; k < 2; ++k) \
;         acc[ai][bj][m][n] = __builtin_amdgcn_mfma_f32_16x16x32_bf16(Bt[n][k], At[m][k], acc[ai][bj][m][n], 0, 0, 0); __builtin_amdgcn_s_setprio(0); } while (0)
; #define PG8_WAIT_V(n) asm volatile("s_waitcnt vmcnt(" #n ")" ::: "memory")
; #define PG8_WAIT_L(n) asm volatile("s_waitcnt lgkmcnt(" #n ")" ::: "memory")
; #define PG8_BAR __builtin_amdgcn_s_barrier()
; #define PG8_SCHED __builtin_amdgcn_sched_barrier(0)
; template <class Epi, class Sched, bool ALIGN_EPI = false, bool SP2 = false>
; __device__ __forceinline__ void gemm_phase(PG8_LAS unsigned char* lds, const Gemm g, const Sched& S, const Epi& E, const int tid_in) {
;     ...
;             const char* a1 = cA + (size_t)(t + 1) * kstep;
;             const char* a2 = last ? nA : cA + (size_t)(t + 2) * kstep; const char* b2 = last ? nB : cB + (size_t)(t + 2) * kstep;
;             const char* a3 = a2 + kstep; const char* b3 = b2 + kstep;
;             if (last && has_next) S.a_ready(nxt);
;             if constexpr (SP2) {
;             PG8_LDB(B0, 0, 0); PG8_LDB(B1, 0, 1); PG8_SCHED; PG8_LDA(At, 0, 0); PG8_STAGE(PG8_SA(1, 1), a1 + hstep, voffA);
;             PG8_WAIT_V(8); PG8_WAIT_L(0); PG8_BAR; PG8_MMA(0, 0, At, B0); PG8_MMA(0, 1, At, B1); PG8_BAR; PG8_SCHED;
;             PG8_LDA(At, 0, 1); PG8_STAGE(PG8_SB(0, 0), b2, voffB); PG8_STAGE(PG8_SB(0, 1), b2 + hstep, voffB); PG8_STAGE(PG8_SA(0, 0), a2, voffA);
.LBB0_352:
	s_add_u32 s38, s34, 0xfff80080
	s_addc_u32 s39, s35, -1
	s_add_i32 s58, 0, 0x10000
	s_cmp_eq_u32 s57, 28
	s_cselect_b32 s43, s27, s39
	s_cselect_b32 s42, s53, s38
	v_add_u32_e32 v145, s58, v142
	s_cselect_b32 s39, s25, s56
	s_cselect_b32 s38, s54, s55
	s_add_i32 s60, 0, 0x14000
	ds_read_b128 v[146:149], v145
	ds_read_b128 v[150:153], v145 offset:1024
	ds_read_b128 v[154:157], v145 offset:2048
	ds_read_b128 v[158:161], v145 offset:3072
	v_add_u32_e32 v145, s60, v142
	ds_read_b128 v[162:165], v145
	ds_read_b128 v[166:169], v145 offset:1024
	ds_read_b128 v[170:173], v145 offset:2048
	ds_read_b128 v[174:177], v145 offset:3072
	s_add_i32 m0, s44, 0xc000
	ds_read_b128 v[178:181], v144
	ds_read_b128 v[182:185], v144 offset:1024
	ds_read_b128 v[186:189], v144 offset:2048
	ds_read_b128 v[190:193], v144 offset:3072
	ds_read_b128 v[194:197], v144 offset:4096
	ds_read_b128 v[198:201], v144 offset:5120
	ds_read_b128 v[202:205], v144 offset:6144
	ds_read_b128 v[208:211], v144 offset:7168
	global_load_lds_dwordx4 v138, s[34:35]
	s_add_i32 m0, s44, 0xe000
	s_nop 0
	global_load_lds_dwordx4 v140, s[34:35]
	s_waitcnt vmcnt(8)
	s_waitcnt lgkmcnt(0)
	s_barrier
	s_setprio 1
	s_waitcnt lgkmcnt(0)
	v_mfma_f32_16x16x32_bf16 v[126:129], v[146:149], v[178:181], v[126:129]
	v_mfma_f32_16x16x32_bf16 v[122:125], v[154:157], v[178:181], v[122:125]
	v_mfma_f32_16x16x32_bf16 v[114:117], v[146:149], v[186:189], v[114:117]
	v_mfma_f32_16x16x32_bf16 v[106:109], v[154:157], v[186:189], v[106:109]
	v_mfma_f32_16x16x32_bf16 v[98:101], v[146:149], v[194:197], v[98:101]
	v_mfma_f32_16x16x32_bf16 v[90:93], v[154:157], v[194:197], v[90:93]
	v_mfma_f32_16x16x32_bf16 v[82:85], v[146:149], v[202:205], v[82:85]
	v_mfma_f32_16x16x32_bf16 v[74:77], v[154:157], v[202:205], v[74:77]
	v_mfma_f32_16x16x32_bf16 v[126:129], v[150:153], v[182:185], v[126:129]
	v_mfma_f32_16x16x32_bf16 v[122:125], v[158:161], v[182:185], v[122:125]
	v_mfma_f32_16x16x32_bf16 v[114:117], v[150:153], v[190:193], v[114:117]
	v_mfma_f32_16x16x32_bf16 v[106:109], v[158:161], v[190:193], v[106:109]
	v_mfma_f32_16x16x32_bf16 v[98:101], v[150:153], v[198:201], v[98:101]
	v_mfma_f32_16x16x32_bf16 v[90:93], v[158:161], v[198:201], v[90:93]
	v_mfma_f32_16x16x32_bf16 v[82:85], v[150:153], v[208:211], v[82:85]
	v_mfma_f32_16x16x32_bf16 v[74:77], v[158:161], v[208:211], v[74:77]
	s_setprio 0
	s_setprio 1
	v_mfma_f32_16x16x32_bf16 v[118:121], v[162:165], v[178:181], v[118:121]
	v_mfma_f32_16x16x32_bf16 v[110:113], v[170:173], v[178:181], v[110:113]
	v_mfma_f32_16x16x32_bf16 v[102:105], v[162:165], v[186:189], v[102:105]
	v_mfma_f32_16x16x32_bf16 v[94:97], v[170:173], v[186:189], v[94:97]
	v_mfma_f32_16x16x32_bf16 v[86:89], v[162:165], v[194:197], v[86:89]
	v_mfma_f32_16x16x32_bf16 v[78:81], v[170:173], v[194:197], v[78:81]
	v_mfma_f32_16x16x32_bf16 v[70:73], v[162:165], v[202:205], v[70:73]
	v_mfma_f32_16x16x32_bf16 v[66:69], v[170:173], v[202:205], v[66:69]
	v_mfma_f32_16x16x32_bf16 v[118:121], v[166:169], v[182:185], v[118:121]
	v_mfma_f32_16x16x32_bf16 v[110:113], v[174:177], v[182:185], v[110:113]
	v_mfma_f32_16x16x32_bf16 v[102:105], v[166:169], v[190:193], v[102:105]
	v_mfma_f32_16x16x32_bf16 v[94:97], v[174:177], v[190:193], v[94:97]
	v_mfma_f32_16x16x32_bf16 v[86:89], v[166:169], v[198:201], v[86:89]
	v_mfma_f32_16x16x32_bf16 v[78:81], v[174:177], v[198:201], v[78:81]
	v_mfma_f32_16x16x32_bf16 v[70:73], v[166:169], v[208:211], v[70:73]
	v_mfma_f32_16x16x32_bf16 v[66:69], v[174:177], v[208:211], v[66:69]
	s_setprio 0
	s_barrier
	s_add_i32 s58, s58, s19
	s_add_u32 s98, s38, 0x80
	s_addc_u32 s99, s39, 0
	s_mov_b32 m0, s58
	ds_read_b128 v[178:181], v144 offset:16384
	ds_read_b128 v[182:185], v144 offset:17408
	ds_read_b128 v[186:189], v144 offset:18432
	ds_read_b128 v[190:193], v144 offset:19456
	ds_read_b128 v[194:197], v144 offset:20480
	ds_read_b128 v[198:201], v144 offset:21504
	ds_read_b128 v[202:205], v144 offset:22528
	ds_read_b128 v[208:211], v144 offset:23552
	global_load_lds_dwordx4 v134, s[38:39]
	s_add_i32 m0, s58, 0x2000
	s_add_u32 s58, s38, 0x80000
	s_addc_u32 s59, s39, 0
	s_add_i32 s60, s60, s19
	global_load_lds_dwordx4 v130, s[38:39]
	s_mov_b32 m0, s60
	s_add_u32 s100, s42, 0x80
	s_addc_u32 s101, s43, 0
	global_load_lds_dwordx4 v134, s[58:59]
	s_add_i32 m0, s60, 0x2000
	s_nop 0
	global_load_lds_dwordx4 v130, s[58:59]
	s_mov_b32 m0, s44
	s_nop 0
	global_load_lds_dwordx4 v136, s[42:43]
	s_mov_b32 m0, s45
	s_nop 0
	global_load_lds_dwordx4 v132, s[42:43]
	s_waitcnt vmcnt(8)
	s_waitcnt lgkmcnt(0)
	s_barrier
; #define PG8_STAGE(bufoff, gbase, voff) do { _Pragma("unroll") for (int _i = 0; _i < 2; ++_i) \
;         __builtin_amdgcn_global_load_lds((const unsigned*)((const char*)(gbase) + (voff)[_i]), (PG8_LAS unsigned*)(lds + (bufoff) + ldsw + _i * 8192), 16, 0, 0); } while (0)
; #define PG8_LDA(dst, b, h) do { _Pragma("unroll") for (int m = 0; m < 4; ++m) _Pragma("unroll") for (int k = 0; k < 2; ++k) dst[m][k] = *(const PG8_LAS bf16x8*)(lds + PG8_SA(b, h) + aoff + m * 2048 + k * 1024); } while (0)
; #define PG8_LDB(dst, b, h) do { _Pragma("unroll") for (int n = 0; n < 2; ++n) _Pragma("unroll") for (int k = 0; k < 2; ++k) dst[n][k] = *(const PG8_LAS bf16x8*)(lds + PG8_SB(b, h) + boff + n * 2048 + k * 1024); } while (0)
; #define PG8_MMA(ai, bj, At, Bt) do { __builtin_amdgcn_s_setprio(1); _Pragma("unroll") for (int m = 0; m < 4; ++m) _Pragma("unroll") for (int n = 0; n < 2; ++n) _Pragma("unroll") for (int k = 0; k < 2; ++k) \
;         acc[ai][bj][m][n] = __builtin_amdgcn_mfma_f32_16x16x32_bf16(Bt[n][k], At[m][k], acc[ai][bj][m][n], 0, 0, 0); __builtin_amdgcn_s_setprio(0); } while (0)
; #define PG8_WAIT_V(n) asm volatile("s_waitcnt vmcnt(" #n ")" ::: "memory")
; #define PG8_WAIT_L(n) asm volatile("s_waitcnt lgkmcnt(" #n ")" ::: "memory")
; #define PG8_BAR __builtin_amdgcn_s_barrier()
; #define PG8_SCHED __builtin_amdgcn_sched_barrier(0)
; template <class Epi, class Sched, bool ALIGN_EPI = false, bool SP2 = false>
; __device__ __forceinline__ void gemm_phase(PG8_LAS unsigned char* lds, const Gemm g, const Sched& S, const Epi& E, const int tid_in) {
;     ...
;             PG8_WAIT_V(8); PG8_WAIT_L(0); PG8_BAR; PG8_MMA(1, 0, At, B0); PG8_MMA(1, 1, At, B1); PG8_BAR; PG8_SCHED;
;             PG8_LDB(B0, 1, 0); PG8_LDB(B1, 1, 1); PG8_SCHED; PG8_LDA(At, 1, 0); PG8_STAGE(PG8_SA(0, 1), a2 + hstep, voffA);
;             PG8_WAIT_V(8); PG8_WAIT_L(0); PG8_BAR; PG8_MMA(0, 0, At, B0); PG8_MMA(0, 1, At, B1); PG8_BAR; PG8_SCHED;
	s_setprio 1
	s_waitcnt lgkmcnt(0)
	v_mfma_f32_16x16x32_bf16 v[62:65], v[146:149], v[178:181], v[62:65]
	v_mfma_f32_16x16x32_bf16 v[58:61], v[154:157], v[178:181], v[58:61]
	v_mfma_f32_16x16x32_bf16 v[50:53], v[146:149], v[186:189], v[50:53]
	v_mfma_f32_16x16x32_bf16 v[42:45], v[154:157], v[186:189], v[42:45]
	v_mfma_f32_16x16x32_bf16 v[34:37], v[146:149], v[194:197], v[34:37]
	v_mfma_f32_16x16x32_bf16 v[26:29], v[154:157], v[194:197], v[26:29]
	v_mfma_f32_16x16x32_bf16 v[16:19], v[146:149], v[202:205], v[16:19]
	v_mfma_f32_16x16x32_bf16 v[8:11], v[154:157], v[202:205], v[8:11]
	v_mfma_f32_16x16x32_bf16 v[62:65], v[150:153], v[182:185], v[62:65]
	v_mfma_f32_16x16x32_bf16 v[58:61], v[158:161], v[182:185], v[58:61]
	v_mfma_f32_16x16x32_bf16 v[50:53], v[150:153], v[190:193], v[50:53]
	v_mfma_f32_16x16x32_bf16 v[42:45], v[158:161], v[190:193], v[42:45]
	v_mfma_f32_16x16x32_bf16 v[34:37], v[150:153], v[198:201], v[34:37]
	v_mfma_f32_16x16x32_bf16 v[26:29], v[158:161], v[198:201], v[26:29]
	v_mfma_f32_16x16x32_bf16 v[16:19], v[150:153], v[208:211], v[16:19]
	v_mfma_f32_16x16x32_bf16 v[8:11], v[158:161], v[208:211], v[8:11]
	s_setprio 0
	s_setprio 1
	v_mfma_f32_16x16x32_bf16 v[54:57], v[162:165], v[178:181], v[54:57]
	v_mfma_f32_16x16x32_bf16 v[46:49], v[170:173], v[178:181], v[46:49]
	v_mfma_f32_16x16x32_bf16 v[38:41], v[162:165], v[186:189], v[38:41]
	v_mfma_f32_16x16x32_bf16 v[30:33], v[170:173], v[186:189], v[30:33]
	v_mfma_f32_16x16x32_bf16 v[22:25], v[162:165], v[194:197], v[22:25]
	v_mfma_f32_16x16x32_bf16 v[12:15], v[170:173], v[194:197], v[12:15]
	v_mfma_f32_16x16x32_bf16 v[4:7], v[162:165], v[202:205], v[4:7]
	v_mfma_f32_16x16x32_bf16 v[0:3], v[170:173], v[202:205], v[0:3]
	v_mfma_f32_16x16x32_bf16 v[54:57], v[166:169], v[182:185], v[54:57]
	v_mfma_f32_16x16x32_bf16 v[46:49], v[174:177], v[182:185], v[46:49]
	v_mfma_f32_16x16x32_bf16 v[38:41], v[166:169], v[190:193], v[38:41]
	v_mfma_f32_16x16x32_bf16 v[30:33], v[174:177], v[190:193], v[30:33]
	v_mfma_f32_16x16x32_bf16 v[22:25], v[166:169], v[198:201], v[22:25]
	v_mfma_f32_16x16x32_bf16 v[12:15], v[174:177], v[198:201], v[12:15]
	v_mfma_f32_16x16x32_bf16 v[4:7], v[166:169], v[208:211], v[4:7]
	v_mfma_f32_16x16x32_bf16 v[0:3], v[174:177], v[208:211], v[0:3]
	s_setprio 0
	s_barrier
	s_add_i32 s58, 0, 0x18000
	v_add_u32_e32 v145, s58, v142
	s_add_i32 s59, 0, 0x1c000
	ds_read_b128 v[146:149], v145
	ds_read_b128 v[150:153], v145 offset:1024
	ds_read_b128 v[154:157], v145 offset:2048
	ds_read_b128 v[158:161], v145 offset:3072
	v_add_u32_e32 v145, s59, v142
	ds_read_b128 v[162:165], v145
	ds_read_b128 v[166:169], v145 offset:1024
	ds_read_b128 v[170:173], v145 offset:2048
	ds_read_b128 v[174:177], v145 offset:3072
	s_add_u32 s42, s42, 0x80000
	s_addc_u32 s43, s43, 0
	s_mov_b32 m0, s46
	ds_read_b128 v[178:181], v144 offset:32768
	ds_read_b128 v[182:185], v144 offset:33792
	ds_read_b128 v[186:189], v144 offset:34816
	ds_read_b128 v[190:193], v144 offset:35840
	ds_read_b128 v[194:197], v144 offset:36864
	ds_read_b128 v[198:201], v144 offset:37888
	ds_read_b128 v[202:205], v144 offset:38912
	ds_read_b128 v[208:211], v144 offset:39936
	global_load_lds_dwordx4 v136, s[42:43]
	s_mov_b32 m0, s47
	s_nop 0
	global_load_lds_dwordx4 v132, s[42:43]
	s_waitcnt vmcnt(8)
	s_waitcnt lgkmcnt(0)
	s_barrier
	s_setprio 1
	s_waitcnt lgkmcnt(0)
	v_mfma_f32_16x16x32_bf16 v[126:129], v[146:149], v[178:181], v[126:129]
	v_mfma_f32_16x16x32_bf16 v[122:125], v[154:157], v[178:181], v[122:125]
	v_mfma_f32_16x16x32_bf16 v[114:117], v[146:149], v[186:189], v[114:117]
	v_mfma_f32_16x16x32_bf16 v[106:109], v[154:157], v[186:189], v[106:109]
	v_mfma_f32_16x16x32_bf16 v[98:101], v[146:149], v[194:197], v[98:101]
	v_mfma_f32_16x16x32_bf16 v[90:93], v[154:157], v[194:197], v[90:93]
	v_mfma_f32_16x16x32_bf16 v[82:85], v[146:149], v[202:205], v[82:85]
	v_mfma_f32_16x16x32_bf16 v[74:77], v[154:157], v[202:205], v[74:77]
	v_mfma_f32_16x16x32_bf16 v[126:129], v[150:153], v[182:185], v[126:129]
	v_mfma_f32_16x16x32_bf16 v[122:125], v[158:161], v[182:185], v[122:125]
	v_mfma_f32_16x16x32_bf16 v[114:117], v[150:153], v[190:193], v[114:117]
	v_mfma_f32_16x16x32_bf16 v[106:109], v[158:161], v[190:193], v[106:109]
	v_mfma_f32_16x16x32_bf16 v[98:101], v[150:153], v[198:201], v[98:101]
	v_mfma_f32_16x16x32_bf16 v[90:93], v[158:161], v[198:201], v[90:93]
	v_mfma_f32_16x16x32_bf16 v[82:85], v[150:153], v[208:211], v[82:85]
	v_mfma_f32_16x16x32_bf16 v[74:77], v[158:161], v[208:211], v[74:77]
	s_setprio 0
	s_setprio 1
	v_mfma_f32_16x16x32_bf16 v[118:121], v[162:165], v[178:181], v[118:121]
	v_mfma_f32_16x16x32_bf16 v[110:113], v[170:173], v[178:181], v[110:113]
	v_mfma_f32_16x16x32_bf16 v[102:105], v[162:165], v[186:189], v[102:105]
	v_mfma_f32_16x16x32_bf16 v[94:97], v[170:173], v[186:189], v[94:97]
	v_mfma_f32_16x16x32_bf16 v[86:89], v[162:165], v[194:197], v[86:89]
	v_mfma_f32_16x16x32_bf16 v[78:81], v[170:173], v[194:197], v[78:81]
	v_mfma_f32_16x16x32_bf16 v[70:73], v[162:165], v[202:205], v[70:73]
	v_mfma_f32_16x16x32_bf16 v[66:69], v[170:173], v[202:205], v[66:69]
	v_mfma_f32_16x16x32_bf16 v[118:121], v[166:169], v[182:185], v[118:121]
	v_mfma_f32_16x16x32_bf16 v[110:113], v[174:177], v[182:185], v[110:113]
	v_mfma_f32_16x16x32_bf16 v[102:105], v[166:169], v[190:193], v[102:105]
	v_mfma_f32_16x16x32_bf16 v[94:97], v[174:177], v[190:193], v[94:97]
	v_mfma_f32_16x16x32_bf16 v[86:89], v[166:169], v[198:201], v[86:89]
	v_mfma_f32_16x16x32_bf16 v[78:81], v[174:177], v[198:201], v[78:81]
	v_mfma_f32_16x16x32_bf16 v[70:73], v[166:169], v[208:211], v[70:73]
	v_mfma_f32_16x16x32_bf16 v[66:69], v[174:177], v[208:211], v[66:69]
	s_setprio 0
	s_barrier
; #define PG8_STAGE(bufoff, gbase, voff) do { _Pragma("unroll") for (int _i = 0; _i < 2; ++_i) \
;         __builtin_amdgcn_global_load_lds((const unsigned*)((const char*)(gbase) + (voff)[_i]), (PG8_LAS unsigned*)(lds + (bufoff) + ldsw + _i * 8192), 16, 0, 0); } while (0)
; #define PG8_LDA(dst, b, h) do { _Pragma("unroll") for (int m = 0; m < 4; ++m) _Pragma("unroll") for (int k = 0; k < 2; ++k) dst[m][k] = *(const PG8_LAS bf16x8*)(lds + PG8_SA(b, h) + aoff + m * 2048 + k * 1024); } while (0)
; #define PG8_MMA(ai, bj, At, Bt) do { __builtin_amdgcn_s_setprio(1); _Pragma("unroll") for (int m = 0; m < 4; ++m) _Pragma("unroll") for (int n = 0; n < 2; ++n) _Pragma("unroll") for (int k = 0; k < 2; ++k) \
;         acc[ai][bj][m][n] = __builtin_amdgcn_mfma_f32_16x16x32_bf16(Bt[n][k], At[m][k], acc[ai][bj][m][n], 0, 0, 0); __builtin_amdgcn_s_setprio(0); } while (0)
; #define PG8_WAIT_V(n) asm volatile("s_waitcnt vmcnt(" #n ")" ::: "memory")
; #define PG8_WAIT_L(n) asm volatile("s_waitcnt lgkmcnt(" #n ")" ::: "memory")
; #define PG8_BAR __builtin_amdgcn_s_barrier()
; #define PG8_SCHED __builtin_amdgcn_sched_barrier(0)
; template <class Epi, class Sched, bool ALIGN_EPI = false, bool SP2 = false>
; __device__ __forceinline__ void gemm_phase(PG8_LAS unsigned char* lds, const Gemm g, const Sched& S, const Epi& E, const int tid_in) {
;     ...
;             PG8_LDA(At, 1, 1); PG8_STAGE(PG8_SB(1, 0), b3, voffB); PG8_STAGE(PG8_SB(1, 1), b3 + hstep, voffB); PG8_STAGE(PG8_SA(1, 0), a3, voffA);
;             PG8_WAIT_V(8); PG8_WAIT_L(0); PG8_BAR; PG8_MMA(1, 0, At, B0); PG8_MMA(1, 1, At, B1); PG8_BAR; PG8_SCHED;
	s_add_i32 s42, s58, s19
	s_mov_b32 m0, s42
	ds_read_b128 v[178:181], v144 offset:49152
	ds_read_b128 v[182:185], v144 offset:50176
	ds_read_b128 v[186:189], v144 offset:51200
	ds_read_b128 v[190:193], v144 offset:52224
	ds_read_b128 v[194:197], v144 offset:53248
	ds_read_b128 v[198:201], v144 offset:54272
	ds_read_b128 v[202:205], v144 offset:55296
	ds_read_b128 v[208:211], v144 offset:56320
	global_load_lds_dwordx4 v134, s[98:99]
	s_add_i32 m0, s42, 0x2000
	s_add_u32 s38, s38, 0x80080
	s_addc_u32 s39, s39, 0
	s_add_i32 s42, s59, s19
	global_load_lds_dwordx4 v130, s[98:99]
	s_mov_b32 m0, s42
	s_nop 0
	global_load_lds_dwordx4 v134, s[38:39]
	s_add_i32 m0, s42, 0x2000
	s_nop 0
	global_load_lds_dwordx4 v130, s[38:39]
	s_mov_b32 m0, s48
	s_nop 0
	global_load_lds_dwordx4 v136, s[100:101]
	s_mov_b32 m0, s49
	s_nop 0
	global_load_lds_dwordx4 v132, s[100:101]
	s_waitcnt vmcnt(8)
	s_waitcnt lgkmcnt(0)
	s_barrier
	s_setprio 1
	s_waitcnt lgkmcnt(0)
	v_mfma_f32_16x16x32_bf16 v[62:65], v[146:149], v[178:181], v[62:65]
	v_mfma_f32_16x16x32_bf16 v[58:61], v[154:157], v[178:181], v[58:61]
	v_mfma_f32_16x16x32_bf16 v[50:53], v[146:149], v[186:189], v[50:53]
	v_mfma_f32_16x16x32_bf16 v[42:45], v[154:157], v[186:189], v[42:45]
	v_mfma_f32_16x16x32_bf16 v[34:37], v[146:149], v[194:197], v[34:37]
	v_mfma_f32_16x16x32_bf16 v[26:29], v[154:157], v[194:197], v[26:29]
	v_mfma_f32_16x16x32_bf16 v[16:19], v[146:149], v[202:205], v[16:19]
	v_mfma_f32_16x16x32_bf16 v[8:11], v[154:157], v[202:205], v[8:11]
	v_mfma_f32_16x16x32_bf16 v[62:65], v[150:153], v[182:185], v[62:65]
	v_mfma_f32_16x16x32_bf16 v[58:61], v[158:161], v[182:185], v[58:61]
	v_mfma_f32_16x16x32_bf16 v[50:53], v[150:153], v[190:193], v[50:53]
	v_mfma_f32_16x16x32_bf16 v[42:45], v[158:161], v[190:193], v[42:45]
	v_mfma_f32_16x16x32_bf16 v[34:37], v[150:153], v[198:201], v[34:37]
	v_mfma_f32_16x16x32_bf16 v[26:29], v[158:161], v[198:201], v[26:29]
	v_mfma_f32_16x16x32_bf16 v[16:19], v[150:153], v[208:211], v[16:19]
	v_mfma_f32_16x16x32_bf16 v[8:11], v[158:161], v[208:211], v[8:11]
	s_setprio 0
	s_setprio 1
	v_mfma_f32_16x16x32_bf16 v[54:57], v[162:165], v[178:181], v[54:57]
	v_mfma_f32_16x16x32_bf16 v[46:49], v[170:173], v[178:181], v[46:49]
	v_mfma_f32_16x16x32_bf16 v[38:41], v[162:165], v[186:189], v[38:41]
	v_mfma_f32_16x16x32_bf16 v[30:33], v[170:173], v[186:189], v[30:33]
	v_mfma_f32_16x16x32_bf16 v[22:25], v[162:165], v[194:197], v[22:25]
	v_mfma_f32_16x16x32_bf16 v[12:15], v[170:173], v[194:197], v[12:15]
	v_mfma_f32_16x16x32_bf16 v[4:7], v[162:165], v[202:205], v[4:7]
	v_mfma_f32_16x16x32_bf16 v[0:3], v[170:173], v[202:205], v[0:3]
	v_mfma_f32_16x16x32_bf16 v[54:57], v[166:169], v[182:185], v[54:57]
	v_mfma_f32_16x16x32_bf16 v[46:49], v[174:177], v[182:185], v[46:49]
	v_mfma_f32_16x16x32_bf16 v[38:41], v[166:169], v[190:193], v[38:41]
	v_mfma_f32_16x16x32_bf16 v[30:33], v[174:177], v[190:193], v[30:33]
	v_mfma_f32_16x16x32_bf16 v[22:25], v[166:169], v[198:201], v[22:25]
	v_mfma_f32_16x16x32_bf16 v[12:15], v[174:177], v[198:201], v[12:15]
	v_mfma_f32_16x16x32_bf16 v[4:7], v[166:169], v[208:211], v[4:7]
	v_mfma_f32_16x16x32_bf16 v[0:3], v[174:177], v[208:211], v[0:3]
	s_setprio 0
	s_barrier
	s_add_i32 s57, s57, 2
	s_add_u32 s34, s34, 0x100
	s_addc_u32 s35, s35, 0
	s_add_u32 s55, s55, 0x100
	s_addc_u32 s56, s56, 0
	s_cmp_gt_u32 s57, 29
	s_cbranch_scc0 .LBB0_352
	s_and_b64 vcc, exec, s[22:23]
	s_cbranch_vccz .LBB0_355
	s_barrier

; #define PG8_STAGE(bufoff, gbase, voff) do { _Pragma("unroll") for (int _i = 0; _i < 2; ++_i) \
;         __builtin_amdgcn_global_load_lds((const unsigned*)((const char*)(gbase) + (voff)[_i]), (PG8_LAS unsigned*)(lds + (bufoff) + ldsw + _i * 8192), 16, 0, 0); } while (0)
; #define PG8_LDA(dst, b, h) do { _Pragma("unroll") for (int m = 0; m < 4; ++m) _Pragma("unroll") for (int k = 0; k < 2; ++k) dst[m][k] = *(const PG8_LAS bf16x8*)(lds + PG8_SA(b, h) + aoff + m * 2048 + k * 1024); } while (0)
; #define PG8_LDB(dst, b, h) do { _Pragma("unroll") for (int n = 0; n < 2; ++n) _Pragma("unroll") for (int k = 0; k < 2; ++k) dst[n][k] = *(const PG8_LAS bf16x8*)(lds + PG8_SB(b, h) + boff + n * 2048 + k * 1024); } while (0)
; #define PG8_MMA(ai, bj, At, Bt) do { __builtin_amdgcn_s_setprio(1); _Pragma("unroll") for (int m = 0; m < 4; ++m) _Pragma("unroll") for (int n = 0; n < 2; ++n) _Pragma("unroll") for (int k = 0; k < 2; ++k) \
;         acc[ai][bj][m][n] = __builtin_amdgcn_mfma_f32_16x16x32_bf16(Bt[n][k], At[m][k], acc[ai][bj][m][n], 0, 0, 0); __builtin_amdgcn_s_setprio(0); } while (0)
; #define PG8_WAIT_V(n) asm volatile("s_waitcnt vmcnt(" #n ")" ::: "memory")
; #define PG8_WAIT_L(n) asm volatile("s_waitcnt lgkmcnt(" #n ")" ::: "memory")
; #define PG8_BAR __builtin_amdgcn_s_barrier()
; #define PG8_SCHED __builtin_amdgcn_sched_barrier(0)
; template <class Epi, class Sched, bool ALIGN_EPI = false, bool SP2 = false>
; __device__ __forceinline__ void gemm_phase(PG8_LAS unsigned char* lds, const Gemm g, const Sched& S, const Epi& E, const int tid_in) {
;     ...
;             const char* a1 = cA + (size_t)(t + 1) * kstep;
;             const char* a2 = last ? nA : cA + (size_t)(t + 2) * kstep; const char* b2 = last ? nB : cB + (size_t)(t + 2) * kstep;
;             const char* a3 = a2 + kstep; const char* b3 = b2 + kstep;
;             if (last && has_next) S.a_ready(nxt);
;             if constexpr (SP2) {
;             PG8_LDB(B0, 0, 0); PG8_LDB(B1, 0, 1); PG8_SCHED; PG8_LDA(At, 0, 0); PG8_STAGE(PG8_SA(1, 1), a1 + hstep, voffA);
;             PG8_WAIT_V(8); PG8_WAIT_L(0); PG8_BAR; PG8_MMA(0, 0, At, B0); PG8_MMA(0, 1, At, B1); PG8_BAR; PG8_SCHED;
;             PG8_LDA(At, 0, 1); PG8_STAGE(PG8_SB(0, 0), b2, voffB); PG8_STAGE(PG8_SB(0, 1), b2 + hstep, voffB); PG8_STAGE(PG8_SA(0, 0), a2, voffA);
.LBB0_374:
	s_add_u32 s38, s34, 0xfff80080
	s_addc_u32 s39, s35, -1
	s_add_i32 s55, 0, 0x10000
	s_cmp_eq_u32 s54, 28
	s_cselect_b32 s43, s21, s39
	s_cselect_b32 s42, s25, s38
	v_add_u32_e32 v144, s55, v21
	s_cselect_b32 s39, s23, s53
	s_cselect_b32 s38, s51, s52
	s_add_i32 s58, 0, 0x14000
	ds_read_b128 v[148:151], v144
	ds_read_b128 v[152:155], v144 offset:1024
	ds_read_b128 v[156:159], v144 offset:2048
	ds_read_b128 v[160:163], v144 offset:3072
	v_add_u32_e32 v144, s58, v21
	ds_read_b128 v[164:167], v144
	ds_read_b128 v[168:171], v144 offset:1024
	ds_read_b128 v[172:175], v144 offset:2048
	ds_read_b128 v[176:179], v144 offset:3072
	s_add_i32 m0, s44, 0xc000
	ds_read_b128 v[180:183], v147
	ds_read_b128 v[184:187], v147 offset:1024
	ds_read_b128 v[188:191], v147 offset:2048
	ds_read_b128 v[192:195], v147 offset:3072
	ds_read_b128 v[196:199], v147 offset:4096
	ds_read_b128 v[200:203], v147 offset:5120
	ds_read_b128 v[208:211], v147 offset:6144
	ds_read_b128 v[212:215], v147 offset:7168
	global_load_lds_dwordx4 v140, s[34:35]
	s_add_i32 m0, s44, 0xe000
	s_nop 0
	global_load_lds_dwordx4 v142, s[34:35]
	s_waitcnt vmcnt(8)
	s_waitcnt lgkmcnt(0)
	s_barrier
	s_setprio 1
	s_waitcnt lgkmcnt(0)
	v_mfma_f32_16x16x32_bf16 v[126:129], v[148:151], v[180:183], v[126:129]
	v_mfma_f32_16x16x32_bf16 v[122:125], v[156:159], v[180:183], v[122:125]
	v_mfma_f32_16x16x32_bf16 v[118:121], v[148:151], v[188:191], v[118:121]
	v_mfma_f32_16x16x32_bf16 v[110:113], v[156:159], v[188:191], v[110:113]
	v_mfma_f32_16x16x32_bf16 v[102:105], v[148:151], v[196:199], v[102:105]
	v_mfma_f32_16x16x32_bf16 v[94:97], v[156:159], v[196:199], v[94:97]
	v_mfma_f32_16x16x32_bf16 v[86:89], v[148:151], v[208:211], v[86:89]
	v_mfma_f32_16x16x32_bf16 v[78:81], v[156:159], v[208:211], v[78:81]
	v_mfma_f32_16x16x32_bf16 v[126:129], v[152:155], v[184:187], v[126:129]
	v_mfma_f32_16x16x32_bf16 v[122:125], v[160:163], v[184:187], v[122:125]
	v_mfma_f32_16x16x32_bf16 v[118:121], v[152:155], v[192:195], v[118:121]
	v_mfma_f32_16x16x32_bf16 v[110:113], v[160:163], v[192:195], v[110:113]
	v_mfma_f32_16x16x32_bf16 v[102:105], v[152:155], v[200:203], v[102:105]
	v_mfma_f32_16x16x32_bf16 v[94:97], v[160:163], v[200:203], v[94:97]
	v_mfma_f32_16x16x32_bf16 v[86:89], v[152:155], v[212:215], v[86:89]
	v_mfma_f32_16x16x32_bf16 v[78:81], v[160:163], v[212:215], v[78:81]
	s_setprio 0
	s_setprio 1
	v_mfma_f32_16x16x32_bf16 v[114:117], v[164:167], v[180:183], v[114:117]
	v_mfma_f32_16x16x32_bf16 v[106:109], v[172:175], v[180:183], v[106:109]
	v_mfma_f32_16x16x32_bf16 v[98:101], v[164:167], v[188:191], v[98:101]
	v_mfma_f32_16x16x32_bf16 v[90:93], v[172:175], v[188:191], v[90:93]
	v_mfma_f32_16x16x32_bf16 v[82:85], v[164:167], v[196:199], v[82:85]
	v_mfma_f32_16x16x32_bf16 v[74:77], v[172:175], v[196:199], v[74:77]
	v_mfma_f32_16x16x32_bf16 v[70:73], v[164:167], v[208:211], v[70:73]
	v_mfma_f32_16x16x32_bf16 v[66:69], v[172:175], v[208:211], v[66:69]
	v_mfma_f32_16x16x32_bf16 v[114:117], v[168:171], v[184:187], v[114:117]
	v_mfma_f32_16x16x32_bf16 v[106:109], v[176:179], v[184:187], v[106:109]
	v_mfma_f32_16x16x32_bf16 v[98:101], v[168:171], v[192:195], v[98:101]
	v_mfma_f32_16x16x32_bf16 v[90:93], v[176:179], v[192:195], v[90:93]
	v_mfma_f32_16x16x32_bf16 v[82:85], v[168:171], v[200:203], v[82:85]
	v_mfma_f32_16x16x32_bf16 v[74:77], v[176:179], v[200:203], v[74:77]
	v_mfma_f32_16x16x32_bf16 v[70:73], v[168:171], v[212:215], v[70:73]
	v_mfma_f32_16x16x32_bf16 v[66:69], v[176:179], v[212:215], v[66:69]
	s_setprio 0
	s_barrier
	s_add_i32 s55, s55, s19
	s_add_u32 s98, s38, 0x80
	s_addc_u32 s99, s39, 0
	s_mov_b32 m0, s55
	ds_read_b128 v[180:183], v147 offset:16384
	ds_read_b128 v[184:187], v147 offset:17408
	ds_read_b128 v[188:191], v147 offset:18432
	ds_read_b128 v[192:195], v147 offset:19456
	ds_read_b128 v[196:199], v147 offset:20480
	ds_read_b128 v[200:203], v147 offset:21504
	ds_read_b128 v[208:211], v147 offset:22528
	ds_read_b128 v[212:215], v147 offset:23552
	global_load_lds_dwordx4 v132, s[38:39]
	s_add_i32 m0, s55, 0x2000
	s_add_u32 s56, s38, 0x80000
	s_addc_u32 s57, s39, 0
	s_add_i32 s55, s58, s19
	global_load_lds_dwordx4 v136, s[38:39]
	s_mov_b32 m0, s55
	s_add_u32 s100, s42, 0x80
	s_addc_u32 s101, s43, 0
	global_load_lds_dwordx4 v132, s[56:57]
	s_add_i32 m0, s55, 0x2000
	s_nop 0
	global_load_lds_dwordx4 v136, s[56:57]
	s_mov_b32 m0, s44
	s_nop 0
	global_load_lds_dwordx4 v130, s[42:43]
	s_mov_b32 m0, s45
	s_nop 0
	global_load_lds_dwordx4 v134, s[42:43]
	s_waitcnt vmcnt(8)
	s_waitcnt lgkmcnt(0)
	s_barrier
; #define PG8_STAGE(bufoff, gbase, voff) do { _Pragma("unroll") for (int _i = 0; _i < 2; ++_i) \
;         __builtin_amdgcn_global_load_lds((const unsigned*)((const char*)(gbase) + (voff)[_i]), (PG8_LAS unsigned*)(lds + (bufoff) + ldsw + _i * 8192), 16, 0, 0); } while (0)
; #define PG8_LDA(dst, b, h) do { _Pragma("unroll") for (int m = 0; m < 4; ++m) _Pragma("unroll") for (int k = 0; k < 2; ++k) dst[m][k] = *(const PG8_LAS bf16x8*)(lds + PG8_SA(b, h) + aoff + m * 2048 + k * 1024); } while (0)
; #define PG8_LDB(dst, b, h) do { _Pragma("unroll") for (int n = 0; n < 2; ++n) _Pragma("unroll") for (int k = 0; k < 2; ++k) dst[n][k] = *(const PG8_LAS bf16x8*)(lds + PG8_SB(b, h) + boff + n * 2048 + k * 1024); } while (0)
; #define PG8_MMA(ai, bj, At, Bt) do { __builtin_amdgcn_s_setprio(1); _Pragma("unroll") for (int m = 0; m < 4; ++m) _Pragma("unroll") for (int n = 0; n < 2; ++n) _Pragma("unroll") for (int k = 0; k < 2; ++k) \
;         acc[ai][bj][m][n] = __builtin_amdgcn_mfma_f32_16x16x32_bf16(Bt[n][k], At[m][k], acc[ai][bj][m][n], 0, 0, 0); __builtin_amdgcn_s_setprio(0); } while (0)
; #define PG8_WAIT_V(n) asm volatile("s_waitcnt vmcnt(" #n ")" ::: "memory")
; #define PG8_WAIT_L(n) asm volatile("s_waitcnt lgkmcnt(" #n ")" ::: "memory")
; #define PG8_BAR __builtin_amdgcn_s_barrier()
; #define PG8_SCHED __builtin_amdgcn_sched_barrier(0)
; template <class Epi, class Sched, bool ALIGN_EPI = false, bool SP2 = false>
; __device__ __forceinline__ void gemm_phase(PG8_LAS unsigned char* lds, const Gemm g, const Sched& S, const Epi& E, const int tid_in) {
;     ...
;             PG8_WAIT_V(8); PG8_WAIT_L(0); PG8_BAR; PG8_MMA(1, 0, At, B0); PG8_MMA(1, 1, At, B1); PG8_BAR; PG8_SCHED;
;             PG8_LDB(B0, 1, 0); PG8_LDB(B1, 1, 1); PG8_SCHED; PG8_LDA(At, 1, 0); PG8_STAGE(PG8_SA(0, 1), a2 + hstep, voffA);
;             PG8_WAIT_V(8); PG8_WAIT_L(0); PG8_BAR; PG8_MMA(0, 0, At, B0); PG8_MMA(0, 1, At, B1); PG8_BAR; PG8_SCHED;
	s_setprio 1
	s_waitcnt lgkmcnt(0)
	v_mfma_f32_16x16x32_bf16 v[62:65], v[148:151], v[180:183], v[62:65]
	v_mfma_f32_16x16x32_bf16 v[58:61], v[156:159], v[180:183], v[58:61]
	v_mfma_f32_16x16x32_bf16 v[54:57], v[148:151], v[188:191], v[54:57]
	v_mfma_f32_16x16x32_bf16 v[46:49], v[156:159], v[188:191], v[46:49]
	v_mfma_f32_16x16x32_bf16 v[38:41], v[148:151], v[196:199], v[38:41]
	v_mfma_f32_16x16x32_bf16 v[30:33], v[156:159], v[196:199], v[30:33]
	v_mfma_f32_16x16x32_bf16 v[22:25], v[148:151], v[208:211], v[22:25]
	v_mfma_f32_16x16x32_bf16 v[12:15], v[156:159], v[208:211], v[12:15]
	v_mfma_f32_16x16x32_bf16 v[62:65], v[152:155], v[184:187], v[62:65]
	v_mfma_f32_16x16x32_bf16 v[58:61], v[160:163], v[184:187], v[58:61]
	v_mfma_f32_16x16x32_bf16 v[54:57], v[152:155], v[192:195], v[54:57]
	v_mfma_f32_16x16x32_bf16 v[46:49], v[160:163], v[192:195], v[46:49]
	v_mfma_f32_16x16x32_bf16 v[38:41], v[152:155], v[200:203], v[38:41]
	v_mfma_f32_16x16x32_bf16 v[30:33], v[160:163], v[200:203], v[30:33]
	v_mfma_f32_16x16x32_bf16 v[22:25], v[152:155], v[212:215], v[22:25]
	v_mfma_f32_16x16x32_bf16 v[12:15], v[160:163], v[212:215], v[12:15]
	s_setprio 0
	s_setprio 1
	v_mfma_f32_16x16x32_bf16 v[50:53], v[164:167], v[180:183], v[50:53]
	v_mfma_f32_16x16x32_bf16 v[42:45], v[172:175], v[180:183], v[42:45]
	v_mfma_f32_16x16x32_bf16 v[34:37], v[164:167], v[188:191], v[34:37]
	v_mfma_f32_16x16x32_bf16 v[26:29], v[172:175], v[188:191], v[26:29]
	v_mfma_f32_16x16x32_bf16 v[16:19], v[164:167], v[196:199], v[16:19]
	v_mfma_f32_16x16x32_bf16 v[8:11], v[172:175], v[196:199], v[8:11]
	v_mfma_f32_16x16x32_bf16 v[4:7], v[164:167], v[208:211], v[4:7]
	v_mfma_f32_16x16x32_bf16 v[0:3], v[172:175], v[208:211], v[0:3]
	v_mfma_f32_16x16x32_bf16 v[50:53], v[168:171], v[184:187], v[50:53]
	v_mfma_f32_16x16x32_bf16 v[42:45], v[176:179], v[184:187], v[42:45]
	v_mfma_f32_16x16x32_bf16 v[34:37], v[168:171], v[192:195], v[34:37]
	v_mfma_f32_16x16x32_bf16 v[26:29], v[176:179], v[192:195], v[26:29]
	v_mfma_f32_16x16x32_bf16 v[16:19], v[168:171], v[200:203], v[16:19]
	v_mfma_f32_16x16x32_bf16 v[8:11], v[176:179], v[200:203], v[8:11]
	v_mfma_f32_16x16x32_bf16 v[4:7], v[168:171], v[212:215], v[4:7]
	v_mfma_f32_16x16x32_bf16 v[0:3], v[176:179], v[212:215], v[0:3]
	s_setprio 0
	s_barrier
	s_add_i32 s55, 0, 0x18000
	s_add_i32 s56, 0, 0x1c000
	v_add_u32_e32 v160, s55, v21
	v_add_u32_e32 v176, s56, v21
	ds_read_b128 v[148:151], v160
	ds_read_b128 v[152:155], v160 offset:1024
	ds_read_b128 v[156:159], v160 offset:2048
	ds_read_b128 v[160:163], v160 offset:3072
	ds_read_b128 v[164:167], v176
	ds_read_b128 v[168:171], v176 offset:1024
	ds_read_b128 v[172:175], v176 offset:2048
	ds_read_b128 v[176:179], v176 offset:3072
	s_add_u32 s42, s42, 0x80000
	s_addc_u32 s43, s43, 0
	s_mov_b32 m0, s46
	ds_read_b128 v[180:183], v147 offset:32768
	ds_read_b128 v[184:187], v147 offset:33792
	ds_read_b128 v[188:191], v147 offset:34816
	ds_read_b128 v[192:195], v147 offset:35840
	ds_read_b128 v[196:199], v147 offset:36864
	ds_read_b128 v[200:203], v147 offset:37888
	ds_read_b128 v[208:211], v147 offset:38912
	ds_read_b128 v[212:215], v147 offset:39936
	global_load_lds_dwordx4 v130, s[42:43]
	s_mov_b32 m0, s47
	s_nop 0
	global_load_lds_dwordx4 v134, s[42:43]
	s_waitcnt vmcnt(8)
	s_waitcnt lgkmcnt(0)
	s_barrier
	s_setprio 1
	s_waitcnt lgkmcnt(0)
	v_mfma_f32_16x16x32_bf16 v[126:129], v[148:151], v[180:183], v[126:129]
	v_mfma_f32_16x16x32_bf16 v[122:125], v[156:159], v[180:183], v[122:125]
	v_mfma_f32_16x16x32_bf16 v[118:121], v[148:151], v[188:191], v[118:121]
	v_mfma_f32_16x16x32_bf16 v[110:113], v[156:159], v[188:191], v[110:113]
	v_mfma_f32_16x16x32_bf16 v[102:105], v[148:151], v[196:199], v[102:105]
	v_mfma_f32_16x16x32_bf16 v[94:97], v[156:159], v[196:199], v[94:97]
	v_mfma_f32_16x16x32_bf16 v[86:89], v[148:151], v[208:211], v[86:89]
	v_mfma_f32_16x16x32_bf16 v[78:81], v[156:159], v[208:211], v[78:81]
	v_mfma_f32_16x16x32_bf16 v[126:129], v[152:155], v[184:187], v[126:129]
	v_mfma_f32_16x16x32_bf16 v[122:125], v[160:163], v[184:187], v[122:125]
	v_mfma_f32_16x16x32_bf16 v[118:121], v[152:155], v[192:195], v[118:121]
	v_mfma_f32_16x16x32_bf16 v[110:113], v[160:163], v[192:195], v[110:113]
	v_mfma_f32_16x16x32_bf16 v[102:105], v[152:155], v[200:203], v[102:105]
	v_mfma_f32_16x16x32_bf16 v[94:97], v[160:163], v[200:203], v[94:97]
	v_mfma_f32_16x16x32_bf16 v[86:89], v[152:155], v[212:215], v[86:89]
	v_mfma_f32_16x16x32_bf16 v[78:81], v[160:163], v[212:215], v[78:81]
	s_setprio 0
	s_setprio 1
	v_mfma_f32_16x16x32_bf16 v[114:117], v[164:167], v[180:183], v[114:117]
	v_mfma_f32_16x16x32_bf16 v[106:109], v[172:175], v[180:183], v[106:109]
	v_mfma_f32_16x16x32_bf16 v[98:101], v[164:167], v[188:191], v[98:101]
	v_mfma_f32_16x16x32_bf16 v[90:93], v[172:175], v[188:191], v[90:93]
	v_mfma_f32_16x16x32_bf16 v[82:85], v[164:167], v[196:199], v[82:85]
	v_mfma_f32_16x16x32_bf16 v[74:77], v[172:175], v[196:199], v[74:77]
	v_mfma_f32_16x16x32_bf16 v[70:73], v[164:167], v[208:211], v[70:73]
	v_mfma_f32_16x16x32_bf16 v[66:69], v[172:175], v[208:211], v[66:69]
	v_mfma_f32_16x16x32_bf16 v[114:117], v[168:171], v[184:187], v[114:117]
	v_mfma_f32_16x16x32_bf16 v[106:109], v[176:179], v[184:187], v[106:109]
	v_mfma_f32_16x16x32_bf16 v[98:101], v[168:171], v[192:195], v[98:101]
	v_mfma_f32_16x16x32_bf16 v[90:93], v[176:179], v[192:195], v[90:93]
	v_mfma_f32_16x16x32_bf16 v[82:85], v[168:171], v[200:203], v[82:85]
	v_mfma_f32_16x16x32_bf16 v[74:77], v[176:179], v[200:203], v[74:77]
	v_mfma_f32_16x16x32_bf16 v[70:73], v[168:171], v[212:215], v[70:73]
	v_mfma_f32_16x16x32_bf16 v[66:69], v[176:179], v[212:215], v[66:69]
	s_setprio 0
	s_barrier
; #define PG8_STAGE(bufoff, gbase, voff) do { _Pragma("unroll") for (int _i = 0; _i < 2; ++_i) \
;         __builtin_amdgcn_global_load_lds((const unsigned*)((const char*)(gbase) + (voff)[_i]), (PG8_LAS unsigned*)(lds + (bufoff) + ldsw + _i * 8192), 16, 0, 0); } while (0)
; #define PG8_LDA(dst, b, h) do { _Pragma("unroll") for (int m = 0; m < 4; ++m) _Pragma("unroll") for (int k = 0; k < 2; ++k) dst[m][k] = *(const PG8_LAS bf16x8*)(lds + PG8_SA(b, h) + aoff + m * 2048 + k * 1024); } while (0)
; #define PG8_MMA(ai, bj, At, Bt) do { __builtin_amdgcn_s_setprio(1); _Pragma("unroll") for (int m = 0; m < 4; ++m) _Pragma("unroll") for (int n = 0; n < 2; ++n) _Pragma("unroll") for (int k = 0; k < 2; ++k) \
;         acc[ai][bj][m][n] = __builtin_amdgcn_mfma_f32_16x16x32_bf16(Bt[n][k], At[m][k], acc[ai][bj][m][n], 0, 0, 0); __builtin_amdgcn_s_setprio(0); } while (0)
; #define PG8_WAIT_V(n) asm volatile("s_waitcnt vmcnt(" #n ")" ::: "memory")
; #define PG8_WAIT_L(n) asm volatile("s_waitcnt lgkmcnt(" #n ")" ::: "memory")
; #define PG8_BAR __builtin_amdgcn_s_barrier()
; #define PG8_SCHED __builtin_amdgcn_sched_barrier(0)
; template <class Epi, class Sched, bool ALIGN_EPI = false, bool SP2 = false>
; __device__ __forceinline__ void gemm_phase(PG8_LAS unsigned char* lds, const Gemm g, const Sched& S, const Epi& E, const int tid_in) {
;     ...
;             PG8_LDA(At, 1, 1); PG8_STAGE(PG8_SB(1, 0), b3, voffB); PG8_STAGE(PG8_SB(1, 1), b3 + hstep, voffB); PG8_STAGE(PG8_SA(1, 0), a3, voffA);
;             PG8_WAIT_V(8); PG8_WAIT_L(0); PG8_BAR; PG8_MMA(1, 0, At, B0); PG8_MMA(1, 1, At, B1); PG8_BAR; PG8_SCHED;
	s_add_i32 s42, s55, s19
	s_mov_b32 m0, s42
	ds_read_b128 v[180:183], v147 offset:49152
	ds_read_b128 v[184:187], v147 offset:50176
	ds_read_b128 v[188:191], v147 offset:51200
	ds_read_b128 v[192:195], v147 offset:52224
	ds_read_b128 v[196:199], v147 offset:53248
	ds_read_b128 v[200:203], v147 offset:54272
	ds_read_b128 v[208:211], v147 offset:55296
	ds_read_b128 v[212:215], v147 offset:56320
	global_load_lds_dwordx4 v132, s[98:99]
	s_add_i32 m0, s42, 0x2000
	s_add_u32 s38, s38, 0x80080
	s_addc_u32 s39, s39, 0
	s_add_i32 s42, s56, s19
	global_load_lds_dwordx4 v136, s[98:99]
	s_mov_b32 m0, s42
	s_nop 0
	global_load_lds_dwordx4 v132, s[38:39]
	s_add_i32 m0, s42, 0x2000
	s_nop 0
	global_load_lds_dwordx4 v136, s[38:39]
	s_mov_b32 m0, s48
	s_nop 0
	global_load_lds_dwordx4 v130, s[100:101]
	s_mov_b32 m0, s49
	s_nop 0
	global_load_lds_dwordx4 v134, s[100:101]
	s_waitcnt vmcnt(8)
	s_waitcnt lgkmcnt(0)
	s_barrier
	s_setprio 1
	s_waitcnt lgkmcnt(0)
	v_mfma_f32_16x16x32_bf16 v[62:65], v[148:151], v[180:183], v[62:65]
	v_mfma_f32_16x16x32_bf16 v[58:61], v[156:159], v[180:183], v[58:61]
	v_mfma_f32_16x16x32_bf16 v[54:57], v[148:151], v[188:191], v[54:57]
	v_mfma_f32_16x16x32_bf16 v[46:49], v[156:159], v[188:191], v[46:49]
	v_mfma_f32_16x16x32_bf16 v[38:41], v[148:151], v[196:199], v[38:41]
	v_mfma_f32_16x16x32_bf16 v[30:33], v[156:159], v[196:199], v[30:33]
	v_mfma_f32_16x16x32_bf16 v[22:25], v[148:151], v[208:211], v[22:25]
	v_mfma_f32_16x16x32_bf16 v[12:15], v[156:159], v[208:211], v[12:15]
	v_mfma_f32_16x16x32_bf16 v[62:65], v[152:155], v[184:187], v[62:65]
	v_mfma_f32_16x16x32_bf16 v[58:61], v[160:163], v[184:187], v[58:61]
	v_mfma_f32_16x16x32_bf16 v[54:57], v[152:155], v[192:195], v[54:57]
	v_mfma_f32_16x16x32_bf16 v[46:49], v[160:163], v[192:195], v[46:49]
	v_mfma_f32_16x16x32_bf16 v[38:41], v[152:155], v[200:203], v[38:41]
	v_mfma_f32_16x16x32_bf16 v[30:33], v[160:163], v[200:203], v[30:33]
	v_mfma_f32_16x16x32_bf16 v[22:25], v[152:155], v[212:215], v[22:25]
	v_mfma_f32_16x16x32_bf16 v[12:15], v[160:163], v[212:215], v[12:15]
	s_setprio 0
	s_setprio 1
	v_mfma_f32_16x16x32_bf16 v[50:53], v[164:167], v[180:183], v[50:53]
	v_mfma_f32_16x16x32_bf16 v[42:45], v[172:175], v[180:183], v[42:45]
	v_mfma_f32_16x16x32_bf16 v[34:37], v[164:167], v[188:191], v[34:37]
	v_mfma_f32_16x16x32_bf16 v[26:29], v[172:175], v[188:191], v[26:29]
	v_mfma_f32_16x16x32_bf16 v[16:19], v[164:167], v[196:199], v[16:19]
	v_mfma_f32_16x16x32_bf16 v[8:11], v[172:175], v[196:199], v[8:11]
	v_mfma_f32_16x16x32_bf16 v[4:7], v[164:167], v[208:211], v[4:7]
	v_mfma_f32_16x16x32_bf16 v[0:3], v[172:175], v[208:211], v[0:3]
	v_mfma_f32_16x16x32_bf16 v[50:53], v[168:171], v[184:187], v[50:53]
	v_mfma_f32_16x16x32_bf16 v[42:45], v[176:179], v[184:187], v[42:45]
	v_mfma_f32_16x16x32_bf16 v[34:37], v[168:171], v[192:195], v[34:37]
	v_mfma_f32_16x16x32_bf16 v[26:29], v[176:179], v[192:195], v[26:29]
	v_mfma_f32_16x16x32_bf16 v[16:19], v[168:171], v[200:203], v[16:19]
	v_mfma_f32_16x16x32_bf16 v[8:11], v[176:179], v[200:203], v[8:11]
	v_mfma_f32_16x16x32_bf16 v[4:7], v[168:171], v[212:215], v[4:7]
	v_mfma_f32_16x16x32_bf16 v[0:3], v[176:179], v[212:215], v[0:3]
	s_setprio 0
	s_barrier
	s_add_i32 s54, s54, 2
	s_add_u32 s34, s34, 0x100
	s_addc_u32 s35, s35, 0
	s_add_u32 s52, s52, 0x100
	s_addc_u32 s53, s53, 0
	s_cmp_gt_u32 s54, 29
	s_cbranch_scc0 .LBB0_374
	s_and_b64 vcc, exec, s[6:7]
	v_readlane_b32 s52, v255, 9
	v_readlane_b32 s53, v255, 10
	s_cbranch_vccz .LBB0_377
	s_barrier

; #define PG8_STAGE(bufoff, gbase, voff) do { _Pragma("unroll") for (int _i = 0; _i < 2; ++_i) \
;         __builtin_amdgcn_global_load_lds((const unsigned*)((const char*)(gbase) + (voff)[_i]), (PG8_LAS unsigned*)(lds + (bufoff) + ldsw + _i * 8192), 16, 0, 0); } while (0)
; #define PG8_LDA(dst, b, h) do { _Pragma("unroll") for (int m = 0; m < 4; ++m) _Pragma("unroll") for (int k = 0; k < 2; ++k) dst[m][k] = *(const PG8_LAS bf16x8*)(lds + PG8_SA(b, h) + aoff + m * 2048 + k * 1024); } while (0)
; #define PG8_LDB(dst, b, h) do { _Pragma("unroll") for (int n = 0; n < 2; ++n) _Pragma("unroll") for (int k = 0; k < 2; ++k) dst[n][k] = *(const PG8_LAS bf16x8*)(lds + PG8_SB(b, h) + boff + n * 2048 + k * 1024); } while (0)
; #define PG8_MMA(ai, bj, At, Bt) do { __builtin_amdgcn_s_setprio(1); _Pragma("unroll") for (int m = 0; m < 4; ++m) _Pragma("unroll") for (int n = 0; n < 2; ++n) _Pragma("unroll") for (int k = 0; k < 2; ++k) \
;         acc[ai][bj][m][n] = __builtin_amdgcn_mfma_f32_16x16x32_bf16(Bt[n][k], At[m][k], acc[ai][bj][m][n], 0, 0, 0); __builtin_amdgcn_s_setprio(0); } while (0)
; #define PG8_WAIT_V(n) asm volatile("s_waitcnt vmcnt(" #n ")" ::: "memory")
; #define PG8_WAIT_L(n) asm volatile("s_waitcnt lgkmcnt(" #n ")" ::: "memory")
; #define PG8_BAR __builtin_amdgcn_s_barrier()
; #define PG8_SCHED __builtin_amdgcn_sched_barrier(0)
; template <class Epi, class Sched, bool ALIGN_EPI = false, bool SP2 = false>
; __device__ __forceinline__ void gemm_phase(PG8_LAS unsigned char* lds, const Gemm g, const Sched& S, const Epi& E, const int tid_in) {
;     ...
;             const char* a1 = cA + (size_t)(t + 1) * kstep;
;             const char* a2 = last ? nA : cA + (size_t)(t + 2) * kstep; const char* b2 = last ? nB : cB + (size_t)(t + 2) * kstep;
;             const char* a3 = a2 + kstep; const char* b3 = b2 + kstep;
;             if (last && has_next) S.a_ready(nxt);
;             if constexpr (SP2) {
;             PG8_LDB(B0, 0, 0); PG8_LDB(B1, 0, 1); PG8_SCHED; PG8_LDA(At, 0, 0); PG8_STAGE(PG8_SA(1, 1), a1 + hstep, voffA);
;             PG8_WAIT_V(8); PG8_WAIT_L(0); PG8_BAR; PG8_MMA(0, 0, At, B0); PG8_MMA(0, 1, At, B1); PG8_BAR; PG8_SCHED;
;             PG8_LDA(At, 0, 1); PG8_STAGE(PG8_SB(0, 0), b2, voffB); PG8_STAGE(PG8_SB(0, 1), b2 + hstep, voffB); PG8_STAGE(PG8_SA(0, 0), a2, voffA);
.LBB0_394:
	s_add_u32 s30, s28, 0xfff80080
	s_addc_u32 s31, s29, -1
	s_add_i32 s54, 0, 0x10000
	s_cmp_eq_u32 s53, 28
	s_cselect_b32 s35, s23, s31
	s_cselect_b32 s34, s49, s30
	v_add_u32_e32 v144, s54, v21
	s_cselect_b32 s31, s21, s52
	s_cselect_b32 s30, s50, s51
	s_add_i32 s56, 0, 0x14000
	ds_read_b128 v[148:151], v144
	ds_read_b128 v[152:155], v144 offset:1024
	ds_read_b128 v[156:159], v144 offset:2048
	ds_read_b128 v[160:163], v144 offset:3072
	v_add_u32_e32 v144, s56, v21
	ds_read_b128 v[164:167], v144
	ds_read_b128 v[168:171], v144 offset:1024
	ds_read_b128 v[172:175], v144 offset:2048
	ds_read_b128 v[176:179], v144 offset:3072
	s_add_i32 m0, s38, 0xc000
	ds_read_b128 v[180:183], v147
	ds_read_b128 v[184:187], v147 offset:1024
	ds_read_b128 v[188:191], v147 offset:2048
	ds_read_b128 v[192:195], v147 offset:3072
	ds_read_b128 v[196:199], v147 offset:4096
	ds_read_b128 v[200:203], v147 offset:5120
	ds_read_b128 v[208:211], v147 offset:6144
	ds_read_b128 v[212:215], v147 offset:7168
	global_load_lds_dwordx4 v140, s[28:29]
	s_add_i32 m0, s38, 0xe000
	s_nop 0
	global_load_lds_dwordx4 v142, s[28:29]
	s_waitcnt vmcnt(8)
	s_waitcnt lgkmcnt(0)
	s_barrier
	s_setprio 1
	s_waitcnt lgkmcnt(0)
	v_mfma_f32_16x16x32_bf16 v[126:129], v[148:151], v[180:183], v[126:129]
	v_mfma_f32_16x16x32_bf16 v[122:125], v[156:159], v[180:183], v[122:125]
	v_mfma_f32_16x16x32_bf16 v[118:121], v[148:151], v[188:191], v[118:121]
	v_mfma_f32_16x16x32_bf16 v[110:113], v[156:159], v[188:191], v[110:113]
	v_mfma_f32_16x16x32_bf16 v[102:105], v[148:151], v[196:199], v[102:105]
	v_mfma_f32_16x16x32_bf16 v[94:97], v[156:159], v[196:199], v[94:97]
	v_mfma_f32_16x16x32_bf16 v[86:89], v[148:151], v[208:211], v[86:89]
	v_mfma_f32_16x16x32_bf16 v[78:81], v[156:159], v[208:211], v[78:81]
	v_mfma_f32_16x16x32_bf16 v[126:129], v[152:155], v[184:187], v[126:129]
	v_mfma_f32_16x16x32_bf16 v[122:125], v[160:163], v[184:187], v[122:125]
	v_mfma_f32_16x16x32_bf16 v[118:121], v[152:155], v[192:195], v[118:121]
	v_mfma_f32_16x16x32_bf16 v[110:113], v[160:163], v[192:195], v[110:113]
	v_mfma_f32_16x16x32_bf16 v[102:105], v[152:155], v[200:203], v[102:105]
	v_mfma_f32_16x16x32_bf16 v[94:97], v[160:163], v[200:203], v[94:97]
	v_mfma_f32_16x16x32_bf16 v[86:89], v[152:155], v[212:215], v[86:89]
	v_mfma_f32_16x16x32_bf16 v[78:81], v[160:163], v[212:215], v[78:81]
	s_setprio 0
	s_setprio 1
	v_mfma_f32_16x16x32_bf16 v[114:117], v[164:167], v[180:183], v[114:117]
	v_mfma_f32_16x16x32_bf16 v[106:109], v[172:175], v[180:183], v[106:109]
	v_mfma_f32_16x16x32_bf16 v[98:101], v[164:167], v[188:191], v[98:101]
	v_mfma_f32_16x16x32_bf16 v[90:93], v[172:175], v[188:191], v[90:93]
	v_mfma_f32_16x16x32_bf16 v[82:85], v[164:167], v[196:199], v[82:85]
	v_mfma_f32_16x16x32_bf16 v[74:77], v[172:175], v[196:199], v[74:77]
	v_mfma_f32_16x16x32_bf16 v[70:73], v[164:167], v[208:211], v[70:73]
	v_mfma_f32_16x16x32_bf16 v[66:69], v[172:175], v[208:211], v[66:69]
	v_mfma_f32_16x16x32_bf16 v[114:117], v[168:171], v[184:187], v[114:117]
	v_mfma_f32_16x16x32_bf16 v[106:109], v[176:179], v[184:187], v[106:109]
	v_mfma_f32_16x16x32_bf16 v[98:101], v[168:171], v[192:195], v[98:101]
	v_mfma_f32_16x16x32_bf16 v[90:93], v[176:179], v[192:195], v[90:93]
	v_mfma_f32_16x16x32_bf16 v[82:85], v[168:171], v[200:203], v[82:85]
	v_mfma_f32_16x16x32_bf16 v[74:77], v[176:179], v[200:203], v[74:77]
	v_mfma_f32_16x16x32_bf16 v[70:73], v[168:171], v[212:215], v[70:73]
	v_mfma_f32_16x16x32_bf16 v[66:69], v[176:179], v[212:215], v[66:69]
	s_setprio 0
	s_barrier
	s_add_i32 s54, s54, s19
	s_add_u32 s98, s30, 0x80
	s_addc_u32 s99, s31, 0
	s_mov_b32 m0, s54
	ds_read_b128 v[180:183], v147 offset:16384
	ds_read_b128 v[184:187], v147 offset:17408
	ds_read_b128 v[188:191], v147 offset:18432
	ds_read_b128 v[192:195], v147 offset:19456
	ds_read_b128 v[196:199], v147 offset:20480
	ds_read_b128 v[200:203], v147 offset:21504
	ds_read_b128 v[208:211], v147 offset:22528
	ds_read_b128 v[212:215], v147 offset:23552
	global_load_lds_dwordx4 v134, s[30:31]
	s_add_i32 m0, s54, 0x2000
	s_add_u32 s54, s30, 0x80000
	s_addc_u32 s55, s31, 0
	s_add_i32 s56, s56, s19
	global_load_lds_dwordx4 v130, s[30:31]
	s_mov_b32 m0, s56
	s_add_u32 s100, s34, 0x80
	s_addc_u32 s101, s35, 0
	global_load_lds_dwordx4 v134, s[54:55]
	s_add_i32 m0, s56, 0x2000
	s_nop 0
	global_load_lds_dwordx4 v130, s[54:55]
	s_mov_b32 m0, s38
	s_nop 0
	global_load_lds_dwordx4 v136, s[34:35]
	s_mov_b32 m0, s39
	s_nop 0
	global_load_lds_dwordx4 v132, s[34:35]
	s_waitcnt vmcnt(8)
	s_waitcnt lgkmcnt(0)
	s_barrier
; #define PG8_STAGE(bufoff, gbase, voff) do { _Pragma("unroll") for (int _i = 0; _i < 2; ++_i) \
;         __builtin_amdgcn_global_load_lds((const unsigned*)((const char*)(gbase) + (voff)[_i]), (PG8_LAS unsigned*)(lds + (bufoff) + ldsw + _i * 8192), 16, 0, 0); } while (0)
; #define PG8_LDA(dst, b, h) do { _Pragma("unroll") for (int m = 0; m < 4; ++m) _Pragma("unroll") for (int k = 0; k < 2; ++k) dst[m][k] = *(const PG8_LAS bf16x8*)(lds + PG8_SA(b, h) + aoff + m * 2048 + k * 1024); } while (0)
; #define PG8_LDB(dst, b, h) do { _Pragma("unroll") for (int n = 0; n < 2; ++n) _Pragma("unroll") for (int k = 0; k < 2; ++k) dst[n][k] = *(const PG8_LAS bf16x8*)(lds + PG8_SB(b, h) + boff + n * 2048 + k * 1024); } while (0)
; #define PG8_MMA(ai, bj, At, Bt) do { __builtin_amdgcn_s_setprio(1); _Pragma("unroll") for (int m = 0; m < 4; ++m) _Pragma("unroll") for (int n = 0; n < 2; ++n) _Pragma("unroll") for (int k = 0; k < 2; ++k) \
;         acc[ai][bj][m][n] = __builtin_amdgcn_mfma_f32_16x16x32_bf16(Bt[n][k], At[m][k], acc[ai][bj][m][n], 0, 0, 0); __builtin_amdgcn_s_setprio(0); } while (0)
; #define PG8_WAIT_V(n) asm volatile("s_waitcnt vmcnt(" #n ")" ::: "memory")
; #define PG8_WAIT_L(n) asm volatile("s_waitcnt lgkmcnt(" #n ")" ::: "memory")
; #define PG8_BAR __builtin_amdgcn_s_barrier()
; #define PG8_SCHED __builtin_amdgcn_sched_barrier(0)
; template <class Epi, class Sched, bool ALIGN_EPI = false, bool SP2 = false>
; __device__ __forceinline__ void gemm_phase(PG8_LAS unsigned char* lds, const Gemm g, const Sched& S, const Epi& E, const int tid_in) {
;     ...
;             PG8_WAIT_V(8); PG8_WAIT_L(0); PG8_BAR; PG8_MMA(1, 0, At, B0); PG8_MMA(1, 1, At, B1); PG8_BAR; PG8_SCHED;
;             PG8_LDB(B0, 1, 0); PG8_LDB(B1, 1, 1); PG8_SCHED; PG8_LDA(At, 1, 0); PG8_STAGE(PG8_SA(0, 1), a2 + hstep, voffA);
;             PG8_WAIT_V(8); PG8_WAIT_L(0); PG8_BAR; PG8_MMA(0, 0, At, B0); PG8_MMA(0, 1, At, B1); PG8_BAR; PG8_SCHED;
	s_setprio 1
	s_waitcnt lgkmcnt(0)
	v_mfma_f32_16x16x32_bf16 v[62:65], v[148:151], v[180:183], v[62:65]
	v_mfma_f32_16x16x32_bf16 v[58:61], v[156:159], v[180:183], v[58:61]
	v_mfma_f32_16x16x32_bf16 v[54:57], v[148:151], v[188:191], v[54:57]
	v_mfma_f32_16x16x32_bf16 v[46:49], v[156:159], v[188:191], v[46:49]
	v_mfma_f32_16x16x32_bf16 v[38:41], v[148:151], v[196:199], v[38:41]
	v_mfma_f32_16x16x32_bf16 v[30:33], v[156:159], v[196:199], v[30:33]
	v_mfma_f32_16x16x32_bf16 v[22:25], v[148:151], v[208:211], v[22:25]
	v_mfma_f32_16x16x32_bf16 v[12:15], v[156:159], v[208:211], v[12:15]
	v_mfma_f32_16x16x32_bf16 v[62:65], v[152:155], v[184:187], v[62:65]
	v_mfma_f32_16x16x32_bf16 v[58:61], v[160:163], v[184:187], v[58:61]
	v_mfma_f32_16x16x32_bf16 v[54:57], v[152:155], v[192:195], v[54:57]
	v_mfma_f32_16x16x32_bf16 v[46:49], v[160:163], v[192:195], v[46:49]
	v_mfma_f32_16x16x32_bf16 v[38:41], v[152:155], v[200:203], v[38:41]
	v_mfma_f32_16x16x32_bf16 v[30:33], v[160:163], v[200:203], v[30:33]
	v_mfma_f32_16x16x32_bf16 v[22:25], v[152:155], v[212:215], v[22:25]
	v_mfma_f32_16x16x32_bf16 v[12:15], v[160:163], v[212:215], v[12:15]
	s_setprio 0
	s_setprio 1
	v_mfma_f32_16x16x32_bf16 v[50:53], v[164:167], v[180:183], v[50:53]
	v_mfma_f32_16x16x32_bf16 v[42:45], v[172:175], v[180:183], v[42:45]
	v_mfma_f32_16x16x32_bf16 v[34:37], v[164:167], v[188:191], v[34:37]
	v_mfma_f32_16x16x32_bf16 v[26:29], v[172:175], v[188:191], v[26:29]
	v_mfma_f32_16x16x32_bf16 v[16:19], v[164:167], v[196:199], v[16:19]
	v_mfma_f32_16x16x32_bf16 v[8:11], v[172:175], v[196:199], v[8:11]
	v_mfma_f32_16x16x32_bf16 v[4:7], v[164:167], v[208:211], v[4:7]
	v_mfma_f32_16x16x32_bf16 v[0:3], v[172:175], v[208:211], v[0:3]
	v_mfma_f32_16x16x32_bf16 v[50:53], v[168:171], v[184:187], v[50:53]
	v_mfma_f32_16x16x32_bf16 v[42:45], v[176:179], v[184:187], v[42:45]
	v_mfma_f32_16x16x32_bf16 v[34:37], v[168:171], v[192:195], v[34:37]
	v_mfma_f32_16x16x32_bf16 v[26:29], v[176:179], v[192:195], v[26:29]
	v_mfma_f32_16x16x32_bf16 v[16:19], v[168:171], v[200:203], v[16:19]
	v_mfma_f32_16x16x32_bf16 v[8:11], v[176:179], v[200:203], v[8:11]
	v_mfma_f32_16x16x32_bf16 v[4:7], v[168:171], v[212:215], v[4:7]
	v_mfma_f32_16x16x32_bf16 v[0:3], v[176:179], v[212:215], v[0:3]
	s_setprio 0
	s_barrier
	s_add_i32 s54, 0, 0x18000
	s_add_i32 s55, 0, 0x1c000
	v_add_u32_e32 v160, s54, v21
	v_add_u32_e32 v176, s55, v21
	ds_read_b128 v[148:151], v160
	ds_read_b128 v[152:155], v160 offset:1024
	ds_read_b128 v[156:159], v160 offset:2048
	ds_read_b128 v[160:163], v160 offset:3072
	ds_read_b128 v[164:167], v176
	ds_read_b128 v[168:171], v176 offset:1024
	ds_read_b128 v[172:175], v176 offset:2048
	ds_read_b128 v[176:179], v176 offset:3072
	s_add_u32 s34, s34, 0x80000
	s_addc_u32 s35, s35, 0
	s_mov_b32 m0, s42
	ds_read_b128 v[180:183], v147 offset:32768
	ds_read_b128 v[184:187], v147 offset:33792
	ds_read_b128 v[188:191], v147 offset:34816
	ds_read_b128 v[192:195], v147 offset:35840
	ds_read_b128 v[196:199], v147 offset:36864
	ds_read_b128 v[200:203], v147 offset:37888
	ds_read_b128 v[208:211], v147 offset:38912
	ds_read_b128 v[212:215], v147 offset:39936
	global_load_lds_dwordx4 v136, s[34:35]
	s_mov_b32 m0, s43
	s_nop 0
	global_load_lds_dwordx4 v132, s[34:35]
	s_waitcnt vmcnt(8)
	s_waitcnt lgkmcnt(0)
	s_barrier
	s_setprio 1
	s_waitcnt lgkmcnt(0)
	v_mfma_f32_16x16x32_bf16 v[126:129], v[148:151], v[180:183], v[126:129]
	v_mfma_f32_16x16x32_bf16 v[122:125], v[156:159], v[180:183], v[122:125]
	v_mfma_f32_16x16x32_bf16 v[118:121], v[148:151], v[188:191], v[118:121]
	v_mfma_f32_16x16x32_bf16 v[110:113], v[156:159], v[188:191], v[110:113]
	v_mfma_f32_16x16x32_bf16 v[102:105], v[148:151], v[196:199], v[102:105]
	v_mfma_f32_16x16x32_bf16 v[94:97], v[156:159], v[196:199], v[94:97]
	v_mfma_f32_16x16x32_bf16 v[86:89], v[148:151], v[208:211], v[86:89]
	v_mfma_f32_16x16x32_bf16 v[78:81], v[156:159], v[208:211], v[78:81]
	v_mfma_f32_16x16x32_bf16 v[126:129], v[152:155], v[184:187], v[126:129]
	v_mfma_f32_16x16x32_bf16 v[122:125], v[160:163], v[184:187], v[122:125]
	v_mfma_f32_16x16x32_bf16 v[118:121], v[152:155], v[192:195], v[118:121]
	v_mfma_f32_16x16x32_bf16 v[110:113], v[160:163], v[192:195], v[110:113]
	v_mfma_f32_16x16x32_bf16 v[102:105], v[152:155], v[200:203], v[102:105]
	v_mfma_f32_16x16x32_bf16 v[94:97], v[160:163], v[200:203], v[94:97]
	v_mfma_f32_16x16x32_bf16 v[86:89], v[152:155], v[212:215], v[86:89]
	v_mfma_f32_16x16x32_bf16 v[78:81], v[160:163], v[212:215], v[78:81]
	s_setprio 0
	s_setprio 1
	v_mfma_f32_16x16x32_bf16 v[114:117], v[164:167], v[180:183], v[114:117]
	v_mfma_f32_16x16x32_bf16 v[106:109], v[172:175], v[180:183], v[106:109]
	v_mfma_f32_16x16x32_bf16 v[98:101], v[164:167], v[188:191], v[98:101]
	v_mfma_f32_16x16x32_bf16 v[90:93], v[172:175], v[188:191], v[90:93]
	v_mfma_f32_16x16x32_bf16 v[82:85], v[164:167], v[196:199], v[82:85]
	v_mfma_f32_16x16x32_bf16 v[74:77], v[172:175], v[196:199], v[74:77]
	v_mfma_f32_16x16x32_bf16 v[70:73], v[164:167], v[208:211], v[70:73]
	v_mfma_f32_16x16x32_bf16 v[66:69], v[172:175], v[208:211], v[66:69]
	v_mfma_f32_16x16x32_bf16 v[114:117], v[168:171], v[184:187], v[114:117]
	v_mfma_f32_16x16x32_bf16 v[106:109], v[176:179], v[184:187], v[106:109]
	v_mfma_f32_16x16x32_bf16 v[98:101], v[168:171], v[192:195], v[98:101]
	v_mfma_f32_16x16x32_bf16 v[90:93], v[176:179], v[192:195], v[90:93]
	v_mfma_f32_16x16x32_bf16 v[82:85], v[168:171], v[200:203], v[82:85]
	v_mfma_f32_16x16x32_bf16 v[74:77], v[176:179], v[200:203], v[74:77]
	v_mfma_f32_16x16x32_bf16 v[70:73], v[168:171], v[212:215], v[70:73]
	v_mfma_f32_16x16x32_bf16 v[66:69], v[176:179], v[212:215], v[66:69]
	s_setprio 0
	s_barrier
; #define PG8_STAGE(bufoff, gbase, voff) do { _Pragma("unroll") for (int _i = 0; _i < 2; ++_i) \
;         __builtin_amdgcn_global_load_lds((const unsigned*)((const char*)(gbase) + (voff)[_i]), (PG8_LAS unsigned*)(lds + (bufoff) + ldsw + _i * 8192), 16, 0, 0); } while (0)
; #define PG8_LDA(dst, b, h) do { _Pragma("unroll") for (int m = 0; m < 4; ++m) _Pragma("unroll") for (int k = 0; k < 2; ++k) dst[m][k] = *(const PG8_LAS bf16x8*)(lds + PG8_SA(b, h) + aoff + m * 2048 + k * 1024); } while (0)
; #define PG8_MMA(ai, bj, At, Bt) do { __builtin_amdgcn_s_setprio(1); _Pragma("unroll") for (int m = 0; m < 4; ++m) _Pragma("unroll") for (int n = 0; n < 2; ++n) _Pragma("unroll") for (int k = 0; k < 2; ++k) \
;         acc[ai][bj][m][n] = __builtin_amdgcn_mfma_f32_16x16x32_bf16(Bt[n][k], At[m][k], acc[ai][bj][m][n], 0, 0, 0); __builtin_amdgcn_s_setprio(0); } while (0)
; #define PG8_WAIT_V(n) asm volatile("s_waitcnt vmcnt(" #n ")" ::: "memory")
; #define PG8_WAIT_L(n) asm volatile("s_waitcnt lgkmcnt(" #n ")" ::: "memory")
; #define PG8_BAR __builtin_amdgcn_s_barrier()
; #define PG8_SCHED __builtin_amdgcn_sched_barrier(0)
; template <class Epi, class Sched, bool ALIGN_EPI = false, bool SP2 = false>
; __device__ __forceinline__ void gemm_phase(PG8_LAS unsigned char* lds, const Gemm g, const Sched& S, const Epi& E, const int tid_in) {
;     ...
;             PG8_LDA(At, 1, 1); PG8_STAGE(PG8_SB(1, 0), b3, voffB); PG8_STAGE(PG8_SB(1, 1), b3 + hstep, voffB); PG8_STAGE(PG8_SA(1, 0), a3, voffA);
;             PG8_WAIT_V(8); PG8_WAIT_L(0); PG8_BAR; PG8_MMA(1, 0, At, B0); PG8_MMA(1, 1, At, B1); PG8_BAR; PG8_SCHED;
	s_add_i32 s34, s54, s19
	s_mov_b32 m0, s34
	ds_read_b128 v[180:183], v147 offset:49152
	ds_read_b128 v[184:187], v147 offset:50176
	ds_read_b128 v[188:191], v147 offset:51200
	ds_read_b128 v[192:195], v147 offset:52224
	ds_read_b128 v[196:199], v147 offset:53248
	ds_read_b128 v[200:203], v147 offset:54272
	ds_read_b128 v[208:211], v147 offset:55296
	ds_read_b128 v[212:215], v147 offset:56320
	global_load_lds_dwordx4 v134, s[98:99]
	s_add_i32 m0, s34, 0x2000
	s_add_u32 s30, s30, 0x80080
	s_addc_u32 s31, s31, 0
	s_add_i32 s34, s55, s19
	global_load_lds_dwordx4 v130, s[98:99]
	s_mov_b32 m0, s34
	s_nop 0
	global_load_lds_dwordx4 v134, s[30:31]
	s_add_i32 m0, s34, 0x2000
	s_nop 0
	global_load_lds_dwordx4 v130, s[30:31]
	s_mov_b32 m0, s44
	s_nop 0
	global_load_lds_dwordx4 v136, s[100:101]
	s_mov_b32 m0, s45
	s_nop 0
	global_load_lds_dwordx4 v132, s[100:101]
	s_waitcnt vmcnt(8)
	s_waitcnt lgkmcnt(0)
	s_barrier
	s_setprio 1
	s_waitcnt lgkmcnt(0)
	v_mfma_f32_16x16x32_bf16 v[62:65], v[148:151], v[180:183], v[62:65]
	v_mfma_f32_16x16x32_bf16 v[58:61], v[156:159], v[180:183], v[58:61]
	v_mfma_f32_16x16x32_bf16 v[54:57], v[148:151], v[188:191], v[54:57]
	v_mfma_f32_16x16x32_bf16 v[46:49], v[156:159], v[188:191], v[46:49]
	v_mfma_f32_16x16x32_bf16 v[38:41], v[148:151], v[196:199], v[38:41]
	v_mfma_f32_16x16x32_bf16 v[30:33], v[156:159], v[196:199], v[30:33]
	v_mfma_f32_16x16x32_bf16 v[22:25], v[148:151], v[208:211], v[22:25]
	v_mfma_f32_16x16x32_bf16 v[12:15], v[156:159], v[208:211], v[12:15]
	v_mfma_f32_16x16x32_bf16 v[62:65], v[152:155], v[184:187], v[62:65]
	v_mfma_f32_16x16x32_bf16 v[58:61], v[160:163], v[184:187], v[58:61]
	v_mfma_f32_16x16x32_bf16 v[54:57], v[152:155], v[192:195], v[54:57]
	v_mfma_f32_16x16x32_bf16 v[46:49], v[160:163], v[192:195], v[46:49]
	v_mfma_f32_16x16x32_bf16 v[38:41], v[152:155], v[200:203], v[38:41]
	v_mfma_f32_16x16x32_bf16 v[30:33], v[160:163], v[200:203], v[30:33]
	v_mfma_f32_16x16x32_bf16 v[22:25], v[152:155], v[212:215], v[22:25]
	v_mfma_f32_16x16x32_bf16 v[12:15], v[160:163], v[212:215], v[12:15]
	s_setprio 0
	s_setprio 1
	v_mfma_f32_16x16x32_bf16 v[50:53], v[164:167], v[180:183], v[50:53]
	v_mfma_f32_16x16x32_bf16 v[42:45], v[172:175], v[180:183], v[42:45]
	v_mfma_f32_16x16x32_bf16 v[34:37], v[164:167], v[188:191], v[34:37]
	v_mfma_f32_16x16x32_bf16 v[26:29], v[172:175], v[188:191], v[26:29]
	v_mfma_f32_16x16x32_bf16 v[16:19], v[164:167], v[196:199], v[16:19]
	v_mfma_f32_16x16x32_bf16 v[8:11], v[172:175], v[196:199], v[8:11]
	v_mfma_f32_16x16x32_bf16 v[4:7], v[164:167], v[208:211], v[4:7]
	v_mfma_f32_16x16x32_bf16 v[0:3], v[172:175], v[208:211], v[0:3]
	v_mfma_f32_16x16x32_bf16 v[50:53], v[168:171], v[184:187], v[50:53]
	v_mfma_f32_16x16x32_bf16 v[42:45], v[176:179], v[184:187], v[42:45]
	v_mfma_f32_16x16x32_bf16 v[34:37], v[168:171], v[192:195], v[34:37]
	v_mfma_f32_16x16x32_bf16 v[26:29], v[176:179], v[192:195], v[26:29]
	v_mfma_f32_16x16x32_bf16 v[16:19], v[168:171], v[200:203], v[16:19]
	v_mfma_f32_16x16x32_bf16 v[8:11], v[176:179], v[200:203], v[8:11]
	v_mfma_f32_16x16x32_bf16 v[4:7], v[168:171], v[212:215], v[4:7]
	v_mfma_f32_16x16x32_bf16 v[0:3], v[176:179], v[212:215], v[0:3]
	s_setprio 0
	s_barrier
	s_add_i32 s53, s53, 2
	s_add_u32 s28, s28, 0x100
	s_addc_u32 s29, s29, 0
	s_add_u32 s51, s51, 0x100
	s_addc_u32 s52, s52, 0
	s_cmp_gt_u32 s53, 29
	s_cbranch_scc0 .LBB0_394
	s_and_b64 vcc, exec, s[6:7]
	v_readlane_b32 s52, v255, 9
	v_readlane_b32 s53, v255, 10
	s_cbranch_vccz .LBB0_397
	s_barrier

; #define PG8_STAGE(bufoff, gbase, voff) do { _Pragma("unroll") for (int _i = 0; _i < 2; ++_i) \
;         __builtin_amdgcn_global_load_lds((const unsigned*)((const char*)(gbase) + (voff)[_i]), (PG8_LAS unsigned*)(lds + (bufoff) + ldsw + _i * 8192), 16, 0, 0); } while (0)
; #define PG8_LDA(dst, b, h) do { _Pragma("unroll") for (int m = 0; m < 4; ++m) _Pragma("unroll") for (int k = 0; k < 2; ++k) dst[m][k] = *(const PG8_LAS bf16x8*)(lds + PG8_SA(b, h) + aoff + m * 2048 + k * 1024); } while (0)
; #define PG8_LDB(dst, b, h) do { _Pragma("unroll") for (int n = 0; n < 2; ++n) _Pragma("unroll") for (int k = 0; k < 2; ++k) dst[n][k] = *(const PG8_LAS bf16x8*)(lds + PG8_SB(b, h) + boff + n * 2048 + k * 1024); } while (0)
; #define PG8_MMA(ai, bj, At, Bt) do { __builtin_amdgcn_s_setprio(1); _Pragma("unroll") for (int m = 0; m < 4; ++m) _Pragma("unroll") for (int n = 0; n < 2; ++n) _Pragma("unroll") for (int k = 0; k < 2; ++k) \
;         acc[ai][bj][m][n] = __builtin_amdgcn_mfma_f32_16x16x32_bf16(Bt[n][k], At[m][k], acc[ai][bj][m][n], 0, 0, 0); __builtin_amdgcn_s_setprio(0); } while (0)
; #define PG8_WAIT_V(n) asm volatile("s_waitcnt vmcnt(" #n ")" ::: "memory")
; #define PG8_WAIT_L(n) asm volatile("s_waitcnt lgkmcnt(" #n ")" ::: "memory")
; #define PG8_BAR __builtin_amdgcn_s_barrier()
; template <class Epi, class Sched, bool ALIGN_EPI = false, bool SP2 = false>
; __device__ __forceinline__ void gemm_phase(PG8_LAS unsigned char* lds, const Gemm g, const Sched& S, const Epi& E, const int tid_in) {
;     ...
;             const char* a1 = cA + (size_t)(t + 1) * kstep;
;             const char* a2 = last ? nA : cA + (size_t)(t + 2) * kstep; const char* b2 = last ? nB : cB + (size_t)(t + 2) * kstep;
;             const char* a3 = a2 + kstep; const char* b3 = b2 + kstep;
;             if (last && has_next) S.a_ready(nxt);
;             if constexpr (SP2) {
;             PG8_LDB(B0, 0, 0); PG8_LDB(B1, 0, 1); PG8_SCHED; PG8_LDA(At, 0, 0); PG8_STAGE(PG8_SA(1, 1), a1 + hstep, voffA);
;             PG8_WAIT_V(8); PG8_WAIT_L(0); PG8_BAR; PG8_MMA(0, 0, At, B0); PG8_MMA(0, 1, At, B1); PG8_BAR; PG8_SCHED;
;             PG8_LDA(At, 0, 1); PG8_STAGE(PG8_SB(0, 0), b2, voffB); PG8_STAGE(PG8_SB(0, 1), b2 + hstep, voffB); PG8_STAGE(PG8_SA(0, 0), a2, voffA);
;             PG8_WAIT_V(8); PG8_WAIT_L(0); PG8_BAR; PG8_MMA(1, 0, At, B0); PG8_MMA(1, 1, At, B1); PG8_BAR; PG8_SCHED;
.LBB0_412:
	s_add_u32 s38, s34, 0xfff80080
	s_addc_u32 s39, s35, -1
	s_add_i32 s59, 0, 0x10000
	s_cmp_eq_u32 s58, 28
	s_cselect_b32 s43, s27, s39
	s_cselect_b32 s42, s54, s38
	s_cselect_b32 s39, s7, s57
	s_cselect_b32 s38, s55, s56
	s_add_i32 s62, 0, 0x14000
	v_add_u32_e32 v78, s59, v162
	v_add_u32_e32 v160, s62, v162
	ds_read_b128 v[66:69], v78
	ds_read_b128 v[70:73], v78 offset:1024
	ds_read_b128 v[74:77], v78 offset:2048
	ds_read_b128 v[78:81], v78 offset:3072
	ds_read_b128 v[166:169], v160
	ds_read_b128 v[170:173], v160 offset:1024
	ds_read_b128 v[174:177], v160 offset:2048
	ds_read_b128 v[178:181], v160 offset:3072
	s_add_i32 m0, s44, 0xc000
	ds_read_b128 v[182:185], v165
	ds_read_b128 v[186:189], v165 offset:1024
	ds_read_b128 v[190:193], v165 offset:2048
	ds_read_b128 v[194:197], v165 offset:3072
	ds_read_b128 v[198:201], v165 offset:4096
	ds_read_b128 v[202:205], v165 offset:5120
	ds_read_b128 v[208:211], v165 offset:6144
	ds_read_b128 v[212:215], v165 offset:7168
	global_load_lds_dwordx4 v156, s[34:35]
	s_add_i32 m0, s44, 0xe000
	s_nop 0
	global_load_lds_dwordx4 v158, s[34:35]
	s_waitcnt vmcnt(8)
	s_waitcnt lgkmcnt(0)
	s_barrier
	s_setprio 1
	s_waitcnt lgkmcnt(0)
	v_mfma_f32_16x16x32_bf16 v[142:145], v[66:69], v[182:185], v[142:145]
	v_mfma_f32_16x16x32_bf16 v[138:141], v[74:77], v[182:185], v[138:141]
	v_mfma_f32_16x16x32_bf16 v[126:129], v[66:69], v[190:193], v[126:129]
	v_mfma_f32_16x16x32_bf16 v[122:125], v[74:77], v[190:193], v[122:125]
	v_mfma_f32_16x16x32_bf16 v[110:113], v[66:69], v[198:201], v[110:113]
	v_mfma_f32_16x16x32_bf16 v[106:109], v[74:77], v[198:201], v[106:109]
	v_mfma_f32_16x16x32_bf16 v[94:97], v[66:69], v[208:211], v[94:97]
	v_mfma_f32_16x16x32_bf16 v[90:93], v[74:77], v[208:211], v[90:93]
	v_mfma_f32_16x16x32_bf16 v[142:145], v[70:73], v[186:189], v[142:145]
	v_mfma_f32_16x16x32_bf16 v[138:141], v[78:81], v[186:189], v[138:141]
	v_mfma_f32_16x16x32_bf16 v[126:129], v[70:73], v[194:197], v[126:129]
	v_mfma_f32_16x16x32_bf16 v[122:125], v[78:81], v[194:197], v[122:125]
	v_mfma_f32_16x16x32_bf16 v[110:113], v[70:73], v[202:205], v[110:113]
	v_mfma_f32_16x16x32_bf16 v[106:109], v[78:81], v[202:205], v[106:109]
	v_mfma_f32_16x16x32_bf16 v[94:97], v[70:73], v[212:215], v[94:97]
	v_mfma_f32_16x16x32_bf16 v[90:93], v[78:81], v[212:215], v[90:93]
	s_setprio 0
	s_setprio 1
	v_mfma_f32_16x16x32_bf16 v[134:137], v[166:169], v[182:185], v[134:137]
	v_mfma_f32_16x16x32_bf16 v[130:133], v[174:177], v[182:185], v[130:133]
	v_mfma_f32_16x16x32_bf16 v[118:121], v[166:169], v[190:193], v[118:121]
	v_mfma_f32_16x16x32_bf16 v[114:117], v[174:177], v[190:193], v[114:117]
	v_mfma_f32_16x16x32_bf16 v[102:105], v[166:169], v[198:201], v[102:105]
	v_mfma_f32_16x16x32_bf16 v[98:101], v[174:177], v[198:201], v[98:101]
	v_mfma_f32_16x16x32_bf16 v[86:89], v[166:169], v[208:211], v[86:89]
	v_mfma_f32_16x16x32_bf16 v[82:85], v[174:177], v[208:211], v[82:85]
	v_mfma_f32_16x16x32_bf16 v[134:137], v[170:173], v[186:189], v[134:137]
	v_mfma_f32_16x16x32_bf16 v[130:133], v[178:181], v[186:189], v[130:133]
	v_mfma_f32_16x16x32_bf16 v[118:121], v[170:173], v[194:197], v[118:121]
	v_mfma_f32_16x16x32_bf16 v[114:117], v[178:181], v[194:197], v[114:117]
	v_mfma_f32_16x16x32_bf16 v[102:105], v[170:173], v[202:205], v[102:105]
	v_mfma_f32_16x16x32_bf16 v[98:101], v[178:181], v[202:205], v[98:101]
	v_mfma_f32_16x16x32_bf16 v[86:89], v[170:173], v[212:215], v[86:89]
	v_mfma_f32_16x16x32_bf16 v[82:85], v[178:181], v[212:215], v[82:85]
	s_setprio 0
	s_barrier
	s_add_i32 s59, s59, s19
	s_add_u32 s98, s38, 0x80
	s_addc_u32 s99, s39, 0
	s_mov_b32 m0, s59
	ds_read_b128 v[182:185], v165 offset:16384
	ds_read_b128 v[186:189], v165 offset:17408
	ds_read_b128 v[190:193], v165 offset:18432
	ds_read_b128 v[194:197], v165 offset:19456
	ds_read_b128 v[198:201], v165 offset:20480
	ds_read_b128 v[202:205], v165 offset:21504
	ds_read_b128 v[208:211], v165 offset:22528
	ds_read_b128 v[212:215], v165 offset:23552
	global_load_lds_dwordx4 v148, s[38:39]
	s_add_i32 m0, s59, 0x2000
	s_add_u32 s60, s38, 0x80000
	s_addc_u32 s61, s39, 0
	s_add_i32 s59, s62, s19
	global_load_lds_dwordx4 v152, s[38:39]
	s_mov_b32 m0, s59
	s_add_u32 s100, s42, 0x80
	s_addc_u32 s101, s43, 0
	global_load_lds_dwordx4 v148, s[60:61]
	s_add_i32 m0, s59, 0x2000
	s_nop 0
	global_load_lds_dwordx4 v152, s[60:61]
	s_mov_b32 m0, s44
	s_nop 0
	global_load_lds_dwordx4 v146, s[42:43]
	s_mov_b32 m0, s45
	s_nop 0
	global_load_lds_dwordx4 v150, s[42:43]
	s_waitcnt vmcnt(8)
	s_waitcnt lgkmcnt(0)
	s_barrier
	s_setprio 1
	s_waitcnt lgkmcnt(0)
	v_mfma_f32_16x16x32_bf16 v[62:65], v[66:69], v[182:185], v[62:65]
	v_mfma_f32_16x16x32_bf16 v[58:61], v[74:77], v[182:185], v[58:61]
	v_mfma_f32_16x16x32_bf16 v[46:49], v[66:69], v[190:193], v[46:49]
	v_mfma_f32_16x16x32_bf16 v[42:45], v[74:77], v[190:193], v[42:45]
	v_mfma_f32_16x16x32_bf16 v[30:33], v[66:69], v[198:201], v[30:33]
	v_mfma_f32_16x16x32_bf16 v[26:29], v[74:77], v[198:201], v[26:29]
	v_mfma_f32_16x16x32_bf16 v[12:15], v[66:69], v[208:211], v[12:15]
	v_mfma_f32_16x16x32_bf16 v[8:11], v[74:77], v[208:211], v[8:11]
	v_mfma_f32_16x16x32_bf16 v[62:65], v[70:73], v[186:189], v[62:65]
	v_mfma_f32_16x16x32_bf16 v[58:61], v[78:81], v[186:189], v[58:61]
	v_mfma_f32_16x16x32_bf16 v[46:49], v[70:73], v[194:197], v[46:49]
	v_mfma_f32_16x16x32_bf16 v[42:45], v[78:81], v[194:197], v[42:45]
	v_mfma_f32_16x16x32_bf16 v[30:33], v[70:73], v[202:205], v[30:33]
	v_mfma_f32_16x16x32_bf16 v[26:29], v[78:81], v[202:205], v[26:29]
	v_mfma_f32_16x16x32_bf16 v[12:15], v[70:73], v[212:215], v[12:15]
	v_mfma_f32_16x16x32_bf16 v[8:11], v[78:81], v[212:215], v[8:11]
	s_setprio 0
	s_setprio 1
	v_mfma_f32_16x16x32_bf16 v[54:57], v[166:169], v[182:185], v[54:57]
	v_mfma_f32_16x16x32_bf16 v[50:53], v[174:177], v[182:185], v[50:53]
	v_mfma_f32_16x16x32_bf16 v[38:41], v[166:169], v[190:193], v[38:41]
	v_mfma_f32_16x16x32_bf16 v[34:37], v[174:177], v[190:193], v[34:37]
	v_mfma_f32_16x16x32_bf16 v[22:25], v[166:169], v[198:201], v[22:25]
	v_mfma_f32_16x16x32_bf16 v[16:19], v[174:177], v[198:201], v[16:19]
	v_mfma_f32_16x16x32_bf16 v[4:7], v[166:169], v[208:211], v[4:7]
	v_mfma_f32_16x16x32_bf16 v[0:3], v[174:177], v[208:211], v[0:3]
	v_mfma_f32_16x16x32_bf16 v[54:57], v[170:173], v[186:189], v[54:57]
	v_mfma_f32_16x16x32_bf16 v[50:53], v[178:181], v[186:189], v[50:53]
	v_mfma_f32_16x16x32_bf16 v[38:41], v[170:173], v[194:197], v[38:41]
	v_mfma_f32_16x16x32_bf16 v[34:37], v[178:181], v[194:197], v[34:37]
	v_mfma_f32_16x16x32_bf16 v[22:25], v[170:173], v[202:205], v[22:25]
	v_mfma_f32_16x16x32_bf16 v[16:19], v[178:181], v[202:205], v[16:19]
	v_mfma_f32_16x16x32_bf16 v[4:7], v[170:173], v[212:215], v[4:7]
	v_mfma_f32_16x16x32_bf16 v[0:3], v[178:181], v[212:215], v[0:3]
	s_setprio 0
	s_barrier
; #define PG8_STAGE(bufoff, gbase, voff) do { _Pragma("unroll") for (int _i = 0; _i < 2; ++_i) \
;         __builtin_amdgcn_global_load_lds((const unsigned*)((const char*)(gbase) + (voff)[_i]), (PG8_LAS unsigned*)(lds + (bufoff) + ldsw + _i * 8192), 16, 0, 0); } while (0)
; #define PG8_LDA(dst, b, h) do { _Pragma("unroll") for (int m = 0; m < 4; ++m) _Pragma("unroll") for (int k = 0; k < 2; ++k) dst[m][k] = *(const PG8_LAS bf16x8*)(lds + PG8_SA(b, h) + aoff + m * 2048 + k * 1024); } while (0)
; #define PG8_LDB(dst, b, h) do { _Pragma("unroll") for (int n = 0; n < 2; ++n) _Pragma("unroll") for (int k = 0; k < 2; ++k) dst[n][k] = *(const PG8_LAS bf16x8*)(lds + PG8_SB(b, h) + boff + n * 2048 + k * 1024); } while (0)
; #define PG8_MMA(ai, bj, At, Bt) do { __builtin_amdgcn_s_setprio(1); _Pragma("unroll") for (int m = 0; m < 4; ++m) _Pragma("unroll") for (int n = 0; n < 2; ++n) _Pragma("unroll") for (int k = 0; k < 2; ++k) \
;         acc[ai][bj][m][n] = __builtin_amdgcn_mfma_f32_16x16x32_bf16(Bt[n][k], At[m][k], acc[ai][bj][m][n], 0, 0, 0); __builtin_amdgcn_s_setprio(0); } while (0)
; #define PG8_WAIT_V(n) asm volatile("s_waitcnt vmcnt(" #n ")" ::: "memory")
; #define PG8_WAIT_L(n) asm volatile("s_waitcnt lgkmcnt(" #n ")" ::: "memory")
; #define PG8_BAR __builtin_amdgcn_s_barrier()
; #define PG8_SCHED __builtin_amdgcn_sched_barrier(0)
; template <class Epi, class Sched, bool ALIGN_EPI = false, bool SP2 = false>
; __device__ __forceinline__ void gemm_phase(PG8_LAS unsigned char* lds, const Gemm g, const Sched& S, const Epi& E, const int tid_in) {
;     ...
;             PG8_LDB(B0, 1, 0); PG8_LDB(B1, 1, 1); PG8_SCHED; PG8_LDA(At, 1, 0); PG8_STAGE(PG8_SA(0, 1), a2 + hstep, voffA);
;             PG8_WAIT_V(8); PG8_WAIT_L(0); PG8_BAR; PG8_MMA(0, 0, At, B0); PG8_MMA(0, 1, At, B1); PG8_BAR; PG8_SCHED;
;             PG8_LDA(At, 1, 1); PG8_STAGE(PG8_SB(1, 0), b3, voffB); PG8_STAGE(PG8_SB(1, 1), b3 + hstep, voffB); PG8_STAGE(PG8_SA(1, 0), a3, voffA);
;             PG8_WAIT_V(8); PG8_WAIT_L(0); PG8_BAR; PG8_MMA(1, 0, At, B0); PG8_MMA(1, 1, At, B1); PG8_BAR; PG8_SCHED;
	s_add_i32 s59, 0, 0x18000
	s_add_i32 s60, 0, 0x1c000
	v_add_u32_e32 v78, s59, v162
	v_add_u32_e32 v178, s60, v162
	ds_read_b128 v[66:69], v78
	ds_read_b128 v[70:73], v78 offset:1024
	ds_read_b128 v[74:77], v78 offset:2048
	ds_read_b128 v[78:81], v78 offset:3072
	ds_read_b128 v[166:169], v178
	ds_read_b128 v[170:173], v178 offset:1024
	ds_read_b128 v[174:177], v178 offset:2048
	ds_read_b128 v[178:181], v178 offset:3072
	s_add_u32 s42, s42, 0x80000
	s_addc_u32 s43, s43, 0
	s_mov_b32 m0, s46
	ds_read_b128 v[182:185], v165 offset:32768
	ds_read_b128 v[186:189], v165 offset:33792
	ds_read_b128 v[190:193], v165 offset:34816
	ds_read_b128 v[194:197], v165 offset:35840
	ds_read_b128 v[198:201], v165 offset:36864
	ds_read_b128 v[202:205], v165 offset:37888
	ds_read_b128 v[208:211], v165 offset:38912
	ds_read_b128 v[212:215], v165 offset:39936
	global_load_lds_dwordx4 v146, s[42:43]
	s_mov_b32 m0, s47
	s_nop 0
	global_load_lds_dwordx4 v150, s[42:43]
	s_waitcnt vmcnt(8)
	s_waitcnt lgkmcnt(0)
	s_barrier
	s_setprio 1
	s_waitcnt lgkmcnt(0)
	v_mfma_f32_16x16x32_bf16 v[142:145], v[66:69], v[182:185], v[142:145]
	v_mfma_f32_16x16x32_bf16 v[138:141], v[74:77], v[182:185], v[138:141]
	v_mfma_f32_16x16x32_bf16 v[126:129], v[66:69], v[190:193], v[126:129]
	v_mfma_f32_16x16x32_bf16 v[122:125], v[74:77], v[190:193], v[122:125]
	v_mfma_f32_16x16x32_bf16 v[110:113], v[66:69], v[198:201], v[110:113]
	v_mfma_f32_16x16x32_bf16 v[106:109], v[74:77], v[198:201], v[106:109]
	v_mfma_f32_16x16x32_bf16 v[94:97], v[66:69], v[208:211], v[94:97]
	v_mfma_f32_16x16x32_bf16 v[90:93], v[74:77], v[208:211], v[90:93]
	v_mfma_f32_16x16x32_bf16 v[142:145], v[70:73], v[186:189], v[142:145]
	v_mfma_f32_16x16x32_bf16 v[138:141], v[78:81], v[186:189], v[138:141]
	v_mfma_f32_16x16x32_bf16 v[126:129], v[70:73], v[194:197], v[126:129]
	v_mfma_f32_16x16x32_bf16 v[122:125], v[78:81], v[194:197], v[122:125]
	v_mfma_f32_16x16x32_bf16 v[110:113], v[70:73], v[202:205], v[110:113]
	v_mfma_f32_16x16x32_bf16 v[106:109], v[78:81], v[202:205], v[106:109]
	v_mfma_f32_16x16x32_bf16 v[94:97], v[70:73], v[212:215], v[94:97]
	v_mfma_f32_16x16x32_bf16 v[90:93], v[78:81], v[212:215], v[90:93]
	s_setprio 0
	s_setprio 1
	v_mfma_f32_16x16x32_bf16 v[134:137], v[166:169], v[182:185], v[134:137]
	v_mfma_f32_16x16x32_bf16 v[130:133], v[174:177], v[182:185], v[130:133]
	v_mfma_f32_16x16x32_bf16 v[118:121], v[166:169], v[190:193], v[118:121]
	v_mfma_f32_16x16x32_bf16 v[114:117], v[174:177], v[190:193], v[114:117]
	v_mfma_f32_16x16x32_bf16 v[102:105], v[166:169], v[198:201], v[102:105]
	v_mfma_f32_16x16x32_bf16 v[98:101], v[174:177], v[198:201], v[98:101]
	v_mfma_f32_16x16x32_bf16 v[86:89], v[166:169], v[208:211], v[86:89]
	v_mfma_f32_16x16x32_bf16 v[82:85], v[174:177], v[208:211], v[82:85]
	v_mfma_f32_16x16x32_bf16 v[134:137], v[170:173], v[186:189], v[134:137]
	v_mfma_f32_16x16x32_bf16 v[130:133], v[178:181], v[186:189], v[130:133]
	v_mfma_f32_16x16x32_bf16 v[118:121], v[170:173], v[194:197], v[118:121]
	v_mfma_f32_16x16x32_bf16 v[114:117], v[178:181], v[194:197], v[114:117]
	v_mfma_f32_16x16x32_bf16 v[102:105], v[170:173], v[202:205], v[102:105]
	v_mfma_f32_16x16x32_bf16 v[98:101], v[178:181], v[202:205], v[98:101]
	v_mfma_f32_16x16x32_bf16 v[86:89], v[170:173], v[212:215], v[86:89]
	v_mfma_f32_16x16x32_bf16 v[82:85], v[178:181], v[212:215], v[82:85]
	s_setprio 0
	s_barrier
	s_add_i32 s42, s59, s19
	s_mov_b32 m0, s42
	ds_read_b128 v[182:185], v165 offset:49152
	ds_read_b128 v[186:189], v165 offset:50176
	ds_read_b128 v[190:193], v165 offset:51200
	ds_read_b128 v[194:197], v165 offset:52224
	ds_read_b128 v[198:201], v165 offset:53248
	ds_read_b128 v[202:205], v165 offset:54272
	ds_read_b128 v[208:211], v165 offset:55296
	ds_read_b128 v[212:215], v165 offset:56320
	global_load_lds_dwordx4 v148, s[98:99]
	s_add_i32 m0, s42, 0x2000
	s_add_u32 s38, s38, 0x80080
	s_addc_u32 s39, s39, 0
	s_add_i32 s42, s60, s19
	global_load_lds_dwordx4 v152, s[98:99]
	s_mov_b32 m0, s42
	s_nop 0
	global_load_lds_dwordx4 v148, s[38:39]
	s_add_i32 m0, s42, 0x2000
	s_nop 0
	global_load_lds_dwordx4 v152, s[38:39]
	s_mov_b32 m0, s48
	s_nop 0
	global_load_lds_dwordx4 v146, s[100:101]
	s_mov_b32 m0, s49
	s_nop 0
	global_load_lds_dwordx4 v150, s[100:101]
	s_waitcnt vmcnt(8)
	s_waitcnt lgkmcnt(0)
	s_barrier
	s_setprio 1
	s_waitcnt lgkmcnt(0)
	v_mfma_f32_16x16x32_bf16 v[62:65], v[66:69], v[182:185], v[62:65]
	v_mfma_f32_16x16x32_bf16 v[58:61], v[74:77], v[182:185], v[58:61]
	v_mfma_f32_16x16x32_bf16 v[46:49], v[66:69], v[190:193], v[46:49]
	v_mfma_f32_16x16x32_bf16 v[42:45], v[74:77], v[190:193], v[42:45]
	v_mfma_f32_16x16x32_bf16 v[30:33], v[66:69], v[198:201], v[30:33]
	v_mfma_f32_16x16x32_bf16 v[26:29], v[74:77], v[198:201], v[26:29]
	v_mfma_f32_16x16x32_bf16 v[12:15], v[66:69], v[208:211], v[12:15]
	v_mfma_f32_16x16x32_bf16 v[8:11], v[74:77], v[208:211], v[8:11]
	v_mfma_f32_16x16x32_bf16 v[62:65], v[70:73], v[186:189], v[62:65]
	v_mfma_f32_16x16x32_bf16 v[58:61], v[78:81], v[186:189], v[58:61]
	v_mfma_f32_16x16x32_bf16 v[46:49], v[70:73], v[194:197], v[46:49]
	v_mfma_f32_16x16x32_bf16 v[42:45], v[78:81], v[194:197], v[42:45]
	v_mfma_f32_16x16x32_bf16 v[30:33], v[70:73], v[202:205], v[30:33]
	v_mfma_f32_16x16x32_bf16 v[26:29], v[78:81], v[202:205], v[26:29]
	v_mfma_f32_16x16x32_bf16 v[12:15], v[70:73], v[212:215], v[12:15]
	v_mfma_f32_16x16x32_bf16 v[8:11], v[78:81], v[212:215], v[8:11]
	s_setprio 0
	s_setprio 1
	v_mfma_f32_16x16x32_bf16 v[54:57], v[166:169], v[182:185], v[54:57]
	v_mfma_f32_16x16x32_bf16 v[50:53], v[174:177], v[182:185], v[50:53]
	v_mfma_f32_16x16x32_bf16 v[38:41], v[166:169], v[190:193], v[38:41]
	v_mfma_f32_16x16x32_bf16 v[34:37], v[174:177], v[190:193], v[34:37]
	v_mfma_f32_16x16x32_bf16 v[22:25], v[166:169], v[198:201], v[22:25]
	v_mfma_f32_16x16x32_bf16 v[16:19], v[174:177], v[198:201], v[16:19]
	v_mfma_f32_16x16x32_bf16 v[4:7], v[166:169], v[208:211], v[4:7]
	v_mfma_f32_16x16x32_bf16 v[0:3], v[174:177], v[208:211], v[0:3]
	v_mfma_f32_16x16x32_bf16 v[54:57], v[170:173], v[186:189], v[54:57]
	v_mfma_f32_16x16x32_bf16 v[50:53], v[178:181], v[186:189], v[50:53]
	v_mfma_f32_16x16x32_bf16 v[38:41], v[170:173], v[194:197], v[38:41]
	v_mfma_f32_16x16x32_bf16 v[34:37], v[178:181], v[194:197], v[34:37]
	v_mfma_f32_16x16x32_bf16 v[22:25], v[170:173], v[202:205], v[22:25]
	v_mfma_f32_16x16x32_bf16 v[16:19], v[178:181], v[202:205], v[16:19]
	v_mfma_f32_16x16x32_bf16 v[4:7], v[170:173], v[212:215], v[4:7]
	v_mfma_f32_16x16x32_bf16 v[0:3], v[178:181], v[212:215], v[0:3]
	s_setprio 0
	s_barrier
	s_add_i32 s58, s58, 2
	s_add_u32 s34, s34, 0x100
	s_addc_u32 s35, s35, 0
	s_add_u32 s56, s56, 0x100
	s_addc_u32 s57, s57, 0
	s_cmp_gt_u32 s58, 29
	s_cbranch_scc0 .LBB0_412
	s_and_b64 vcc, exec, s[2:3]
	s_cbranch_vccz .LBB0_415
	s_barrier

; #define PG8_STAGE(bufoff, gbase, voff) do { _Pragma("unroll") for (int _i = 0; _i < 2; ++_i) \
;         __builtin_amdgcn_global_load_lds((const unsigned*)((const char*)(gbase) + (voff)[_i]), (PG8_LAS unsigned*)(lds + (bufoff) + ldsw + _i * 8192), 16, 0, 0); } while (0)
; #define PG8_LDA(dst, b, h) do { _Pragma("unroll") for (int m = 0; m < 4; ++m) _Pragma("unroll") for (int k = 0; k < 2; ++k) dst[m][k] = *(const PG8_LAS bf16x8*)(lds + PG8_SA(b, h) + aoff + m * 2048 + k * 1024); } while (0)
; #define PG8_LDB(dst, b, h) do { _Pragma("unroll") for (int n = 0; n < 2; ++n) _Pragma("unroll") for (int k = 0; k < 2; ++k) dst[n][k] = *(const PG8_LAS bf16x8*)(lds + PG8_SB(b, h) + boff + n * 2048 + k * 1024); } while (0)
; #define PG8_MMA(ai, bj, At, Bt) do { __builtin_amdgcn_s_setprio(1); _Pragma("unroll") for (int m = 0; m < 4; ++m) _Pragma("unroll") for (int n = 0; n < 2; ++n) _Pragma("unroll") for (int k = 0; k < 2; ++k) \
;         acc[ai][bj][m][n] = __builtin_amdgcn_mfma_f32_16x16x32_bf16(Bt[n][k], At[m][k], acc[ai][bj][m][n], 0, 0, 0); __builtin_amdgcn_s_setprio(0); } while (0)
; #define PG8_WAIT_V(n) asm volatile("s_waitcnt vmcnt(" #n ")" ::: "memory")
; #define PG8_WAIT_L(n) asm volatile("s_waitcnt lgkmcnt(" #n ")" ::: "memory")
; #define PG8_BAR __builtin_amdgcn_s_barrier()
; #define PG8_SCHED __builtin_amdgcn_sched_barrier(0)
; template <class Epi, class Sched, bool ALIGN_EPI = false, bool SP2 = false>
; __device__ __forceinline__ void gemm_phase(PG8_LAS unsigned char* lds, const Gemm g, const Sched& S, const Epi& E, const int tid_in) {
;     ...
;             const char* a1 = cA + (size_t)(t + 1) * kstep;
;             const char* a2 = last ? nA : cA + (size_t)(t + 2) * kstep; const char* b2 = last ? nB : cB + (size_t)(t + 2) * kstep;
;             const char* a3 = a2 + kstep; const char* b3 = b2 + kstep;
;             if (last && has_next) S.a_ready(nxt);
;             if constexpr (SP2) {
;             PG8_LDB(B0, 0, 0); PG8_LDB(B1, 0, 1); PG8_SCHED; PG8_LDA(At, 0, 0); PG8_STAGE(PG8_SA(1, 1), a1 + hstep, voffA);
;             PG8_WAIT_V(8); PG8_WAIT_L(0); PG8_BAR; PG8_MMA(0, 0, At, B0); PG8_MMA(0, 1, At, B1); PG8_BAR; PG8_SCHED;
;             PG8_LDA(At, 0, 1); PG8_STAGE(PG8_SB(0, 0), b2, voffB); PG8_STAGE(PG8_SB(0, 1), b2 + hstep, voffB); PG8_STAGE(PG8_SA(0, 0), a2, voffA);
.LBB0_960:
	s_add_u32 s36, s30, s34
	s_addc_u32 s37, s31, s35
	s_add_u32 s36, s36, 0x100
	s_addc_u32 s37, s37, 0
	s_add_u32 s61, s58, s34
	s_addc_u32 s62, s59, s35
	s_add_i32 s63, 0, 0x10000
	s_cmpk_eq_i32 s34, 0xb00
	s_cselect_b32 s41, s27, s37
	s_cselect_b32 s40, s26, s36
	s_cselect_b32 s37, s29, s62
	s_cselect_b32 s36, s28, s61
	s_add_i32 s61, 0, 0x14000
	v_add_u32_e32 v142, s63, v230
	v_add_u32_e32 v158, s61, v230
	ds_read_b128 v[130:133], v142
	ds_read_b128 v[134:137], v142 offset:1024
	ds_read_b128 v[138:141], v142 offset:2048
	ds_read_b128 v[142:145], v142 offset:3072
	ds_read_b128 v[146:149], v158
	ds_read_b128 v[150:153], v158 offset:1024
	ds_read_b128 v[154:157], v158 offset:2048
	ds_read_b128 v[158:161], v158 offset:3072
	v_lshl_add_u64 v[214:215], v[182:183], 0, s[34:35]
	s_add_i32 m0, s42, 0xc000
	ds_read_b128 v[162:165], v233
	ds_read_b128 v[166:169], v233 offset:1024
	ds_read_b128 v[170:173], v233 offset:2048
	ds_read_b128 v[174:177], v233 offset:3072
	ds_read_b128 v[178:181], v233 offset:4096
	ds_read_b128 v[186:189], v233 offset:5120
	ds_read_b128 v[190:193], v233 offset:6144
	ds_read_b128 v[210:213], v233 offset:7168
	global_load_lds_dwordx4 v[214:215], off
	v_lshl_add_u64 v[214:215], v[184:185], 0, s[34:35]
	s_add_i32 m0, s42, 0xe000
	s_nop 0
	global_load_lds_dwordx4 v[214:215], off
	s_waitcnt vmcnt(8)
	s_waitcnt lgkmcnt(0)
	s_barrier
	s_setprio 1
	s_waitcnt lgkmcnt(0)
	v_mfma_f32_16x16x32_bf16 v[126:129], v[130:133], v[162:165], v[126:129]
	v_mfma_f32_16x16x32_bf16 v[122:125], v[138:141], v[162:165], v[122:125]
	v_mfma_f32_16x16x32_bf16 v[110:113], v[130:133], v[170:173], v[110:113]
	v_mfma_f32_16x16x32_bf16 v[106:109], v[138:141], v[170:173], v[106:109]
	v_mfma_f32_16x16x32_bf16 v[102:105], v[130:133], v[178:181], v[102:105]
	v_mfma_f32_16x16x32_bf16 v[94:97], v[138:141], v[178:181], v[94:97]
	v_mfma_f32_16x16x32_bf16 v[86:89], v[130:133], v[190:193], v[86:89]
	v_mfma_f32_16x16x32_bf16 v[78:81], v[138:141], v[190:193], v[78:81]
	v_mfma_f32_16x16x32_bf16 v[126:129], v[134:137], v[166:169], v[126:129]
	v_mfma_f32_16x16x32_bf16 v[122:125], v[142:145], v[166:169], v[122:125]
	v_mfma_f32_16x16x32_bf16 v[110:113], v[134:137], v[174:177], v[110:113]
	v_mfma_f32_16x16x32_bf16 v[106:109], v[142:145], v[174:177], v[106:109]
	v_mfma_f32_16x16x32_bf16 v[102:105], v[134:137], v[186:189], v[102:105]
	v_mfma_f32_16x16x32_bf16 v[94:97], v[142:145], v[186:189], v[94:97]
	v_mfma_f32_16x16x32_bf16 v[86:89], v[134:137], v[210:213], v[86:89]
	v_mfma_f32_16x16x32_bf16 v[78:81], v[142:145], v[210:213], v[78:81]
	s_setprio 0
	s_setprio 1
	v_mfma_f32_16x16x32_bf16 v[118:121], v[146:149], v[162:165], v[118:121]
	v_mfma_f32_16x16x32_bf16 v[114:117], v[154:157], v[162:165], v[114:117]
	v_mfma_f32_16x16x32_bf16 v[98:101], v[146:149], v[170:173], v[98:101]
	v_mfma_f32_16x16x32_bf16 v[90:93], v[154:157], v[170:173], v[90:93]
	v_mfma_f32_16x16x32_bf16 v[82:85], v[146:149], v[178:181], v[82:85]
	v_mfma_f32_16x16x32_bf16 v[74:77], v[154:157], v[178:181], v[74:77]
	v_mfma_f32_16x16x32_bf16 v[70:73], v[146:149], v[190:193], v[70:73]
	v_mfma_f32_16x16x32_bf16 v[66:69], v[154:157], v[190:193], v[66:69]
	v_mfma_f32_16x16x32_bf16 v[118:121], v[150:153], v[166:169], v[118:121]
	v_mfma_f32_16x16x32_bf16 v[114:117], v[158:161], v[166:169], v[114:117]
	v_mfma_f32_16x16x32_bf16 v[98:101], v[150:153], v[174:177], v[98:101]
	v_mfma_f32_16x16x32_bf16 v[90:93], v[158:161], v[174:177], v[90:93]
	v_mfma_f32_16x16x32_bf16 v[82:85], v[150:153], v[186:189], v[82:85]
	v_mfma_f32_16x16x32_bf16 v[74:77], v[158:161], v[186:189], v[74:77]
	v_mfma_f32_16x16x32_bf16 v[70:73], v[150:153], v[210:213], v[70:73]
	v_mfma_f32_16x16x32_bf16 v[66:69], v[158:161], v[210:213], v[66:69]
	s_setprio 0
	s_barrier
	s_add_i32 s62, s63, s19
	s_add_u32 s98, s36, 0x80
	s_addc_u32 s99, s37, 0
	s_mov_b32 m0, s62
	ds_read_b128 v[162:165], v233 offset:16384
	ds_read_b128 v[166:169], v233 offset:17408
	ds_read_b128 v[170:173], v233 offset:18432
	ds_read_b128 v[174:177], v233 offset:19456
	ds_read_b128 v[178:181], v233 offset:20480
	ds_read_b128 v[186:189], v233 offset:21504
	ds_read_b128 v[190:193], v233 offset:22528
	ds_read_b128 v[210:213], v233 offset:23552
	global_load_lds_dwordx4 v198, s[36:37]
	s_add_i32 m0, s62, 0x2000
	s_add_u32 s62, s36, 0x60000
	s_addc_u32 s63, s37, 0
	s_add_i32 s61, s61, s19
	global_load_lds_dwordx4 v194, s[36:37]
	s_mov_b32 m0, s61
	s_add_u32 s100, s40, 0x80
	s_addc_u32 s101, s41, 0
	global_load_lds_dwordx4 v198, s[62:63]
	s_add_i32 m0, s61, 0x2000
	s_nop 0
	global_load_lds_dwordx4 v194, s[62:63]
	s_mov_b32 m0, s42
	s_nop 0
	global_load_lds_dwordx4 v200, s[40:41]
	s_mov_b32 m0, s43
	s_nop 0
	global_load_lds_dwordx4 v196, s[40:41]
	s_waitcnt vmcnt(8)
	s_waitcnt lgkmcnt(0)
	s_barrier
; #define PG8_STAGE(bufoff, gbase, voff) do { _Pragma("unroll") for (int _i = 0; _i < 2; ++_i) \
;         __builtin_amdgcn_global_load_lds((const unsigned*)((const char*)(gbase) + (voff)[_i]), (PG8_LAS unsigned*)(lds + (bufoff) + ldsw + _i * 8192), 16, 0, 0); } while (0)
; #define PG8_LDA(dst, b, h) do { _Pragma("unroll") for (int m = 0; m < 4; ++m) _Pragma("unroll") for (int k = 0; k < 2; ++k) dst[m][k] = *(const PG8_LAS bf16x8*)(lds + PG8_SA(b, h) + aoff + m * 2048 + k * 1024); } while (0)
; #define PG8_LDB(dst, b, h) do { _Pragma("unroll") for (int n = 0; n < 2; ++n) _Pragma("unroll") for (int k = 0; k < 2; ++k) dst[n][k] = *(const PG8_LAS bf16x8*)(lds + PG8_SB(b, h) + boff + n * 2048 + k * 1024); } while (0)
; #define PG8_MMA(ai, bj, At, Bt) do { __builtin_amdgcn_s_setprio(1); _Pragma("unroll") for (int m = 0; m < 4; ++m) _Pragma("unroll") for (int n = 0; n < 2; ++n) _Pragma("unroll") for (int k = 0; k < 2; ++k) \
;         acc[ai][bj][m][n] = __builtin_amdgcn_mfma_f32_16x16x32_bf16(Bt[n][k], At[m][k], acc[ai][bj][m][n], 0, 0, 0); __builtin_amdgcn_s_setprio(0); } while (0)
; #define PG8_WAIT_V(n) asm volatile("s_waitcnt vmcnt(" #n ")" ::: "memory")
; #define PG8_WAIT_L(n) asm volatile("s_waitcnt lgkmcnt(" #n ")" ::: "memory")
; #define PG8_BAR __builtin_amdgcn_s_barrier()
; #define PG8_SCHED __builtin_amdgcn_sched_barrier(0)
; template <class Epi, class Sched, bool ALIGN_EPI = false, bool SP2 = false>
; __device__ __forceinline__ void gemm_phase(PG8_LAS unsigned char* lds, const Gemm g, const Sched& S, const Epi& E, const int tid_in) {
;     ...
;             PG8_WAIT_V(8); PG8_WAIT_L(0); PG8_BAR; PG8_MMA(1, 0, At, B0); PG8_MMA(1, 1, At, B1); PG8_BAR; PG8_SCHED;
;             PG8_LDB(B0, 1, 0); PG8_LDB(B1, 1, 1); PG8_SCHED; PG8_LDA(At, 1, 0); PG8_STAGE(PG8_SA(0, 1), a2 + hstep, voffA);
;             PG8_WAIT_V(8); PG8_WAIT_L(0); PG8_BAR; PG8_MMA(0, 0, At, B0); PG8_MMA(0, 1, At, B1); PG8_BAR; PG8_SCHED;
	s_setprio 1
	s_waitcnt lgkmcnt(0)
	v_mfma_f32_16x16x32_bf16 v[62:65], v[130:133], v[162:165], v[62:65]
	v_mfma_f32_16x16x32_bf16 v[58:61], v[138:141], v[162:165], v[58:61]
	v_mfma_f32_16x16x32_bf16 v[54:57], v[130:133], v[170:173], v[54:57]
	v_mfma_f32_16x16x32_bf16 v[46:49], v[138:141], v[170:173], v[46:49]
	v_mfma_f32_16x16x32_bf16 v[38:41], v[130:133], v[178:181], v[38:41]
	v_mfma_f32_16x16x32_bf16 v[30:33], v[138:141], v[178:181], v[30:33]
	v_mfma_f32_16x16x32_bf16 v[22:25], v[130:133], v[190:193], v[22:25]
	v_mfma_f32_16x16x32_bf16 v[12:15], v[138:141], v[190:193], v[12:15]
	v_mfma_f32_16x16x32_bf16 v[62:65], v[134:137], v[166:169], v[62:65]
	v_mfma_f32_16x16x32_bf16 v[58:61], v[142:145], v[166:169], v[58:61]
	v_mfma_f32_16x16x32_bf16 v[54:57], v[134:137], v[174:177], v[54:57]
	v_mfma_f32_16x16x32_bf16 v[46:49], v[142:145], v[174:177], v[46:49]
	v_mfma_f32_16x16x32_bf16 v[38:41], v[134:137], v[186:189], v[38:41]
	v_mfma_f32_16x16x32_bf16 v[30:33], v[142:145], v[186:189], v[30:33]
	v_mfma_f32_16x16x32_bf16 v[22:25], v[134:137], v[210:213], v[22:25]
	v_mfma_f32_16x16x32_bf16 v[12:15], v[142:145], v[210:213], v[12:15]
	s_setprio 0
	s_setprio 1
	v_mfma_f32_16x16x32_bf16 v[50:53], v[146:149], v[162:165], v[50:53]
	v_mfma_f32_16x16x32_bf16 v[42:45], v[154:157], v[162:165], v[42:45]
	v_mfma_f32_16x16x32_bf16 v[34:37], v[146:149], v[170:173], v[34:37]
	v_mfma_f32_16x16x32_bf16 v[26:29], v[154:157], v[170:173], v[26:29]
	v_mfma_f32_16x16x32_bf16 v[16:19], v[146:149], v[178:181], v[16:19]
	v_mfma_f32_16x16x32_bf16 v[8:11], v[154:157], v[178:181], v[8:11]
	v_mfma_f32_16x16x32_bf16 v[4:7], v[146:149], v[190:193], v[4:7]
	v_mfma_f32_16x16x32_bf16 v[0:3], v[154:157], v[190:193], v[0:3]
	v_mfma_f32_16x16x32_bf16 v[50:53], v[150:153], v[166:169], v[50:53]
	v_mfma_f32_16x16x32_bf16 v[42:45], v[158:161], v[166:169], v[42:45]
	v_mfma_f32_16x16x32_bf16 v[34:37], v[150:153], v[174:177], v[34:37]
	v_mfma_f32_16x16x32_bf16 v[26:29], v[158:161], v[174:177], v[26:29]
	v_mfma_f32_16x16x32_bf16 v[16:19], v[150:153], v[186:189], v[16:19]
	v_mfma_f32_16x16x32_bf16 v[8:11], v[158:161], v[186:189], v[8:11]
	v_mfma_f32_16x16x32_bf16 v[4:7], v[150:153], v[210:213], v[4:7]
	v_mfma_f32_16x16x32_bf16 v[0:3], v[158:161], v[210:213], v[0:3]
	s_setprio 0
	s_barrier
	s_add_i32 s61, 0, 0x18000
	s_add_i32 s62, 0, 0x1c000
	v_add_u32_e32 v142, s61, v230
	v_add_u32_e32 v158, s62, v230
	ds_read_b128 v[130:133], v142
	ds_read_b128 v[134:137], v142 offset:1024
	ds_read_b128 v[138:141], v142 offset:2048
	ds_read_b128 v[142:145], v142 offset:3072
	ds_read_b128 v[146:149], v158
	ds_read_b128 v[150:153], v158 offset:1024
	ds_read_b128 v[154:157], v158 offset:2048
	ds_read_b128 v[158:161], v158 offset:3072
	s_add_u32 s40, s40, 0x60000
	s_addc_u32 s41, s41, 0
	s_mov_b32 m0, s44
	ds_read_b128 v[162:165], v233 offset:32768
	ds_read_b128 v[166:169], v233 offset:33792
	ds_read_b128 v[170:173], v233 offset:34816
	ds_read_b128 v[174:177], v233 offset:35840
	ds_read_b128 v[178:181], v233 offset:36864
	ds_read_b128 v[186:189], v233 offset:37888
	ds_read_b128 v[190:193], v233 offset:38912
	ds_read_b128 v[210:213], v233 offset:39936
	global_load_lds_dwordx4 v200, s[40:41]
	s_mov_b32 m0, s45
	s_nop 0
	global_load_lds_dwordx4 v196, s[40:41]
	s_waitcnt vmcnt(8)
	s_waitcnt lgkmcnt(0)
	s_barrier
	s_setprio 1
	s_waitcnt lgkmcnt(0)
	v_mfma_f32_16x16x32_bf16 v[126:129], v[130:133], v[162:165], v[126:129]
	v_mfma_f32_16x16x32_bf16 v[122:125], v[138:141], v[162:165], v[122:125]
	v_mfma_f32_16x16x32_bf16 v[110:113], v[130:133], v[170:173], v[110:113]
	v_mfma_f32_16x16x32_bf16 v[106:109], v[138:141], v[170:173], v[106:109]
	v_mfma_f32_16x16x32_bf16 v[102:105], v[130:133], v[178:181], v[102:105]
	v_mfma_f32_16x16x32_bf16 v[94:97], v[138:141], v[178:181], v[94:97]
	v_mfma_f32_16x16x32_bf16 v[86:89], v[130:133], v[190:193], v[86:89]
	v_mfma_f32_16x16x32_bf16 v[78:81], v[138:141], v[190:193], v[78:81]
	v_mfma_f32_16x16x32_bf16 v[126:129], v[134:137], v[166:169], v[126:129]
	v_mfma_f32_16x16x32_bf16 v[122:125], v[142:145], v[166:169], v[122:125]
	v_mfma_f32_16x16x32_bf16 v[110:113], v[134:137], v[174:177], v[110:113]
	v_mfma_f32_16x16x32_bf16 v[106:109], v[142:145], v[174:177], v[106:109]
	v_mfma_f32_16x16x32_bf16 v[102:105], v[134:137], v[186:189], v[102:105]
	v_mfma_f32_16x16x32_bf16 v[94:97], v[142:145], v[186:189], v[94:97]
	v_mfma_f32_16x16x32_bf16 v[86:89], v[134:137], v[210:213], v[86:89]
	v_mfma_f32_16x16x32_bf16 v[78:81], v[142:145], v[210:213], v[78:81]
	s_setprio 0
	s_setprio 1
	v_mfma_f32_16x16x32_bf16 v[118:121], v[146:149], v[162:165], v[118:121]
	v_mfma_f32_16x16x32_bf16 v[114:117], v[154:157], v[162:165], v[114:117]
	v_mfma_f32_16x16x32_bf16 v[98:101], v[146:149], v[170:173], v[98:101]
	v_mfma_f32_16x16x32_bf16 v[90:93], v[154:157], v[170:173], v[90:93]
	v_mfma_f32_16x16x32_bf16 v[82:85], v[146:149], v[178:181], v[82:85]
	v_mfma_f32_16x16x32_bf16 v[74:77], v[154:157], v[178:181], v[74:77]
	v_mfma_f32_16x16x32_bf16 v[70:73], v[146:149], v[190:193], v[70:73]
	v_mfma_f32_16x16x32_bf16 v[66:69], v[154:157], v[190:193], v[66:69]
	v_mfma_f32_16x16x32_bf16 v[118:121], v[150:153], v[166:169], v[118:121]
	v_mfma_f32_16x16x32_bf16 v[114:117], v[158:161], v[166:169], v[114:117]
	v_mfma_f32_16x16x32_bf16 v[98:101], v[150:153], v[174:177], v[98:101]
	v_mfma_f32_16x16x32_bf16 v[90:93], v[158:161], v[174:177], v[90:93]
	v_mfma_f32_16x16x32_bf16 v[82:85], v[150:153], v[186:189], v[82:85]
	v_mfma_f32_16x16x32_bf16 v[74:77], v[158:161], v[186:189], v[74:77]
	v_mfma_f32_16x16x32_bf16 v[70:73], v[150:153], v[210:213], v[70:73]
	v_mfma_f32_16x16x32_bf16 v[66:69], v[158:161], v[210:213], v[66:69]
	s_setprio 0
	s_barrier
; #define PG8_STAGE(bufoff, gbase, voff) do { _Pragma("unroll") for (int _i = 0; _i < 2; ++_i) \
;         __builtin_amdgcn_global_load_lds((const unsigned*)((const char*)(gbase) + (voff)[_i]), (PG8_LAS unsigned*)(lds + (bufoff) + ldsw + _i * 8192), 16, 0, 0); } while (0)
; #define PG8_LDA(dst, b, h) do { _Pragma("unroll") for (int m = 0; m < 4; ++m) _Pragma("unroll") for (int k = 0; k < 2; ++k) dst[m][k] = *(const PG8_LAS bf16x8*)(lds + PG8_SA(b, h) + aoff + m * 2048 + k * 1024); } while (0)
; #define PG8_MMA(ai, bj, At, Bt) do { __builtin_amdgcn_s_setprio(1); _Pragma("unroll") for (int m = 0; m < 4; ++m) _Pragma("unroll") for (int n = 0; n < 2; ++n) _Pragma("unroll") for (int k = 0; k < 2; ++k) \
;         acc[ai][bj][m][n] = __builtin_amdgcn_mfma_f32_16x16x32_bf16(Bt[n][k], At[m][k], acc[ai][bj][m][n], 0, 0, 0); __builtin_amdgcn_s_setprio(0); } while (0)
; #define PG8_WAIT_V(n) asm volatile("s_waitcnt vmcnt(" #n ")" ::: "memory")
; #define PG8_WAIT_L(n) asm volatile("s_waitcnt lgkmcnt(" #n ")" ::: "memory")
; #define PG8_BAR __builtin_amdgcn_s_barrier()
; #define PG8_SCHED __builtin_amdgcn_sched_barrier(0)
; template <class Epi, class Sched, bool ALIGN_EPI = false, bool SP2 = false>
; __device__ __forceinline__ void gemm_phase(PG8_LAS unsigned char* lds, const Gemm g, const Sched& S, const Epi& E, const int tid_in) {
;     ...
;             PG8_LDA(At, 1, 1); PG8_STAGE(PG8_SB(1, 0), b3, voffB); PG8_STAGE(PG8_SB(1, 1), b3 + hstep, voffB); PG8_STAGE(PG8_SA(1, 0), a3, voffA);
;             PG8_WAIT_V(8); PG8_WAIT_L(0); PG8_BAR; PG8_MMA(1, 0, At, B0); PG8_MMA(1, 1, At, B1); PG8_BAR; PG8_SCHED;
	s_add_i32 s40, s61, s19
	s_mov_b32 m0, s40
	ds_read_b128 v[162:165], v233 offset:49152
	ds_read_b128 v[166:169], v233 offset:50176
	ds_read_b128 v[170:173], v233 offset:51200
	ds_read_b128 v[174:177], v233 offset:52224
	ds_read_b128 v[178:181], v233 offset:53248
	ds_read_b128 v[186:189], v233 offset:54272
	ds_read_b128 v[190:193], v233 offset:55296
	ds_read_b128 v[210:213], v233 offset:56320
	global_load_lds_dwordx4 v198, s[98:99]
	s_add_i32 m0, s40, 0x2000
	s_add_u32 s36, s36, 0x60080
	s_addc_u32 s37, s37, 0
	s_add_i32 s40, s62, s19
	global_load_lds_dwordx4 v194, s[98:99]
	s_mov_b32 m0, s40
	s_nop 0
	global_load_lds_dwordx4 v198, s[36:37]
	s_add_i32 m0, s40, 0x2000
	s_nop 0
	global_load_lds_dwordx4 v194, s[36:37]
	s_mov_b32 m0, s47
	s_nop 0
	global_load_lds_dwordx4 v200, s[100:101]
	s_mov_b32 m0, s48
	s_nop 0
	global_load_lds_dwordx4 v196, s[100:101]
	s_waitcnt vmcnt(8)
	s_waitcnt lgkmcnt(0)
	s_barrier
	s_setprio 1
	s_waitcnt lgkmcnt(0)
	v_mfma_f32_16x16x32_bf16 v[62:65], v[130:133], v[162:165], v[62:65]
	v_mfma_f32_16x16x32_bf16 v[58:61], v[138:141], v[162:165], v[58:61]
	v_mfma_f32_16x16x32_bf16 v[54:57], v[130:133], v[170:173], v[54:57]
	v_mfma_f32_16x16x32_bf16 v[46:49], v[138:141], v[170:173], v[46:49]
	v_mfma_f32_16x16x32_bf16 v[38:41], v[130:133], v[178:181], v[38:41]
	v_mfma_f32_16x16x32_bf16 v[30:33], v[138:141], v[178:181], v[30:33]
	v_mfma_f32_16x16x32_bf16 v[22:25], v[130:133], v[190:193], v[22:25]
	v_mfma_f32_16x16x32_bf16 v[12:15], v[138:141], v[190:193], v[12:15]
	v_mfma_f32_16x16x32_bf16 v[62:65], v[134:137], v[166:169], v[62:65]
	v_mfma_f32_16x16x32_bf16 v[58:61], v[142:145], v[166:169], v[58:61]
	v_mfma_f32_16x16x32_bf16 v[54:57], v[134:137], v[174:177], v[54:57]
	v_mfma_f32_16x16x32_bf16 v[46:49], v[142:145], v[174:177], v[46:49]
	v_mfma_f32_16x16x32_bf16 v[38:41], v[134:137], v[186:189], v[38:41]
	v_mfma_f32_16x16x32_bf16 v[30:33], v[142:145], v[186:189], v[30:33]
	v_mfma_f32_16x16x32_bf16 v[22:25], v[134:137], v[210:213], v[22:25]
	v_mfma_f32_16x16x32_bf16 v[12:15], v[142:145], v[210:213], v[12:15]
	s_setprio 0
	s_setprio 1
	v_mfma_f32_16x16x32_bf16 v[50:53], v[146:149], v[162:165], v[50:53]
	v_mfma_f32_16x16x32_bf16 v[42:45], v[154:157], v[162:165], v[42:45]
	v_mfma_f32_16x16x32_bf16 v[34:37], v[146:149], v[170:173], v[34:37]
	v_mfma_f32_16x16x32_bf16 v[26:29], v[154:157], v[170:173], v[26:29]
	v_mfma_f32_16x16x32_bf16 v[16:19], v[146:149], v[178:181], v[16:19]
	v_mfma_f32_16x16x32_bf16 v[8:11], v[154:157], v[178:181], v[8:11]
	v_mfma_f32_16x16x32_bf16 v[4:7], v[146:149], v[190:193], v[4:7]
	v_mfma_f32_16x16x32_bf16 v[0:3], v[154:157], v[190:193], v[0:3]
	v_mfma_f32_16x16x32_bf16 v[50:53], v[150:153], v[166:169], v[50:53]
	v_mfma_f32_16x16x32_bf16 v[42:45], v[158:161], v[166:169], v[42:45]
	v_mfma_f32_16x16x32_bf16 v[34:37], v[150:153], v[174:177], v[34:37]
	v_mfma_f32_16x16x32_bf16 v[26:29], v[158:161], v[174:177], v[26:29]
	v_mfma_f32_16x16x32_bf16 v[16:19], v[150:153], v[186:189], v[16:19]
	v_mfma_f32_16x16x32_bf16 v[8:11], v[158:161], v[186:189], v[8:11]
	v_mfma_f32_16x16x32_bf16 v[4:7], v[150:153], v[210:213], v[4:7]
	v_mfma_f32_16x16x32_bf16 v[0:3], v[158:161], v[210:213], v[0:3]
	s_setprio 0
	s_barrier
	s_add_i32 s60, s60, 2
	s_add_u32 s34, s34, 0x100
	s_addc_u32 s35, s35, 0
	s_cmp_gt_u32 s60, 21
	s_cbranch_scc1 .LBB0_963

; #define PG8_STAGE(bufoff, gbase, voff) do { _Pragma("unroll") for (int _i = 0; _i < 2; ++_i) \
;         __builtin_amdgcn_global_load_lds((const unsigned*)((const char*)(gbase) + (voff)[_i]), (PG8_LAS unsigned*)(lds + (bufoff) + ldsw + _i * 8192), 16, 0, 0); } while (0)
; #define PG8_LDA(dst, b, h) do { _Pragma("unroll") for (int m = 0; m < 4; ++m) _Pragma("unroll") for (int k = 0; k < 2; ++k) dst[m][k] = *(const PG8_LAS bf16x8*)(lds + PG8_SA(b, h) + aoff + m * 2048 + k * 1024); } while (0)
; #define PG8_LDB(dst, b, h) do { _Pragma("unroll") for (int n = 0; n < 2; ++n) _Pragma("unroll") for (int k = 0; k < 2; ++k) dst[n][k] = *(const PG8_LAS bf16x8*)(lds + PG8_SB(b, h) + boff + n * 2048 + k * 1024); } while (0)
; #define PG8_MMA(ai, bj, At, Bt) do { __builtin_amdgcn_s_setprio(1); _Pragma("unroll") for (int m = 0; m < 4; ++m) _Pragma("unroll") for (int n = 0; n < 2; ++n) _Pragma("unroll") for (int k = 0; k < 2; ++k) \
;         acc[ai][bj][m][n] = __builtin_amdgcn_mfma_f32_16x16x32_bf16(Bt[n][k], At[m][k], acc[ai][bj][m][n], 0, 0, 0); __builtin_amdgcn_s_setprio(0); } while (0)
; #define PG8_WAIT_V(n) asm volatile("s_waitcnt vmcnt(" #n ")" ::: "memory")
; #define PG8_WAIT_L(n) asm volatile("s_waitcnt lgkmcnt(" #n ")" ::: "memory")
; #define PG8_BAR __builtin_amdgcn_s_barrier()
; #define PG8_SCHED __builtin_amdgcn_sched_barrier(0)
; template <class Epi, class Sched, bool ALIGN_EPI = false, bool SP2 = false>
; __device__ __forceinline__ void gemm_phase(PG8_LAS unsigned char* lds, const Gemm g, const Sched& S, const Epi& E, const int tid_in) {
;     ...
;             const char* a1 = cA + (size_t)(t + 1) * kstep;
;             const char* a2 = last ? nA : cA + (size_t)(t + 2) * kstep; const char* b2 = last ? nB : cB + (size_t)(t + 2) * kstep;
;             const char* a3 = a2 + kstep; const char* b3 = b2 + kstep;
;             if (last && has_next) S.a_ready(nxt);
;             if constexpr (SP2) {
;             PG8_LDB(B0, 0, 0); PG8_LDB(B1, 0, 1); PG8_SCHED; PG8_LDA(At, 0, 0); PG8_STAGE(PG8_SA(1, 1), a1 + hstep, voffA);
;             PG8_WAIT_V(8); PG8_WAIT_L(0); PG8_BAR; PG8_MMA(0, 0, At, B0); PG8_MMA(0, 1, At, B1); PG8_BAR; PG8_SCHED;
;             PG8_LDA(At, 0, 1); PG8_STAGE(PG8_SB(0, 0), b2, voffB); PG8_STAGE(PG8_SB(0, 1), b2 + hstep, voffB); PG8_STAGE(PG8_SA(0, 0), a2, voffA);
.LBB0_1037:
	s_add_u32 s30, s28, 0xfff80080
	s_addc_u32 s31, s29, -1
	s_add_i32 s46, 0, 0x10000
	s_cmp_eq_u32 vcc_lo, 28
	s_cselect_b32 s35, s38, s31
	s_cselect_b32 s34, s39, s30
	s_cselect_b32 s31, s40, s92
	s_cselect_b32 s30, s41, s57
	s_add_i32 vcc_hi, 0, 0x14000
	v_add_u32_e32 v142, s46, v21
	v_add_u32_e32 v158, vcc_hi, v21
	ds_read_b128 v[130:133], v142
	ds_read_b128 v[134:137], v142 offset:1024
	ds_read_b128 v[138:141], v142 offset:2048
	ds_read_b128 v[142:145], v142 offset:3072
	ds_read_b128 v[146:149], v158
	ds_read_b128 v[150:153], v158 offset:1024
	ds_read_b128 v[154:157], v158 offset:2048
	ds_read_b128 v[158:161], v158 offset:3072
	s_add_i32 m0, s64, 0xc000
	ds_read_b128 v[162:165], v208
	ds_read_b128 v[166:169], v208 offset:1024
	ds_read_b128 v[170:173], v208 offset:2048
	ds_read_b128 v[174:177], v208 offset:3072
	ds_read_b128 v[178:181], v208 offset:4096
	ds_read_b128 v[182:185], v208 offset:5120
	ds_read_b128 v[186:189], v208 offset:6144
	ds_read_b128 v[190:193], v208 offset:7168
	global_load_lds_dwordx4 v218, s[28:29]
	s_add_i32 m0, s64, 0xe000
	s_nop 0
	global_load_lds_dwordx4 v220, s[28:29]
	s_waitcnt vmcnt(8)
	s_waitcnt lgkmcnt(0)
	s_barrier
	s_setprio 1
	s_waitcnt lgkmcnt(0)
	v_mfma_f32_16x16x32_bf16 v[126:129], v[130:133], v[162:165], v[126:129]
	v_mfma_f32_16x16x32_bf16 v[122:125], v[138:141], v[162:165], v[122:125]
	v_mfma_f32_16x16x32_bf16 v[110:113], v[130:133], v[170:173], v[110:113]
	v_mfma_f32_16x16x32_bf16 v[106:109], v[138:141], v[170:173], v[106:109]
	v_mfma_f32_16x16x32_bf16 v[94:97], v[130:133], v[178:181], v[94:97]
	v_mfma_f32_16x16x32_bf16 v[90:93], v[138:141], v[178:181], v[90:93]
	v_mfma_f32_16x16x32_bf16 v[78:81], v[130:133], v[186:189], v[78:81]
	v_mfma_f32_16x16x32_bf16 v[74:77], v[138:141], v[186:189], v[74:77]
	v_mfma_f32_16x16x32_bf16 v[126:129], v[134:137], v[166:169], v[126:129]
	v_mfma_f32_16x16x32_bf16 v[122:125], v[142:145], v[166:169], v[122:125]
	v_mfma_f32_16x16x32_bf16 v[110:113], v[134:137], v[174:177], v[110:113]
	v_mfma_f32_16x16x32_bf16 v[106:109], v[142:145], v[174:177], v[106:109]
	v_mfma_f32_16x16x32_bf16 v[94:97], v[134:137], v[182:185], v[94:97]
	v_mfma_f32_16x16x32_bf16 v[90:93], v[142:145], v[182:185], v[90:93]
	v_mfma_f32_16x16x32_bf16 v[78:81], v[134:137], v[190:193], v[78:81]
	v_mfma_f32_16x16x32_bf16 v[74:77], v[142:145], v[190:193], v[74:77]
	s_setprio 0
	s_setprio 1
	v_mfma_f32_16x16x32_bf16 v[118:121], v[146:149], v[162:165], v[118:121]
	v_mfma_f32_16x16x32_bf16 v[114:117], v[154:157], v[162:165], v[114:117]
	v_mfma_f32_16x16x32_bf16 v[102:105], v[146:149], v[170:173], v[102:105]
	v_mfma_f32_16x16x32_bf16 v[98:101], v[154:157], v[170:173], v[98:101]
	v_mfma_f32_16x16x32_bf16 v[86:89], v[146:149], v[178:181], v[86:89]
	v_mfma_f32_16x16x32_bf16 v[82:85], v[154:157], v[178:181], v[82:85]
	v_mfma_f32_16x16x32_bf16 v[70:73], v[146:149], v[186:189], v[70:73]
	v_mfma_f32_16x16x32_bf16 v[66:69], v[154:157], v[186:189], v[66:69]
	v_mfma_f32_16x16x32_bf16 v[118:121], v[150:153], v[166:169], v[118:121]
	v_mfma_f32_16x16x32_bf16 v[114:117], v[158:161], v[166:169], v[114:117]
	v_mfma_f32_16x16x32_bf16 v[102:105], v[150:153], v[174:177], v[102:105]
	v_mfma_f32_16x16x32_bf16 v[98:101], v[158:161], v[174:177], v[98:101]
	v_mfma_f32_16x16x32_bf16 v[86:89], v[150:153], v[182:185], v[86:89]
	v_mfma_f32_16x16x32_bf16 v[82:85], v[158:161], v[182:185], v[82:85]
	v_mfma_f32_16x16x32_bf16 v[70:73], v[150:153], v[190:193], v[70:73]
	v_mfma_f32_16x16x32_bf16 v[66:69], v[158:161], v[190:193], v[66:69]
	s_setprio 0
	s_barrier
	s_add_i32 s46, s46, s8
	s_add_u32 s98, s30, 0x80
	s_addc_u32 s99, s31, 0
	s_mov_b32 m0, s46
	ds_read_b128 v[162:165], v208 offset:16384
	ds_read_b128 v[166:169], v208 offset:17408
	ds_read_b128 v[170:173], v208 offset:18432
	ds_read_b128 v[174:177], v208 offset:19456
	ds_read_b128 v[178:181], v208 offset:20480
	ds_read_b128 v[182:185], v208 offset:21504
	ds_read_b128 v[186:189], v208 offset:22528
	ds_read_b128 v[190:193], v208 offset:23552
	global_load_lds_dwordx4 v204, s[30:31]
	s_add_i32 m0, s46, 0x2000
	s_add_u32 s46, s30, 0x80000
	s_addc_u32 s47, s31, 0
	s_add_i32 vcc_hi, vcc_hi, s8
	global_load_lds_dwordx4 v216, s[30:31]
	s_mov_b32 m0, vcc_hi
	s_add_u32 s100, s34, 0x80
	s_addc_u32 s101, s35, 0
	global_load_lds_dwordx4 v204, s[46:47]
	s_add_i32 m0, vcc_hi, 0x2000
	s_nop 0
	global_load_lds_dwordx4 v216, s[46:47]
	s_mov_b32 m0, s64
	s_nop 0
	global_load_lds_dwordx4 v202, s[34:35]
	s_mov_b32 m0, s65
	s_nop 0
	global_load_lds_dwordx4 v214, s[34:35]
	s_waitcnt vmcnt(8)
	s_waitcnt lgkmcnt(0)
	s_barrier
; #define PG8_STAGE(bufoff, gbase, voff) do { _Pragma("unroll") for (int _i = 0; _i < 2; ++_i) \
;         __builtin_amdgcn_global_load_lds((const unsigned*)((const char*)(gbase) + (voff)[_i]), (PG8_LAS unsigned*)(lds + (bufoff) + ldsw + _i * 8192), 16, 0, 0); } while (0)
; #define PG8_LDA(dst, b, h) do { _Pragma("unroll") for (int m = 0; m < 4; ++m) _Pragma("unroll") for (int k = 0; k < 2; ++k) dst[m][k] = *(const PG8_LAS bf16x8*)(lds + PG8_SA(b, h) + aoff + m * 2048 + k * 1024); } while (0)
; #define PG8_LDB(dst, b, h) do { _Pragma("unroll") for (int n = 0; n < 2; ++n) _Pragma("unroll") for (int k = 0; k < 2; ++k) dst[n][k] = *(const PG8_LAS bf16x8*)(lds + PG8_SB(b, h) + boff + n * 2048 + k * 1024); } while (0)
; #define PG8_MMA(ai, bj, At, Bt) do { __builtin_amdgcn_s_setprio(1); _Pragma("unroll") for (int m = 0; m < 4; ++m) _Pragma("unroll") for (int n = 0; n < 2; ++n) _Pragma("unroll") for (int k = 0; k < 2; ++k) \
;         acc[ai][bj][m][n] = __builtin_amdgcn_mfma_f32_16x16x32_bf16(Bt[n][k], At[m][k], acc[ai][bj][m][n], 0, 0, 0); __builtin_amdgcn_s_setprio(0); } while (0)
; #define PG8_WAIT_V(n) asm volatile("s_waitcnt vmcnt(" #n ")" ::: "memory")
; #define PG8_WAIT_L(n) asm volatile("s_waitcnt lgkmcnt(" #n ")" ::: "memory")
; #define PG8_BAR __builtin_amdgcn_s_barrier()
; #define PG8_SCHED __builtin_amdgcn_sched_barrier(0)
; template <class Epi, class Sched, bool ALIGN_EPI = false, bool SP2 = false>
; __device__ __forceinline__ void gemm_phase(PG8_LAS unsigned char* lds, const Gemm g, const Sched& S, const Epi& E, const int tid_in) {
;     ...
;             PG8_WAIT_V(8); PG8_WAIT_L(0); PG8_BAR; PG8_MMA(1, 0, At, B0); PG8_MMA(1, 1, At, B1); PG8_BAR; PG8_SCHED;
;             PG8_LDB(B0, 1, 0); PG8_LDB(B1, 1, 1); PG8_SCHED; PG8_LDA(At, 1, 0); PG8_STAGE(PG8_SA(0, 1), a2 + hstep, voffA);
;             PG8_WAIT_V(8); PG8_WAIT_L(0); PG8_BAR; PG8_MMA(0, 0, At, B0); PG8_MMA(0, 1, At, B1); PG8_BAR; PG8_SCHED;
	s_setprio 1
	s_waitcnt lgkmcnt(0)
	v_mfma_f32_16x16x32_bf16 v[62:65], v[130:133], v[162:165], v[62:65]
	v_mfma_f32_16x16x32_bf16 v[58:61], v[138:141], v[162:165], v[58:61]
	v_mfma_f32_16x16x32_bf16 v[46:49], v[130:133], v[170:173], v[46:49]
	v_mfma_f32_16x16x32_bf16 v[42:45], v[138:141], v[170:173], v[42:45]
	v_mfma_f32_16x16x32_bf16 v[30:33], v[130:133], v[178:181], v[30:33]
	v_mfma_f32_16x16x32_bf16 v[26:29], v[138:141], v[178:181], v[26:29]
	v_mfma_f32_16x16x32_bf16 v[12:15], v[130:133], v[186:189], v[12:15]
	v_mfma_f32_16x16x32_bf16 v[8:11], v[138:141], v[186:189], v[8:11]
	v_mfma_f32_16x16x32_bf16 v[62:65], v[134:137], v[166:169], v[62:65]
	v_mfma_f32_16x16x32_bf16 v[58:61], v[142:145], v[166:169], v[58:61]
	v_mfma_f32_16x16x32_bf16 v[46:49], v[134:137], v[174:177], v[46:49]
	v_mfma_f32_16x16x32_bf16 v[42:45], v[142:145], v[174:177], v[42:45]
	v_mfma_f32_16x16x32_bf16 v[30:33], v[134:137], v[182:185], v[30:33]
	v_mfma_f32_16x16x32_bf16 v[26:29], v[142:145], v[182:185], v[26:29]
	v_mfma_f32_16x16x32_bf16 v[12:15], v[134:137], v[190:193], v[12:15]
	v_mfma_f32_16x16x32_bf16 v[8:11], v[142:145], v[190:193], v[8:11]
	s_setprio 0
	s_setprio 1
	v_mfma_f32_16x16x32_bf16 v[54:57], v[146:149], v[162:165], v[54:57]
	v_mfma_f32_16x16x32_bf16 v[50:53], v[154:157], v[162:165], v[50:53]
	v_mfma_f32_16x16x32_bf16 v[38:41], v[146:149], v[170:173], v[38:41]
	v_mfma_f32_16x16x32_bf16 v[34:37], v[154:157], v[170:173], v[34:37]
	v_mfma_f32_16x16x32_bf16 v[22:25], v[146:149], v[178:181], v[22:25]
	v_mfma_f32_16x16x32_bf16 v[16:19], v[154:157], v[178:181], v[16:19]
	v_mfma_f32_16x16x32_bf16 v[4:7], v[146:149], v[186:189], v[4:7]
	v_mfma_f32_16x16x32_bf16 v[0:3], v[154:157], v[186:189], v[0:3]
	v_mfma_f32_16x16x32_bf16 v[54:57], v[150:153], v[166:169], v[54:57]
	v_mfma_f32_16x16x32_bf16 v[50:53], v[158:161], v[166:169], v[50:53]
	v_mfma_f32_16x16x32_bf16 v[38:41], v[150:153], v[174:177], v[38:41]
	v_mfma_f32_16x16x32_bf16 v[34:37], v[158:161], v[174:177], v[34:37]
	v_mfma_f32_16x16x32_bf16 v[22:25], v[150:153], v[182:185], v[22:25]
	v_mfma_f32_16x16x32_bf16 v[16:19], v[158:161], v[182:185], v[16:19]
	v_mfma_f32_16x16x32_bf16 v[4:7], v[150:153], v[190:193], v[4:7]
	v_mfma_f32_16x16x32_bf16 v[0:3], v[158:161], v[190:193], v[0:3]
	s_setprio 0
	s_barrier
	s_add_i32 s46, 0, 0x18000
	s_add_i32 s47, 0, 0x1c000
	v_add_u32_e32 v142, s46, v21
	v_add_u32_e32 v158, s47, v21
	ds_read_b128 v[130:133], v142
	ds_read_b128 v[134:137], v142 offset:1024
	ds_read_b128 v[138:141], v142 offset:2048
	ds_read_b128 v[142:145], v142 offset:3072
	ds_read_b128 v[146:149], v158
	ds_read_b128 v[150:153], v158 offset:1024
	ds_read_b128 v[154:157], v158 offset:2048
	ds_read_b128 v[158:161], v158 offset:3072
	s_add_u32 s34, s34, 0x80000
	s_addc_u32 s35, s35, 0
	s_mov_b32 m0, s66
	ds_read_b128 v[162:165], v208 offset:32768
	ds_read_b128 v[166:169], v208 offset:33792
	ds_read_b128 v[170:173], v208 offset:34816
	ds_read_b128 v[174:177], v208 offset:35840
	ds_read_b128 v[178:181], v208 offset:36864
	ds_read_b128 v[182:185], v208 offset:37888
	ds_read_b128 v[186:189], v208 offset:38912
	ds_read_b128 v[190:193], v208 offset:39936
	global_load_lds_dwordx4 v202, s[34:35]
	s_mov_b32 m0, s67
	s_nop 0
	global_load_lds_dwordx4 v214, s[34:35]
	s_waitcnt vmcnt(8)
	s_waitcnt lgkmcnt(0)
	s_barrier
	s_setprio 1
	s_waitcnt lgkmcnt(0)
	v_mfma_f32_16x16x32_bf16 v[126:129], v[130:133], v[162:165], v[126:129]
	v_mfma_f32_16x16x32_bf16 v[122:125], v[138:141], v[162:165], v[122:125]
	v_mfma_f32_16x16x32_bf16 v[110:113], v[130:133], v[170:173], v[110:113]
	v_mfma_f32_16x16x32_bf16 v[106:109], v[138:141], v[170:173], v[106:109]
	v_mfma_f32_16x16x32_bf16 v[94:97], v[130:133], v[178:181], v[94:97]
	v_mfma_f32_16x16x32_bf16 v[90:93], v[138:141], v[178:181], v[90:93]
	v_mfma_f32_16x16x32_bf16 v[78:81], v[130:133], v[186:189], v[78:81]
	v_mfma_f32_16x16x32_bf16 v[74:77], v[138:141], v[186:189], v[74:77]
	v_mfma_f32_16x16x32_bf16 v[126:129], v[134:137], v[166:169], v[126:129]
	v_mfma_f32_16x16x32_bf16 v[122:125], v[142:145], v[166:169], v[122:125]
	v_mfma_f32_16x16x32_bf16 v[110:113], v[134:137], v[174:177], v[110:113]
	v_mfma_f32_16x16x32_bf16 v[106:109], v[142:145], v[174:177], v[106:109]
	v_mfma_f32_16x16x32_bf16 v[94:97], v[134:137], v[182:185], v[94:97]
	v_mfma_f32_16x16x32_bf16 v[90:93], v[142:145], v[182:185], v[90:93]
	v_mfma_f32_16x16x32_bf16 v[78:81], v[134:137], v[190:193], v[78:81]
	v_mfma_f32_16x16x32_bf16 v[74:77], v[142:145], v[190:193], v[74:77]
	s_setprio 0
	s_setprio 1
	v_mfma_f32_16x16x32_bf16 v[118:121], v[146:149], v[162:165], v[118:121]
	v_mfma_f32_16x16x32_bf16 v[114:117], v[154:157], v[162:165], v[114:117]
	v_mfma_f32_16x16x32_bf16 v[102:105], v[146:149], v[170:173], v[102:105]
	v_mfma_f32_16x16x32_bf16 v[98:101], v[154:157], v[170:173], v[98:101]
	v_mfma_f32_16x16x32_bf16 v[86:89], v[146:149], v[178:181], v[86:89]
	v_mfma_f32_16x16x32_bf16 v[82:85], v[154:157], v[178:181], v[82:85]
	v_mfma_f32_16x16x32_bf16 v[70:73], v[146:149], v[186:189], v[70:73]
	v_mfma_f32_16x16x32_bf16 v[66:69], v[154:157], v[186:189], v[66:69]
	v_mfma_f32_16x16x32_bf16 v[118:121], v[150:153], v[166:169], v[118:121]
	v_mfma_f32_16x16x32_bf16 v[114:117], v[158:161], v[166:169], v[114:117]
	v_mfma_f32_16x16x32_bf16 v[102:105], v[150:153], v[174:177], v[102:105]
	v_mfma_f32_16x16x32_bf16 v[98:101], v[158:161], v[174:177], v[98:101]
	v_mfma_f32_16x16x32_bf16 v[86:89], v[150:153], v[182:185], v[86:89]
	v_mfma_f32_16x16x32_bf16 v[82:85], v[158:161], v[182:185], v[82:85]
	v_mfma_f32_16x16x32_bf16 v[70:73], v[150:153], v[190:193], v[70:73]
	v_mfma_f32_16x16x32_bf16 v[66:69], v[158:161], v[190:193], v[66:69]
	s_setprio 0
	s_barrier
; #define PG8_STAGE(bufoff, gbase, voff) do { _Pragma("unroll") for (int _i = 0; _i < 2; ++_i) \
;         __builtin_amdgcn_global_load_lds((const unsigned*)((const char*)(gbase) + (voff)[_i]), (PG8_LAS unsigned*)(lds + (bufoff) + ldsw + _i * 8192), 16, 0, 0); } while (0)
; #define PG8_LDA(dst, b, h) do { _Pragma("unroll") for (int m = 0; m < 4; ++m) _Pragma("unroll") for (int k = 0; k < 2; ++k) dst[m][k] = *(const PG8_LAS bf16x8*)(lds + PG8_SA(b, h) + aoff + m * 2048 + k * 1024); } while (0)
; #define PG8_MMA(ai, bj, At, Bt) do { __builtin_amdgcn_s_setprio(1); _Pragma("unroll") for (int m = 0; m < 4; ++m) _Pragma("unroll") for (int n = 0; n < 2; ++n) _Pragma("unroll") for (int k = 0; k < 2; ++k) \
;         acc[ai][bj][m][n] = __builtin_amdgcn_mfma_f32_16x16x32_bf16(Bt[n][k], At[m][k], acc[ai][bj][m][n], 0, 0, 0); __builtin_amdgcn_s_setprio(0); } while (0)
; #define PG8_WAIT_V(n) asm volatile("s_waitcnt vmcnt(" #n ")" ::: "memory")
; #define PG8_WAIT_L(n) asm volatile("s_waitcnt lgkmcnt(" #n ")" ::: "memory")
; #define PG8_BAR __builtin_amdgcn_s_barrier()
; #define PG8_SCHED __builtin_amdgcn_sched_barrier(0)
; template <class Epi, class Sched, bool ALIGN_EPI = false, bool SP2 = false>
; __device__ __forceinline__ void gemm_phase(PG8_LAS unsigned char* lds, const Gemm g, const Sched& S, const Epi& E, const int tid_in) {
;     ...
;             PG8_LDA(At, 1, 1); PG8_STAGE(PG8_SB(1, 0), b3, voffB); PG8_STAGE(PG8_SB(1, 1), b3 + hstep, voffB); PG8_STAGE(PG8_SA(1, 0), a3, voffA);
;             PG8_WAIT_V(8); PG8_WAIT_L(0); PG8_BAR; PG8_MMA(1, 0, At, B0); PG8_MMA(1, 1, At, B1); PG8_BAR; PG8_SCHED;
	s_add_i32 s34, s46, s8
	s_mov_b32 m0, s34
	ds_read_b128 v[162:165], v208 offset:49152
	ds_read_b128 v[166:169], v208 offset:50176
	ds_read_b128 v[170:173], v208 offset:51200
	ds_read_b128 v[174:177], v208 offset:52224
	ds_read_b128 v[178:181], v208 offset:53248
	ds_read_b128 v[182:185], v208 offset:54272
	ds_read_b128 v[186:189], v208 offset:55296
	ds_read_b128 v[190:193], v208 offset:56320
	global_load_lds_dwordx4 v204, s[98:99]
	s_add_i32 m0, s34, 0x2000
	s_add_u32 s30, s30, 0x80080
	s_addc_u32 s31, s31, 0
	s_add_i32 s34, s47, s8
	global_load_lds_dwordx4 v216, s[98:99]
	s_mov_b32 m0, s34
	s_nop 0
	global_load_lds_dwordx4 v204, s[30:31]
	s_add_i32 m0, s34, 0x2000
	s_nop 0
	global_load_lds_dwordx4 v216, s[30:31]
	s_mov_b32 m0, s75
	s_nop 0
	global_load_lds_dwordx4 v202, s[100:101]
	s_mov_b32 m0, s76
	s_nop 0
	global_load_lds_dwordx4 v214, s[100:101]
	s_waitcnt vmcnt(8)
	s_waitcnt lgkmcnt(0)
	s_barrier
	s_setprio 1
	s_waitcnt lgkmcnt(0)
	v_mfma_f32_16x16x32_bf16 v[62:65], v[130:133], v[162:165], v[62:65]
	v_mfma_f32_16x16x32_bf16 v[58:61], v[138:141], v[162:165], v[58:61]
	v_mfma_f32_16x16x32_bf16 v[46:49], v[130:133], v[170:173], v[46:49]
	v_mfma_f32_16x16x32_bf16 v[42:45], v[138:141], v[170:173], v[42:45]
	v_mfma_f32_16x16x32_bf16 v[30:33], v[130:133], v[178:181], v[30:33]
	v_mfma_f32_16x16x32_bf16 v[26:29], v[138:141], v[178:181], v[26:29]
	v_mfma_f32_16x16x32_bf16 v[12:15], v[130:133], v[186:189], v[12:15]
	v_mfma_f32_16x16x32_bf16 v[8:11], v[138:141], v[186:189], v[8:11]
	v_mfma_f32_16x16x32_bf16 v[62:65], v[134:137], v[166:169], v[62:65]
	v_mfma_f32_16x16x32_bf16 v[58:61], v[142:145], v[166:169], v[58:61]
	v_mfma_f32_16x16x32_bf16 v[46:49], v[134:137], v[174:177], v[46:49]
	v_mfma_f32_16x16x32_bf16 v[42:45], v[142:145], v[174:177], v[42:45]
	v_mfma_f32_16x16x32_bf16 v[30:33], v[134:137], v[182:185], v[30:33]
	v_mfma_f32_16x16x32_bf16 v[26:29], v[142:145], v[182:185], v[26:29]
	v_mfma_f32_16x16x32_bf16 v[12:15], v[134:137], v[190:193], v[12:15]
	v_mfma_f32_16x16x32_bf16 v[8:11], v[142:145], v[190:193], v[8:11]
	s_setprio 0
	s_setprio 1
	v_mfma_f32_16x16x32_bf16 v[54:57], v[146:149], v[162:165], v[54:57]
	v_mfma_f32_16x16x32_bf16 v[50:53], v[154:157], v[162:165], v[50:53]
	v_mfma_f32_16x16x32_bf16 v[38:41], v[146:149], v[170:173], v[38:41]
	v_mfma_f32_16x16x32_bf16 v[34:37], v[154:157], v[170:173], v[34:37]
	v_mfma_f32_16x16x32_bf16 v[22:25], v[146:149], v[178:181], v[22:25]
	v_mfma_f32_16x16x32_bf16 v[16:19], v[154:157], v[178:181], v[16:19]
	v_mfma_f32_16x16x32_bf16 v[4:7], v[146:149], v[186:189], v[4:7]
	v_mfma_f32_16x16x32_bf16 v[0:3], v[154:157], v[186:189], v[0:3]
	v_mfma_f32_16x16x32_bf16 v[54:57], v[150:153], v[166:169], v[54:57]
	v_mfma_f32_16x16x32_bf16 v[50:53], v[158:161], v[166:169], v[50:53]
	v_mfma_f32_16x16x32_bf16 v[38:41], v[150:153], v[174:177], v[38:41]
	v_mfma_f32_16x16x32_bf16 v[34:37], v[158:161], v[174:177], v[34:37]
	v_mfma_f32_16x16x32_bf16 v[22:25], v[150:153], v[182:185], v[22:25]
	v_mfma_f32_16x16x32_bf16 v[16:19], v[158:161], v[182:185], v[16:19]
	v_mfma_f32_16x16x32_bf16 v[4:7], v[150:153], v[190:193], v[4:7]
	v_mfma_f32_16x16x32_bf16 v[0:3], v[158:161], v[190:193], v[0:3]
	s_setprio 0
	s_barrier
	s_add_i32 vcc_lo, vcc_lo, 2
	s_add_u32 s28, s28, 0x100
	s_addc_u32 s29, s29, 0
	s_add_u32 s57, s57, 0x100
	s_addc_u32 s92, s92, 0
	s_cmp_gt_u32 vcc_lo, 29
	s_cbranch_scc0 .LBB0_1037
	s_and_b64 vcc, exec, s[48:49]
	s_cbranch_vccz .LBB0_1040
	s_barrier

; #define PG8_STAGE(bufoff, gbase, voff) do { _Pragma("unroll") for (int _i = 0; _i < 2; ++_i) \
;         __builtin_amdgcn_global_load_lds((const unsigned*)((const char*)(gbase) + (voff)[_i]), (PG8_LAS unsigned*)(lds + (bufoff) + ldsw + _i * 8192), 16, 0, 0); } while (0)
; #define PG8_LDA(dst, b, h) do { _Pragma("unroll") for (int m = 0; m < 4; ++m) _Pragma("unroll") for (int k = 0; k < 2; ++k) dst[m][k] = *(const PG8_LAS bf16x8*)(lds + PG8_SA(b, h) + aoff + m * 2048 + k * 1024); } while (0)
; #define PG8_LDB(dst, b, h) do { _Pragma("unroll") for (int n = 0; n < 2; ++n) _Pragma("unroll") for (int k = 0; k < 2; ++k) dst[n][k] = *(const PG8_LAS bf16x8*)(lds + PG8_SB(b, h) + boff + n * 2048 + k * 1024); } while (0)
; #define PG8_MMA(ai, bj, At, Bt) do { __builtin_amdgcn_s_setprio(1); _Pragma("unroll") for (int m = 0; m < 4; ++m) _Pragma("unroll") for (int n = 0; n < 2; ++n) _Pragma("unroll") for (int k = 0; k < 2; ++k) \
;         acc[ai][bj][m][n] = __builtin_amdgcn_mfma_f32_16x16x32_bf16(Bt[n][k], At[m][k], acc[ai][bj][m][n], 0, 0, 0); __builtin_amdgcn_s_setprio(0); } while (0)
; #define PG8_WAIT_V(n) asm volatile("s_waitcnt vmcnt(" #n ")" ::: "memory")
; #define PG8_WAIT_L(n) asm volatile("s_waitcnt lgkmcnt(" #n ")" ::: "memory")
; #define PG8_BAR __builtin_amdgcn_s_barrier()
; template <class Epi, class Sched, bool ALIGN_EPI = false, bool SP2 = false>
; __device__ __forceinline__ void gemm_phase(PG8_LAS unsigned char* lds, const Gemm g, const Sched& S, const Epi& E, const int tid_in) {
;     ...
;             const char* a1 = cA + (size_t)(t + 1) * kstep;
;             const char* a2 = last ? nA : cA + (size_t)(t + 2) * kstep; const char* b2 = last ? nB : cB + (size_t)(t + 2) * kstep;
;             const char* a3 = a2 + kstep; const char* b3 = b2 + kstep;
;             if (last && has_next) S.a_ready(nxt);
;             if constexpr (SP2) {
;             PG8_LDB(B0, 0, 0); PG8_LDB(B1, 0, 1); PG8_SCHED; PG8_LDA(At, 0, 0); PG8_STAGE(PG8_SA(1, 1), a1 + hstep, voffA);
;             PG8_WAIT_V(8); PG8_WAIT_L(0); PG8_BAR; PG8_MMA(0, 0, At, B0); PG8_MMA(0, 1, At, B1); PG8_BAR; PG8_SCHED;
;             PG8_LDA(At, 0, 1); PG8_STAGE(PG8_SB(0, 0), b2, voffB); PG8_STAGE(PG8_SB(0, 1), b2 + hstep, voffB); PG8_STAGE(PG8_SA(0, 0), a2, voffA);
;             PG8_WAIT_V(8); PG8_WAIT_L(0); PG8_BAR; PG8_MMA(1, 0, At, B0); PG8_MMA(1, 1, At, B1); PG8_BAR; PG8_SCHED;
.LBB0_1157:
	s_add_u32 s52, s50, 0xfff80080
	s_addc_u32 s53, s51, -1
	s_add_i32 s63, 0, 0x10000
	s_cmp_eq_u32 s62, 28
	s_cselect_b32 s55, s35, s53
	s_cselect_b32 s54, s58, s52
	s_cselect_b32 s53, s31, s61
	s_cselect_b32 s52, s59, s60
	s_add_i32 s66, 0, 0x14000
	v_add_u32_e32 v78, s63, v177
	v_add_u32_e32 v134, s66, v177
	ds_read_b128 v[66:69], v78
	ds_read_b128 v[70:73], v78 offset:1024
	ds_read_b128 v[74:77], v78 offset:2048
	ds_read_b128 v[78:81], v78 offset:3072
	ds_read_b128 v[122:125], v134
	ds_read_b128 v[126:129], v134 offset:1024
	ds_read_b128 v[130:133], v134 offset:2048
	ds_read_b128 v[134:137], v134 offset:3072
	s_add_i32 m0, s89, 0xc000
	ds_read_b128 v[188:191], v193
	ds_read_b128 v[194:197], v193 offset:1024
	ds_read_b128 v[198:201], v193 offset:2048
	ds_read_b128 v[202:205], v193 offset:3072
	ds_read_b128 v[208:211], v193 offset:4096
	ds_read_b128 v[212:215], v193 offset:5120
	ds_read_b128 v[216:219], v193 offset:6144
	ds_read_b128 v[220:223], v193 offset:7168
	global_load_lds_dwordx4 v184, s[50:51]
	s_add_i32 m0, s89, 0xe000
	s_nop 0
	global_load_lds_dwordx4 v186, s[50:51]
	s_waitcnt vmcnt(8)
	s_waitcnt lgkmcnt(0)
	s_barrier
	s_setprio 1
	s_waitcnt lgkmcnt(0)
	v_mfma_f32_16x16x32_bf16 v[150:153], v[66:69], v[188:191], v[150:153]
	v_mfma_f32_16x16x32_bf16 v[110:113], v[74:77], v[188:191], v[110:113]
	v_mfma_f32_16x16x32_bf16 v[146:149], v[66:69], v[198:201], v[146:149]
	v_mfma_f32_16x16x32_bf16 v[106:109], v[74:77], v[198:201], v[106:109]
	v_mfma_f32_16x16x32_bf16 v[142:145], v[66:69], v[208:211], v[142:145]
	v_mfma_f32_16x16x32_bf16 v[102:105], v[74:77], v[208:211], v[102:105]
	v_mfma_f32_16x16x32_bf16 v[138:141], v[66:69], v[216:219], v[138:141]
	v_mfma_f32_16x16x32_bf16 v[98:101], v[74:77], v[216:219], v[98:101]
	v_mfma_f32_16x16x32_bf16 v[150:153], v[70:73], v[194:197], v[150:153]
	v_mfma_f32_16x16x32_bf16 v[110:113], v[78:81], v[194:197], v[110:113]
	v_mfma_f32_16x16x32_bf16 v[146:149], v[70:73], v[202:205], v[146:149]
	v_mfma_f32_16x16x32_bf16 v[106:109], v[78:81], v[202:205], v[106:109]
	v_mfma_f32_16x16x32_bf16 v[142:145], v[70:73], v[212:215], v[142:145]
	v_mfma_f32_16x16x32_bf16 v[102:105], v[78:81], v[212:215], v[102:105]
	v_mfma_f32_16x16x32_bf16 v[138:141], v[70:73], v[220:223], v[138:141]
	v_mfma_f32_16x16x32_bf16 v[98:101], v[78:81], v[220:223], v[98:101]
	s_setprio 0
	s_setprio 1
	v_mfma_f32_16x16x32_bf16 v[94:97], v[122:125], v[188:191], v[94:97]
	v_mfma_f32_16x16x32_bf16 v[90:93], v[130:133], v[188:191], v[90:93]
	v_mfma_f32_16x16x32_bf16 v[158:161], v[122:125], v[198:201], v[158:161]
	v_mfma_f32_16x16x32_bf16 v[118:121], v[130:133], v[198:201], v[118:121]
	v_mfma_f32_16x16x32_bf16 v[154:157], v[122:125], v[208:211], v[154:157]
	v_mfma_f32_16x16x32_bf16 v[114:117], v[130:133], v[208:211], v[114:117]
	v_mfma_f32_16x16x32_bf16 v[86:89], v[122:125], v[216:219], v[86:89]
	v_mfma_f32_16x16x32_bf16 v[82:85], v[130:133], v[216:219], v[82:85]
	v_mfma_f32_16x16x32_bf16 v[94:97], v[126:129], v[194:197], v[94:97]
	v_mfma_f32_16x16x32_bf16 v[90:93], v[134:137], v[194:197], v[90:93]
	v_mfma_f32_16x16x32_bf16 v[158:161], v[126:129], v[202:205], v[158:161]
	v_mfma_f32_16x16x32_bf16 v[118:121], v[134:137], v[202:205], v[118:121]
	v_mfma_f32_16x16x32_bf16 v[154:157], v[126:129], v[212:215], v[154:157]
	v_mfma_f32_16x16x32_bf16 v[114:117], v[134:137], v[212:215], v[114:117]
	v_mfma_f32_16x16x32_bf16 v[86:89], v[126:129], v[220:223], v[86:89]
	v_mfma_f32_16x16x32_bf16 v[82:85], v[134:137], v[220:223], v[82:85]
	s_setprio 0
	s_barrier
	s_add_i32 s63, s63, s1
	s_add_u32 s98, s52, 0x80
	s_addc_u32 s99, s53, 0
	s_mov_b32 m0, s63
	ds_read_b128 v[188:191], v193 offset:16384
	ds_read_b128 v[194:197], v193 offset:17408
	ds_read_b128 v[198:201], v193 offset:18432
	ds_read_b128 v[202:205], v193 offset:19456
	ds_read_b128 v[208:211], v193 offset:20480
	ds_read_b128 v[212:215], v193 offset:21504
	ds_read_b128 v[216:219], v193 offset:22528
	ds_read_b128 v[220:223], v193 offset:23552
	global_load_lds_dwordx4 v164, s[52:53]
	s_add_i32 m0, s63, 0x2000
	s_add_u32 s64, s52, 0x80000
	s_addc_u32 s65, s53, 0
	s_add_i32 s63, s66, s1
	global_load_lds_dwordx4 v168, s[52:53]
	s_mov_b32 m0, s63
	s_add_u32 s100, s54, 0x80
	s_addc_u32 s101, s55, 0
	global_load_lds_dwordx4 v164, s[64:65]
	s_add_i32 m0, s63, 0x2000
	s_nop 0
	global_load_lds_dwordx4 v168, s[64:65]
	s_mov_b32 m0, s89
	s_nop 0
	global_load_lds_dwordx4 v162, s[54:55]
	s_mov_b32 m0, s92
	s_nop 0
	global_load_lds_dwordx4 v166, s[54:55]
	s_waitcnt vmcnt(8)
	s_waitcnt lgkmcnt(0)
	s_barrier
	s_setprio 1
	s_waitcnt lgkmcnt(0)
	v_mfma_f32_16x16x32_bf16 v[54:57], v[66:69], v[188:191], v[54:57]
	v_mfma_f32_16x16x32_bf16 v[30:33], v[74:77], v[188:191], v[30:33]
	v_mfma_f32_16x16x32_bf16 v[50:53], v[66:69], v[198:201], v[50:53]
	v_mfma_f32_16x16x32_bf16 v[26:29], v[74:77], v[198:201], v[26:29]
	v_mfma_f32_16x16x32_bf16 v[46:49], v[66:69], v[208:211], v[46:49]
	v_mfma_f32_16x16x32_bf16 v[22:25], v[74:77], v[208:211], v[22:25]
	v_mfma_f32_16x16x32_bf16 v[42:45], v[66:69], v[216:219], v[42:45]
	v_mfma_f32_16x16x32_bf16 v[16:19], v[74:77], v[216:219], v[16:19]
	v_mfma_f32_16x16x32_bf16 v[54:57], v[70:73], v[194:197], v[54:57]
	v_mfma_f32_16x16x32_bf16 v[30:33], v[78:81], v[194:197], v[30:33]
	v_mfma_f32_16x16x32_bf16 v[50:53], v[70:73], v[202:205], v[50:53]
	v_mfma_f32_16x16x32_bf16 v[26:29], v[78:81], v[202:205], v[26:29]
	v_mfma_f32_16x16x32_bf16 v[46:49], v[70:73], v[212:215], v[46:49]
	v_mfma_f32_16x16x32_bf16 v[22:25], v[78:81], v[212:215], v[22:25]
	v_mfma_f32_16x16x32_bf16 v[42:45], v[70:73], v[220:223], v[42:45]
	v_mfma_f32_16x16x32_bf16 v[16:19], v[78:81], v[220:223], v[16:19]
	s_setprio 0
	s_setprio 1
	v_mfma_f32_16x16x32_bf16 v[12:15], v[122:125], v[188:191], v[12:15]
	v_mfma_f32_16x16x32_bf16 v[8:11], v[130:133], v[188:191], v[8:11]
	v_mfma_f32_16x16x32_bf16 v[62:65], v[122:125], v[198:201], v[62:65]
	v_mfma_f32_16x16x32_bf16 v[38:41], v[130:133], v[198:201], v[38:41]
	v_mfma_f32_16x16x32_bf16 v[58:61], v[122:125], v[208:211], v[58:61]
	v_mfma_f32_16x16x32_bf16 v[34:37], v[130:133], v[208:211], v[34:37]
	v_mfma_f32_16x16x32_bf16 v[4:7], v[122:125], v[216:219], v[4:7]
	v_mfma_f32_16x16x32_bf16 v[0:3], v[130:133], v[216:219], v[0:3]
	v_mfma_f32_16x16x32_bf16 v[12:15], v[126:129], v[194:197], v[12:15]
	v_mfma_f32_16x16x32_bf16 v[8:11], v[134:137], v[194:197], v[8:11]
	v_mfma_f32_16x16x32_bf16 v[62:65], v[126:129], v[202:205], v[62:65]
	v_mfma_f32_16x16x32_bf16 v[38:41], v[134:137], v[202:205], v[38:41]
	v_mfma_f32_16x16x32_bf16 v[58:61], v[126:129], v[212:215], v[58:61]
	v_mfma_f32_16x16x32_bf16 v[34:37], v[134:137], v[212:215], v[34:37]
	v_mfma_f32_16x16x32_bf16 v[4:7], v[126:129], v[220:223], v[4:7]
	v_mfma_f32_16x16x32_bf16 v[0:3], v[134:137], v[220:223], v[0:3]
	s_setprio 0
	s_barrier
; #define PG8_STAGE(bufoff, gbase, voff) do { _Pragma("unroll") for (int _i = 0; _i < 2; ++_i) \
;         __builtin_amdgcn_global_load_lds((const unsigned*)((const char*)(gbase) + (voff)[_i]), (PG8_LAS unsigned*)(lds + (bufoff) + ldsw + _i * 8192), 16, 0, 0); } while (0)
; #define PG8_LDA(dst, b, h) do { _Pragma("unroll") for (int m = 0; m < 4; ++m) _Pragma("unroll") for (int k = 0; k < 2; ++k) dst[m][k] = *(const PG8_LAS bf16x8*)(lds + PG8_SA(b, h) + aoff + m * 2048 + k * 1024); } while (0)
; #define PG8_LDB(dst, b, h) do { _Pragma("unroll") for (int n = 0; n < 2; ++n) _Pragma("unroll") for (int k = 0; k < 2; ++k) dst[n][k] = *(const PG8_LAS bf16x8*)(lds + PG8_SB(b, h) + boff + n * 2048 + k * 1024); } while (0)
; #define PG8_MMA(ai, bj, At, Bt) do { __builtin_amdgcn_s_setprio(1); _Pragma("unroll") for (int m = 0; m < 4; ++m) _Pragma("unroll") for (int n = 0; n < 2; ++n) _Pragma("unroll") for (int k = 0; k < 2; ++k) \
;         acc[ai][bj][m][n] = __builtin_amdgcn_mfma_f32_16x16x32_bf16(Bt[n][k], At[m][k], acc[ai][bj][m][n], 0, 0, 0); __builtin_amdgcn_s_setprio(0); } while (0)
; #define PG8_WAIT_V(n) asm volatile("s_waitcnt vmcnt(" #n ")" ::: "memory")
; #define PG8_WAIT_L(n) asm volatile("s_waitcnt lgkmcnt(" #n ")" ::: "memory")
; #define PG8_BAR __builtin_amdgcn_s_barrier()
; #define PG8_SCHED __builtin_amdgcn_sched_barrier(0)
; template <class Epi, class Sched, bool ALIGN_EPI = false, bool SP2 = false>
; __device__ __forceinline__ void gemm_phase(PG8_LAS unsigned char* lds, const Gemm g, const Sched& S, const Epi& E, const int tid_in) {
;     ...
;             PG8_LDB(B0, 1, 0); PG8_LDB(B1, 1, 1); PG8_SCHED; PG8_LDA(At, 1, 0); PG8_STAGE(PG8_SA(0, 1), a2 + hstep, voffA);
;             PG8_WAIT_V(8); PG8_WAIT_L(0); PG8_BAR; PG8_MMA(0, 0, At, B0); PG8_MMA(0, 1, At, B1); PG8_BAR; PG8_SCHED;
;             PG8_LDA(At, 1, 1); PG8_STAGE(PG8_SB(1, 0), b3, voffB); PG8_STAGE(PG8_SB(1, 1), b3 + hstep, voffB); PG8_STAGE(PG8_SA(1, 0), a3, voffA);
;             PG8_WAIT_V(8); PG8_WAIT_L(0); PG8_BAR; PG8_MMA(1, 0, At, B0); PG8_MMA(1, 1, At, B1); PG8_BAR; PG8_SCHED;
	s_add_i32 s63, 0, 0x18000
	s_add_i32 s64, 0, 0x1c000
	v_add_u32_e32 v78, s63, v177
	v_add_u32_e32 v134, s64, v177
	ds_read_b128 v[66:69], v78
	ds_read_b128 v[70:73], v78 offset:1024
	ds_read_b128 v[74:77], v78 offset:2048
	ds_read_b128 v[78:81], v78 offset:3072
	ds_read_b128 v[122:125], v134
	ds_read_b128 v[126:129], v134 offset:1024
	ds_read_b128 v[130:133], v134 offset:2048
	ds_read_b128 v[134:137], v134 offset:3072
	s_add_u32 s54, s54, 0x80000
	s_addc_u32 s55, s55, 0
	s_mov_b32 m0, s2
	ds_read_b128 v[188:191], v193 offset:32768
	ds_read_b128 v[194:197], v193 offset:33792
	ds_read_b128 v[198:201], v193 offset:34816
	ds_read_b128 v[202:205], v193 offset:35840
	ds_read_b128 v[208:211], v193 offset:36864
	ds_read_b128 v[212:215], v193 offset:37888
	ds_read_b128 v[216:219], v193 offset:38912
	ds_read_b128 v[220:223], v193 offset:39936
	global_load_lds_dwordx4 v162, s[54:55]
	s_mov_b32 m0, s3
	s_nop 0
	global_load_lds_dwordx4 v166, s[54:55]
	s_waitcnt vmcnt(8)
	s_waitcnt lgkmcnt(0)
	s_barrier
	s_setprio 1
	s_waitcnt lgkmcnt(0)
	v_mfma_f32_16x16x32_bf16 v[150:153], v[66:69], v[188:191], v[150:153]
	v_mfma_f32_16x16x32_bf16 v[110:113], v[74:77], v[188:191], v[110:113]
	v_mfma_f32_16x16x32_bf16 v[146:149], v[66:69], v[198:201], v[146:149]
	v_mfma_f32_16x16x32_bf16 v[106:109], v[74:77], v[198:201], v[106:109]
	v_mfma_f32_16x16x32_bf16 v[142:145], v[66:69], v[208:211], v[142:145]
	v_mfma_f32_16x16x32_bf16 v[102:105], v[74:77], v[208:211], v[102:105]
	v_mfma_f32_16x16x32_bf16 v[138:141], v[66:69], v[216:219], v[138:141]
	v_mfma_f32_16x16x32_bf16 v[98:101], v[74:77], v[216:219], v[98:101]
	v_mfma_f32_16x16x32_bf16 v[150:153], v[70:73], v[194:197], v[150:153]
	v_mfma_f32_16x16x32_bf16 v[110:113], v[78:81], v[194:197], v[110:113]
	v_mfma_f32_16x16x32_bf16 v[146:149], v[70:73], v[202:205], v[146:149]
	v_mfma_f32_16x16x32_bf16 v[106:109], v[78:81], v[202:205], v[106:109]
	v_mfma_f32_16x16x32_bf16 v[142:145], v[70:73], v[212:215], v[142:145]
	v_mfma_f32_16x16x32_bf16 v[102:105], v[78:81], v[212:215], v[102:105]
	v_mfma_f32_16x16x32_bf16 v[138:141], v[70:73], v[220:223], v[138:141]
	v_mfma_f32_16x16x32_bf16 v[98:101], v[78:81], v[220:223], v[98:101]
	s_setprio 0
	s_setprio 1
	v_mfma_f32_16x16x32_bf16 v[94:97], v[122:125], v[188:191], v[94:97]
	v_mfma_f32_16x16x32_bf16 v[90:93], v[130:133], v[188:191], v[90:93]
	v_mfma_f32_16x16x32_bf16 v[158:161], v[122:125], v[198:201], v[158:161]
	v_mfma_f32_16x16x32_bf16 v[118:121], v[130:133], v[198:201], v[118:121]
	v_mfma_f32_16x16x32_bf16 v[154:157], v[122:125], v[208:211], v[154:157]
	v_mfma_f32_16x16x32_bf16 v[114:117], v[130:133], v[208:211], v[114:117]
	v_mfma_f32_16x16x32_bf16 v[86:89], v[122:125], v[216:219], v[86:89]
	v_mfma_f32_16x16x32_bf16 v[82:85], v[130:133], v[216:219], v[82:85]
	v_mfma_f32_16x16x32_bf16 v[94:97], v[126:129], v[194:197], v[94:97]
	v_mfma_f32_16x16x32_bf16 v[90:93], v[134:137], v[194:197], v[90:93]
	v_mfma_f32_16x16x32_bf16 v[158:161], v[126:129], v[202:205], v[158:161]
	v_mfma_f32_16x16x32_bf16 v[118:121], v[134:137], v[202:205], v[118:121]
	v_mfma_f32_16x16x32_bf16 v[154:157], v[126:129], v[212:215], v[154:157]
	v_mfma_f32_16x16x32_bf16 v[114:117], v[134:137], v[212:215], v[114:117]
	v_mfma_f32_16x16x32_bf16 v[86:89], v[126:129], v[220:223], v[86:89]
	v_mfma_f32_16x16x32_bf16 v[82:85], v[134:137], v[220:223], v[82:85]
	s_setprio 0
	s_barrier
	s_add_i32 s54, s63, s1
	s_mov_b32 m0, s54
	ds_read_b128 v[188:191], v193 offset:49152
	ds_read_b128 v[194:197], v193 offset:50176
	ds_read_b128 v[198:201], v193 offset:51200
	ds_read_b128 v[202:205], v193 offset:52224
	ds_read_b128 v[208:211], v193 offset:53248
	ds_read_b128 v[212:215], v193 offset:54272
	ds_read_b128 v[216:219], v193 offset:55296
	ds_read_b128 v[220:223], v193 offset:56320
	global_load_lds_dwordx4 v164, s[98:99]
	s_add_i32 m0, s54, 0x2000
	s_add_u32 s52, s52, 0x80080
	s_addc_u32 s53, s53, 0
	s_add_i32 s54, s64, s1
	global_load_lds_dwordx4 v168, s[98:99]
	s_mov_b32 m0, s54
	s_nop 0
	global_load_lds_dwordx4 v164, s[52:53]
	s_add_i32 m0, s54, 0x2000
	s_nop 0
	global_load_lds_dwordx4 v168, s[52:53]
	s_mov_b32 m0, s24
	s_nop 0
	global_load_lds_dwordx4 v162, s[100:101]
	s_mov_b32 m0, s25
	s_nop 0
	global_load_lds_dwordx4 v166, s[100:101]
	s_waitcnt vmcnt(8)
	s_waitcnt lgkmcnt(0)
	s_barrier
	s_setprio 1
	s_waitcnt lgkmcnt(0)
	v_mfma_f32_16x16x32_bf16 v[54:57], v[66:69], v[188:191], v[54:57]
	v_mfma_f32_16x16x32_bf16 v[30:33], v[74:77], v[188:191], v[30:33]
	v_mfma_f32_16x16x32_bf16 v[50:53], v[66:69], v[198:201], v[50:53]
	v_mfma_f32_16x16x32_bf16 v[26:29], v[74:77], v[198:201], v[26:29]
	v_mfma_f32_16x16x32_bf16 v[46:49], v[66:69], v[208:211], v[46:49]
	v_mfma_f32_16x16x32_bf16 v[22:25], v[74:77], v[208:211], v[22:25]
	v_mfma_f32_16x16x32_bf16 v[42:45], v[66:69], v[216:219], v[42:45]
	v_mfma_f32_16x16x32_bf16 v[16:19], v[74:77], v[216:219], v[16:19]
	v_mfma_f32_16x16x32_bf16 v[54:57], v[70:73], v[194:197], v[54:57]
	v_mfma_f32_16x16x32_bf16 v[30:33], v[78:81], v[194:197], v[30:33]
	v_mfma_f32_16x16x32_bf16 v[50:53], v[70:73], v[202:205], v[50:53]
	v_mfma_f32_16x16x32_bf16 v[26:29], v[78:81], v[202:205], v[26:29]
	v_mfma_f32_16x16x32_bf16 v[46:49], v[70:73], v[212:215], v[46:49]
	v_mfma_f32_16x16x32_bf16 v[22:25], v[78:81], v[212:215], v[22:25]
	v_mfma_f32_16x16x32_bf16 v[42:45], v[70:73], v[220:223], v[42:45]
	v_mfma_f32_16x16x32_bf16 v[16:19], v[78:81], v[220:223], v[16:19]
	s_setprio 0
	s_setprio 1
	v_mfma_f32_16x16x32_bf16 v[12:15], v[122:125], v[188:191], v[12:15]
	v_mfma_f32_16x16x32_bf16 v[8:11], v[130:133], v[188:191], v[8:11]
	v_mfma_f32_16x16x32_bf16 v[62:65], v[122:125], v[198:201], v[62:65]
	v_mfma_f32_16x16x32_bf16 v[38:41], v[130:133], v[198:201], v[38:41]
	v_mfma_f32_16x16x32_bf16 v[58:61], v[122:125], v[208:211], v[58:61]
	v_mfma_f32_16x16x32_bf16 v[34:37], v[130:133], v[208:211], v[34:37]
	v_mfma_f32_16x16x32_bf16 v[4:7], v[122:125], v[216:219], v[4:7]
	v_mfma_f32_16x16x32_bf16 v[0:3], v[130:133], v[216:219], v[0:3]
	v_mfma_f32_16x16x32_bf16 v[12:15], v[126:129], v[194:197], v[12:15]
	v_mfma_f32_16x16x32_bf16 v[8:11], v[134:137], v[194:197], v[8:11]
	v_mfma_f32_16x16x32_bf16 v[62:65], v[126:129], v[202:205], v[62:65]
	v_mfma_f32_16x16x32_bf16 v[38:41], v[134:137], v[202:205], v[38:41]
	v_mfma_f32_16x16x32_bf16 v[58:61], v[126:129], v[212:215], v[58:61]
	v_mfma_f32_16x16x32_bf16 v[34:37], v[134:137], v[212:215], v[34:37]
	v_mfma_f32_16x16x32_bf16 v[4:7], v[126:129], v[220:223], v[4:7]
	v_mfma_f32_16x16x32_bf16 v[0:3], v[134:137], v[220:223], v[0:3]
	s_setprio 0
	s_barrier
	s_add_i32 s62, s62, 2
	s_add_u32 s50, s50, 0x100
	s_addc_u32 s51, s51, 0
	s_add_u32 s60, s60, 0x100
	s_addc_u32 s61, s61, 0
	s_cmp_gt_u32 s62, 29
	s_cbranch_scc0 .LBB0_1157
	s_and_b64 vcc, exec, s[28:29]
	s_cbranch_vccz .LBB0_1160
	s_barrier

; #define PG8_STAGE(bufoff, gbase, voff) do { _Pragma("unroll") for (int _i = 0; _i < 2; ++_i) \
;         __builtin_amdgcn_global_load_lds((const unsigned*)((const char*)(gbase) + (voff)[_i]), (PG8_LAS unsigned*)(lds + (bufoff) + ldsw + _i * 8192), 16, 0, 0); } while (0)
; #define PG8_LDA(dst, b, h) do { _Pragma("unroll") for (int m = 0; m < 4; ++m) _Pragma("unroll") for (int k = 0; k < 2; ++k) dst[m][k] = *(const PG8_LAS bf16x8*)(lds + PG8_SA(b, h) + aoff + m * 2048 + k * 1024); } while (0)
; #define PG8_LDB(dst, b, h) do { _Pragma("unroll") for (int n = 0; n < 2; ++n) _Pragma("unroll") for (int k = 0; k < 2; ++k) dst[n][k] = *(const PG8_LAS bf16x8*)(lds + PG8_SB(b, h) + boff + n * 2048 + k * 1024); } while (0)
; #define PG8_MMA(ai, bj, At, Bt) do { __builtin_amdgcn_s_setprio(1); _Pragma("unroll") for (int m = 0; m < 4; ++m) _Pragma("unroll") for (int n = 0; n < 2; ++n) _Pragma("unroll") for (int k = 0; k < 2; ++k) \
;         acc[ai][bj][m][n] = __builtin_amdgcn_mfma_f32_16x16x32_bf16(Bt[n][k], At[m][k], acc[ai][bj][m][n], 0, 0, 0); __builtin_amdgcn_s_setprio(0); } while (0)
; #define PG8_WAIT_V(n) asm volatile("s_waitcnt vmcnt(" #n ")" ::: "memory")
; #define PG8_WAIT_L(n) asm volatile("s_waitcnt lgkmcnt(" #n ")" ::: "memory")
; #define PG8_BAR __builtin_amdgcn_s_barrier()
; #define PG8_SCHED __builtin_amdgcn_sched_barrier(0)
; template <class Epi, class Sched, bool ALIGN_EPI = false, bool SP2 = false>
; __device__ __forceinline__ void gemm_phase(PG8_LAS unsigned char* lds, const Gemm g, const Sched& S, const Epi& E, const int tid_in) {
;     ...
;             const char* a1 = cA + (size_t)(t + 1) * kstep;
;             const char* a2 = last ? nA : cA + (size_t)(t + 2) * kstep; const char* b2 = last ? nB : cB + (size_t)(t + 2) * kstep;
;             const char* a3 = a2 + kstep; const char* b3 = b2 + kstep;
;             if (last && has_next) S.a_ready(nxt);
;             if constexpr (SP2) {
;             PG8_LDB(B0, 0, 0); PG8_LDB(B1, 0, 1); PG8_SCHED; PG8_LDA(At, 0, 0); PG8_STAGE(PG8_SA(1, 1), a1 + hstep, voffA);
;             PG8_WAIT_V(8); PG8_WAIT_L(0); PG8_BAR; PG8_MMA(0, 0, At, B0); PG8_MMA(0, 1, At, B1); PG8_BAR; PG8_SCHED;
;             PG8_LDA(At, 0, 1); PG8_STAGE(PG8_SB(0, 0), b2, voffB); PG8_STAGE(PG8_SB(0, 1), b2 + hstep, voffB); PG8_STAGE(PG8_SA(0, 0), a2, voffA);
.LBB0_1305:
	s_add_u32 s30, s28, 0x100
	s_addc_u32 s31, s29, 0
	s_add_i32 s57, 0, 0x10000
	s_cmpk_eq_i32 s56, 0x54
	s_cselect_b32 s39, s25, s31
	s_cselect_b32 s38, s24, s30
	s_cselect_b32 s35, s27, s55
	s_cselect_b32 s34, s26, s54
	s_add_i32 s58, 0, 0x14000
	v_add_u32_e32 v102, s57, v208
	v_add_u32_e32 v142, s58, v208
	ds_read_b128 v[78:81], v102
	ds_read_b128 v[86:89], v102 offset:1024
	ds_read_b128 v[94:97], v102 offset:2048
	ds_read_b128 v[102:105], v102 offset:3072
	ds_read_b128 v[118:121], v142
	ds_read_b128 v[126:129], v142 offset:1024
	ds_read_b128 v[134:137], v142 offset:2048
	ds_read_b128 v[142:145], v142 offset:3072
	v_lshl_add_u64 v[194:195], s[28:29], 0, v[222:223]
	s_add_i32 m0, s40, 0xc000
	ds_read_b128 v[154:157], v244
	ds_read_b128 v[158:161], v244 offset:1024
	ds_read_b128 v[162:165], v244 offset:2048
	ds_read_b128 v[166:169], v244 offset:3072
	ds_read_b128 v[170:173], v244 offset:4096
	ds_read_b128 v[182:185], v244 offset:5120
	ds_read_b128 v[186:189], v244 offset:6144
	ds_read_b128 v[190:193], v244 offset:7168
	global_load_lds_dwordx4 v[194:195], off
	v_lshl_add_u64 v[194:195], s[28:29], 0, v[224:225]
	s_add_i32 m0, s40, 0xe000
	s_nop 0
	global_load_lds_dwordx4 v[194:195], off
	s_waitcnt vmcnt(8)
	s_waitcnt lgkmcnt(0)
	s_barrier
	s_setprio 1
	s_waitcnt lgkmcnt(0)
	v_mfma_f32_16x16x32_bf16 v[178:181], v[78:81], v[154:157], v[178:181]
	v_mfma_f32_16x16x32_bf16 v[174:177], v[94:97], v[154:157], v[174:177]
	v_mfma_f32_16x16x32_bf16 v[138:141], v[78:81], v[162:165], v[138:141]
	v_mfma_f32_16x16x32_bf16 v[130:133], v[94:97], v[162:165], v[130:133]
	v_mfma_f32_16x16x32_bf16 v[110:113], v[78:81], v[170:173], v[110:113]
	v_mfma_f32_16x16x32_bf16 v[106:109], v[94:97], v[170:173], v[106:109]
	v_mfma_f32_16x16x32_bf16 v[82:85], v[78:81], v[186:189], v[82:85]
	v_mfma_f32_16x16x32_bf16 v[74:77], v[94:97], v[186:189], v[74:77]
	v_mfma_f32_16x16x32_bf16 v[178:181], v[86:89], v[158:161], v[178:181]
	v_mfma_f32_16x16x32_bf16 v[174:177], v[102:105], v[158:161], v[174:177]
	v_mfma_f32_16x16x32_bf16 v[138:141], v[86:89], v[166:169], v[138:141]
	v_mfma_f32_16x16x32_bf16 v[130:133], v[102:105], v[166:169], v[130:133]
	v_mfma_f32_16x16x32_bf16 v[110:113], v[86:89], v[182:185], v[110:113]
	v_mfma_f32_16x16x32_bf16 v[106:109], v[102:105], v[182:185], v[106:109]
	v_mfma_f32_16x16x32_bf16 v[82:85], v[86:89], v[190:193], v[82:85]
	v_mfma_f32_16x16x32_bf16 v[74:77], v[102:105], v[190:193], v[74:77]
	s_setprio 0
	s_setprio 1
	v_mfma_f32_16x16x32_bf16 v[150:153], v[118:121], v[154:157], v[150:153]
	v_mfma_f32_16x16x32_bf16 v[146:149], v[134:137], v[154:157], v[146:149]
	v_mfma_f32_16x16x32_bf16 v[122:125], v[118:121], v[162:165], v[122:125]
	v_mfma_f32_16x16x32_bf16 v[114:117], v[134:137], v[162:165], v[114:117]
	v_mfma_f32_16x16x32_bf16 v[98:101], v[118:121], v[170:173], v[98:101]
	v_mfma_f32_16x16x32_bf16 v[90:93], v[134:137], v[170:173], v[90:93]
	v_mfma_f32_16x16x32_bf16 v[70:73], v[118:121], v[186:189], v[70:73]
	v_mfma_f32_16x16x32_bf16 v[66:69], v[134:137], v[186:189], v[66:69]
	v_mfma_f32_16x16x32_bf16 v[150:153], v[126:129], v[158:161], v[150:153]
	v_mfma_f32_16x16x32_bf16 v[146:149], v[142:145], v[158:161], v[146:149]
	v_mfma_f32_16x16x32_bf16 v[122:125], v[126:129], v[166:169], v[122:125]
	v_mfma_f32_16x16x32_bf16 v[114:117], v[142:145], v[166:169], v[114:117]
	v_mfma_f32_16x16x32_bf16 v[98:101], v[126:129], v[182:185], v[98:101]
	v_mfma_f32_16x16x32_bf16 v[90:93], v[142:145], v[182:185], v[90:93]
	v_mfma_f32_16x16x32_bf16 v[70:73], v[126:129], v[190:193], v[70:73]
	v_mfma_f32_16x16x32_bf16 v[66:69], v[142:145], v[190:193], v[66:69]
	s_setprio 0
	s_barrier
	s_add_i32 s28, s57, s19
	s_add_u32 s98, s34, 0x80
	s_addc_u32 s99, s35, 0
	s_mov_b32 m0, s28
	ds_read_b128 v[154:157], v244 offset:16384
	ds_read_b128 v[158:161], v244 offset:17408
	ds_read_b128 v[162:165], v244 offset:18432
	ds_read_b128 v[166:169], v244 offset:19456
	ds_read_b128 v[170:173], v244 offset:20480
	ds_read_b128 v[182:185], v244 offset:21504
	ds_read_b128 v[186:189], v244 offset:22528
	ds_read_b128 v[190:193], v244 offset:23552
	global_load_lds_dwordx4 v218, s[34:35]
	s_add_i32 m0, s28, 0x2000
	s_add_u32 s28, s34, 0x160000
	s_addc_u32 s29, s35, 0
	s_add_i32 s57, s58, s19
	global_load_lds_dwordx4 v214, s[34:35]
	s_mov_b32 m0, s57
	s_add_u32 s100, s38, 0x80
	s_addc_u32 s101, s39, 0
	global_load_lds_dwordx4 v218, s[28:29]
	s_add_i32 m0, s57, 0x2000
	s_nop 0
	global_load_lds_dwordx4 v214, s[28:29]
	s_mov_b32 m0, s40
	s_nop 0
	global_load_lds_dwordx4 v220, s[38:39]
	s_mov_b32 m0, s41
	s_nop 0
	global_load_lds_dwordx4 v216, s[38:39]
	s_waitcnt vmcnt(8)
	s_waitcnt lgkmcnt(0)
	s_barrier
; #define PG8_STAGE(bufoff, gbase, voff) do { _Pragma("unroll") for (int _i = 0; _i < 2; ++_i) \
;         __builtin_amdgcn_global_load_lds((const unsigned*)((const char*)(gbase) + (voff)[_i]), (PG8_LAS unsigned*)(lds + (bufoff) + ldsw + _i * 8192), 16, 0, 0); } while (0)
; #define PG8_LDA(dst, b, h) do { _Pragma("unroll") for (int m = 0; m < 4; ++m) _Pragma("unroll") for (int k = 0; k < 2; ++k) dst[m][k] = *(const PG8_LAS bf16x8*)(lds + PG8_SA(b, h) + aoff + m * 2048 + k * 1024); } while (0)
; #define PG8_LDB(dst, b, h) do { _Pragma("unroll") for (int n = 0; n < 2; ++n) _Pragma("unroll") for (int k = 0; k < 2; ++k) dst[n][k] = *(const PG8_LAS bf16x8*)(lds + PG8_SB(b, h) + boff + n * 2048 + k * 1024); } while (0)
; #define PG8_MMA(ai, bj, At, Bt) do { __builtin_amdgcn_s_setprio(1); _Pragma("unroll") for (int m = 0; m < 4; ++m) _Pragma("unroll") for (int n = 0; n < 2; ++n) _Pragma("unroll") for (int k = 0; k < 2; ++k) \
;         acc[ai][bj][m][n] = __builtin_amdgcn_mfma_f32_16x16x32_bf16(Bt[n][k], At[m][k], acc[ai][bj][m][n], 0, 0, 0); __builtin_amdgcn_s_setprio(0); } while (0)
; #define PG8_WAIT_V(n) asm volatile("s_waitcnt vmcnt(" #n ")" ::: "memory")
; #define PG8_WAIT_L(n) asm volatile("s_waitcnt lgkmcnt(" #n ")" ::: "memory")
; #define PG8_BAR __builtin_amdgcn_s_barrier()
; #define PG8_SCHED __builtin_amdgcn_sched_barrier(0)
; template <class Epi, class Sched, bool ALIGN_EPI = false, bool SP2 = false>
; __device__ __forceinline__ void gemm_phase(PG8_LAS unsigned char* lds, const Gemm g, const Sched& S, const Epi& E, const int tid_in) {
;     ...
;             PG8_WAIT_V(8); PG8_WAIT_L(0); PG8_BAR; PG8_MMA(1, 0, At, B0); PG8_MMA(1, 1, At, B1); PG8_BAR; PG8_SCHED;
;             PG8_LDB(B0, 1, 0); PG8_LDB(B1, 1, 1); PG8_SCHED; PG8_LDA(At, 1, 0); PG8_STAGE(PG8_SA(0, 1), a2 + hstep, voffA);
;             PG8_WAIT_V(8); PG8_WAIT_L(0); PG8_BAR; PG8_MMA(0, 0, At, B0); PG8_MMA(0, 1, At, B1); PG8_BAR; PG8_SCHED;
	s_setprio 1
	s_waitcnt lgkmcnt(0)
	v_mfma_f32_16x16x32_bf16 v[62:65], v[78:81], v[154:157], v[62:65]
	v_mfma_f32_16x16x32_bf16 v[58:61], v[94:97], v[154:157], v[58:61]
	v_mfma_f32_16x16x32_bf16 v[46:49], v[78:81], v[162:165], v[46:49]
	v_mfma_f32_16x16x32_bf16 v[42:45], v[94:97], v[162:165], v[42:45]
	v_mfma_f32_16x16x32_bf16 v[30:33], v[78:81], v[170:173], v[30:33]
	v_mfma_f32_16x16x32_bf16 v[26:29], v[94:97], v[170:173], v[26:29]
	v_mfma_f32_16x16x32_bf16 v[12:15], v[78:81], v[186:189], v[12:15]
	v_mfma_f32_16x16x32_bf16 v[8:11], v[94:97], v[186:189], v[8:11]
	v_mfma_f32_16x16x32_bf16 v[62:65], v[86:89], v[158:161], v[62:65]
	v_mfma_f32_16x16x32_bf16 v[58:61], v[102:105], v[158:161], v[58:61]
	v_mfma_f32_16x16x32_bf16 v[46:49], v[86:89], v[166:169], v[46:49]
	v_mfma_f32_16x16x32_bf16 v[42:45], v[102:105], v[166:169], v[42:45]
	v_mfma_f32_16x16x32_bf16 v[30:33], v[86:89], v[182:185], v[30:33]
	v_mfma_f32_16x16x32_bf16 v[26:29], v[102:105], v[182:185], v[26:29]
	v_mfma_f32_16x16x32_bf16 v[12:15], v[86:89], v[190:193], v[12:15]
	v_mfma_f32_16x16x32_bf16 v[8:11], v[102:105], v[190:193], v[8:11]
	s_setprio 0
	s_setprio 1
	v_mfma_f32_16x16x32_bf16 v[54:57], v[118:121], v[154:157], v[54:57]
	v_mfma_f32_16x16x32_bf16 v[50:53], v[134:137], v[154:157], v[50:53]
	v_mfma_f32_16x16x32_bf16 v[38:41], v[118:121], v[162:165], v[38:41]
	v_mfma_f32_16x16x32_bf16 v[34:37], v[134:137], v[162:165], v[34:37]
	v_mfma_f32_16x16x32_bf16 v[22:25], v[118:121], v[170:173], v[22:25]
	v_mfma_f32_16x16x32_bf16 v[16:19], v[134:137], v[170:173], v[16:19]
	v_mfma_f32_16x16x32_bf16 v[4:7], v[118:121], v[186:189], v[4:7]
	v_mfma_f32_16x16x32_bf16 v[0:3], v[134:137], v[186:189], v[0:3]
	v_mfma_f32_16x16x32_bf16 v[54:57], v[126:129], v[158:161], v[54:57]
	v_mfma_f32_16x16x32_bf16 v[50:53], v[142:145], v[158:161], v[50:53]
	v_mfma_f32_16x16x32_bf16 v[38:41], v[126:129], v[166:169], v[38:41]
	v_mfma_f32_16x16x32_bf16 v[34:37], v[142:145], v[166:169], v[34:37]
	v_mfma_f32_16x16x32_bf16 v[22:25], v[126:129], v[182:185], v[22:25]
	v_mfma_f32_16x16x32_bf16 v[16:19], v[142:145], v[182:185], v[16:19]
	v_mfma_f32_16x16x32_bf16 v[4:7], v[126:129], v[190:193], v[4:7]
	v_mfma_f32_16x16x32_bf16 v[0:3], v[142:145], v[190:193], v[0:3]
	s_setprio 0
	s_barrier
	s_add_i32 s57, 0, 0x18000
	s_add_i32 s58, 0, 0x1c000
	v_add_u32_e32 v102, s57, v208
	v_add_u32_e32 v142, s58, v208
	ds_read_b128 v[78:81], v102
	ds_read_b128 v[86:89], v102 offset:1024
	ds_read_b128 v[94:97], v102 offset:2048
	ds_read_b128 v[102:105], v102 offset:3072
	ds_read_b128 v[118:121], v142
	ds_read_b128 v[126:129], v142 offset:1024
	ds_read_b128 v[134:137], v142 offset:2048
	ds_read_b128 v[142:145], v142 offset:3072
	s_add_u32 s28, s38, 0x160000
	s_addc_u32 s29, s39, 0
	s_mov_b32 m0, s42
	ds_read_b128 v[154:157], v244 offset:32768
	ds_read_b128 v[158:161], v244 offset:33792
	ds_read_b128 v[162:165], v244 offset:34816
	ds_read_b128 v[166:169], v244 offset:35840
	ds_read_b128 v[170:173], v244 offset:36864
	ds_read_b128 v[182:185], v244 offset:37888
	ds_read_b128 v[186:189], v244 offset:38912
	ds_read_b128 v[190:193], v244 offset:39936
	global_load_lds_dwordx4 v220, s[28:29]
	s_mov_b32 m0, s43
	s_nop 0
	global_load_lds_dwordx4 v216, s[28:29]
	s_waitcnt vmcnt(8)
	s_waitcnt lgkmcnt(0)
	s_barrier
	s_setprio 1
	s_waitcnt lgkmcnt(0)
	v_mfma_f32_16x16x32_bf16 v[178:181], v[78:81], v[154:157], v[178:181]
	v_mfma_f32_16x16x32_bf16 v[174:177], v[94:97], v[154:157], v[174:177]
	v_mfma_f32_16x16x32_bf16 v[138:141], v[78:81], v[162:165], v[138:141]
	v_mfma_f32_16x16x32_bf16 v[130:133], v[94:97], v[162:165], v[130:133]
	v_mfma_f32_16x16x32_bf16 v[110:113], v[78:81], v[170:173], v[110:113]
	v_mfma_f32_16x16x32_bf16 v[106:109], v[94:97], v[170:173], v[106:109]
	v_mfma_f32_16x16x32_bf16 v[82:85], v[78:81], v[186:189], v[82:85]
	v_mfma_f32_16x16x32_bf16 v[74:77], v[94:97], v[186:189], v[74:77]
	v_mfma_f32_16x16x32_bf16 v[178:181], v[86:89], v[158:161], v[178:181]
	v_mfma_f32_16x16x32_bf16 v[174:177], v[102:105], v[158:161], v[174:177]
	v_mfma_f32_16x16x32_bf16 v[138:141], v[86:89], v[166:169], v[138:141]
	v_mfma_f32_16x16x32_bf16 v[130:133], v[102:105], v[166:169], v[130:133]
	v_mfma_f32_16x16x32_bf16 v[110:113], v[86:89], v[182:185], v[110:113]
	v_mfma_f32_16x16x32_bf16 v[106:109], v[102:105], v[182:185], v[106:109]
	v_mfma_f32_16x16x32_bf16 v[82:85], v[86:89], v[190:193], v[82:85]
	v_mfma_f32_16x16x32_bf16 v[74:77], v[102:105], v[190:193], v[74:77]
	s_setprio 0
	s_setprio 1
	v_mfma_f32_16x16x32_bf16 v[150:153], v[118:121], v[154:157], v[150:153]
	v_mfma_f32_16x16x32_bf16 v[146:149], v[134:137], v[154:157], v[146:149]
	v_mfma_f32_16x16x32_bf16 v[122:125], v[118:121], v[162:165], v[122:125]
	v_mfma_f32_16x16x32_bf16 v[114:117], v[134:137], v[162:165], v[114:117]
	v_mfma_f32_16x16x32_bf16 v[98:101], v[118:121], v[170:173], v[98:101]
	v_mfma_f32_16x16x32_bf16 v[90:93], v[134:137], v[170:173], v[90:93]
	v_mfma_f32_16x16x32_bf16 v[70:73], v[118:121], v[186:189], v[70:73]
	v_mfma_f32_16x16x32_bf16 v[66:69], v[134:137], v[186:189], v[66:69]
	v_mfma_f32_16x16x32_bf16 v[150:153], v[126:129], v[158:161], v[150:153]
	v_mfma_f32_16x16x32_bf16 v[146:149], v[142:145], v[158:161], v[146:149]
	v_mfma_f32_16x16x32_bf16 v[122:125], v[126:129], v[166:169], v[122:125]
	v_mfma_f32_16x16x32_bf16 v[114:117], v[142:145], v[166:169], v[114:117]
	v_mfma_f32_16x16x32_bf16 v[98:101], v[126:129], v[182:185], v[98:101]
	v_mfma_f32_16x16x32_bf16 v[90:93], v[142:145], v[182:185], v[90:93]
	v_mfma_f32_16x16x32_bf16 v[70:73], v[126:129], v[190:193], v[70:73]
	v_mfma_f32_16x16x32_bf16 v[66:69], v[142:145], v[190:193], v[66:69]
	s_setprio 0
	s_barrier
; #define PG8_STAGE(bufoff, gbase, voff) do { _Pragma("unroll") for (int _i = 0; _i < 2; ++_i) \
;         __builtin_amdgcn_global_load_lds((const unsigned*)((const char*)(gbase) + (voff)[_i]), (PG8_LAS unsigned*)(lds + (bufoff) + ldsw + _i * 8192), 16, 0, 0); } while (0)
; #define PG8_LDA(dst, b, h) do { _Pragma("unroll") for (int m = 0; m < 4; ++m) _Pragma("unroll") for (int k = 0; k < 2; ++k) dst[m][k] = *(const PG8_LAS bf16x8*)(lds + PG8_SA(b, h) + aoff + m * 2048 + k * 1024); } while (0)
; #define PG8_MMA(ai, bj, At, Bt) do { __builtin_amdgcn_s_setprio(1); _Pragma("unroll") for (int m = 0; m < 4; ++m) _Pragma("unroll") for (int n = 0; n < 2; ++n) _Pragma("unroll") for (int k = 0; k < 2; ++k) \
;         acc[ai][bj][m][n] = __builtin_amdgcn_mfma_f32_16x16x32_bf16(Bt[n][k], At[m][k], acc[ai][bj][m][n], 0, 0, 0); __builtin_amdgcn_s_setprio(0); } while (0)
; #define PG8_WAIT_V(n) asm volatile("s_waitcnt vmcnt(" #n ")" ::: "memory")
; #define PG8_WAIT_L(n) asm volatile("s_waitcnt lgkmcnt(" #n ")" ::: "memory")
; #define PG8_BAR __builtin_amdgcn_s_barrier()
; #define PG8_SCHED __builtin_amdgcn_sched_barrier(0)
; template <class Epi, class Sched, bool ALIGN_EPI = false, bool SP2 = false>
; __device__ __forceinline__ void gemm_phase(PG8_LAS unsigned char* lds, const Gemm g, const Sched& S, const Epi& E, const int tid_in) {
;     ...
;             PG8_LDA(At, 1, 1); PG8_STAGE(PG8_SB(1, 0), b3, voffB); PG8_STAGE(PG8_SB(1, 1), b3 + hstep, voffB); PG8_STAGE(PG8_SA(1, 0), a3, voffA);
;             PG8_WAIT_V(8); PG8_WAIT_L(0); PG8_BAR; PG8_MMA(1, 0, At, B0); PG8_MMA(1, 1, At, B1); PG8_BAR; PG8_SCHED;
	s_add_i32 s28, s57, s19
	s_mov_b32 m0, s28
	ds_read_b128 v[154:157], v244 offset:49152
	ds_read_b128 v[158:161], v244 offset:50176
	ds_read_b128 v[162:165], v244 offset:51200
	ds_read_b128 v[166:169], v244 offset:52224
	ds_read_b128 v[170:173], v244 offset:53248
	ds_read_b128 v[182:185], v244 offset:54272
	ds_read_b128 v[186:189], v244 offset:55296
	ds_read_b128 v[190:193], v244 offset:56320
	global_load_lds_dwordx4 v218, s[98:99]
	s_add_i32 m0, s28, 0x2000
	s_add_u32 s28, s34, 0x160080
	s_addc_u32 s29, s35, 0
	s_add_i32 s34, s58, s19
	global_load_lds_dwordx4 v214, s[98:99]
	s_mov_b32 m0, s34
	s_nop 0
	global_load_lds_dwordx4 v218, s[28:29]
	s_add_i32 m0, s34, 0x2000
	s_nop 0
	global_load_lds_dwordx4 v214, s[28:29]
	s_mov_b32 m0, s46
	s_nop 0
	global_load_lds_dwordx4 v220, s[100:101]
	s_mov_b32 m0, s47
	s_nop 0
	global_load_lds_dwordx4 v216, s[100:101]
	s_waitcnt vmcnt(8)
	s_waitcnt lgkmcnt(0)
	s_barrier
	s_setprio 1
	s_waitcnt lgkmcnt(0)
	v_mfma_f32_16x16x32_bf16 v[62:65], v[78:81], v[154:157], v[62:65]
	v_mfma_f32_16x16x32_bf16 v[58:61], v[94:97], v[154:157], v[58:61]
	v_mfma_f32_16x16x32_bf16 v[46:49], v[78:81], v[162:165], v[46:49]
	v_mfma_f32_16x16x32_bf16 v[42:45], v[94:97], v[162:165], v[42:45]
	v_mfma_f32_16x16x32_bf16 v[30:33], v[78:81], v[170:173], v[30:33]
	v_mfma_f32_16x16x32_bf16 v[26:29], v[94:97], v[170:173], v[26:29]
	v_mfma_f32_16x16x32_bf16 v[12:15], v[78:81], v[186:189], v[12:15]
	v_mfma_f32_16x16x32_bf16 v[8:11], v[94:97], v[186:189], v[8:11]
	v_mfma_f32_16x16x32_bf16 v[62:65], v[86:89], v[158:161], v[62:65]
	v_mfma_f32_16x16x32_bf16 v[58:61], v[102:105], v[158:161], v[58:61]
	v_mfma_f32_16x16x32_bf16 v[46:49], v[86:89], v[166:169], v[46:49]
	v_mfma_f32_16x16x32_bf16 v[42:45], v[102:105], v[166:169], v[42:45]
	v_mfma_f32_16x16x32_bf16 v[30:33], v[86:89], v[182:185], v[30:33]
	v_mfma_f32_16x16x32_bf16 v[26:29], v[102:105], v[182:185], v[26:29]
	v_mfma_f32_16x16x32_bf16 v[12:15], v[86:89], v[190:193], v[12:15]
	v_mfma_f32_16x16x32_bf16 v[8:11], v[102:105], v[190:193], v[8:11]
	s_setprio 0
	s_setprio 1
	v_mfma_f32_16x16x32_bf16 v[54:57], v[118:121], v[154:157], v[54:57]
	v_mfma_f32_16x16x32_bf16 v[50:53], v[134:137], v[154:157], v[50:53]
	v_mfma_f32_16x16x32_bf16 v[38:41], v[118:121], v[162:165], v[38:41]
	v_mfma_f32_16x16x32_bf16 v[34:37], v[134:137], v[162:165], v[34:37]
	v_mfma_f32_16x16x32_bf16 v[22:25], v[118:121], v[170:173], v[22:25]
	v_mfma_f32_16x16x32_bf16 v[16:19], v[134:137], v[170:173], v[16:19]
	v_mfma_f32_16x16x32_bf16 v[4:7], v[118:121], v[186:189], v[4:7]
	v_mfma_f32_16x16x32_bf16 v[0:3], v[134:137], v[186:189], v[0:3]
	v_mfma_f32_16x16x32_bf16 v[54:57], v[126:129], v[158:161], v[54:57]
	v_mfma_f32_16x16x32_bf16 v[50:53], v[142:145], v[158:161], v[50:53]
	v_mfma_f32_16x16x32_bf16 v[38:41], v[126:129], v[166:169], v[38:41]
	v_mfma_f32_16x16x32_bf16 v[34:37], v[142:145], v[166:169], v[34:37]
	v_mfma_f32_16x16x32_bf16 v[22:25], v[126:129], v[182:185], v[22:25]
	v_mfma_f32_16x16x32_bf16 v[16:19], v[142:145], v[182:185], v[16:19]
	v_mfma_f32_16x16x32_bf16 v[4:7], v[126:129], v[190:193], v[4:7]
	v_mfma_f32_16x16x32_bf16 v[0:3], v[142:145], v[190:193], v[0:3]
	s_setprio 0
	s_barrier
	s_add_i32 s56, s56, 2
	s_add_u32 s54, s54, 0x100
	s_addc_u32 s55, s55, 0
	s_cmpk_gt_u32 s56, 0x55
	s_mov_b64 s[28:29], s[30:31]
	s_cbranch_scc0 .LBB0_1305
	v_mov_b32_e32 v207, 0x7f800000
	s_and_b64 vcc, exec, s[22:23]
	s_cbranch_vccz .LBB0_1308
	s_barrier
